# GEMM K-loops: 160 provably redundant lgkmcnt ladder waits inside the MMA blocks removed (explicit lgkmcnt(0) before the barrier already covers them)
# speedup vs baseline: 1.0019x; 1.0019x over previous
; #define PG8_STAGE(srd, bufoff, goff, voff) do { _Pragma("unroll") for (int _i = 0; _i < 2; ++_i) \
;         __builtin_amdgcn_raw_ptr_buffer_load_lds(srd, (PG8_LAS unsigned*)(lds + (bufoff) + ldsw + _i * 8192), 16, (voff)[_i], (goff), 0, 0); } while (0)
; #define PG8_LDA(dst, b, h) do { _Pragma("unroll") for (int m = 0; m < 4; ++m) _Pragma("unroll") for (int k = 0; k < 2; ++k) dst[m][k] = *(const PG8_LAS bf16x8*)(lds + PG8_SA(b, h) + aoff + m * 2048 + k * 1024); } while (0)
; #define PG8_LDB(dst, b, h) do { _Pragma("unroll") for (int n = 0; n < 2; ++n) _Pragma("unroll") for (int k = 0; k < 2; ++k) dst[n][k] = *(const PG8_LAS bf16x8*)(lds + PG8_SB(b, h) + boff + n * 2048 + k * 1024); } while (0)
; #define PG8_MMA(ai, bj, At, Bt) do { __builtin_amdgcn_s_setprio(1); _Pragma("unroll") for (int m = 0; m < 4; ++m) _Pragma("unroll") for (int n = 0; n < 2; ++n) _Pragma("unroll") for (int k = 0; k < 2; ++k) \
;         acc[ai][bj][m][n] = __builtin_amdgcn_mfma_f32_16x16x32_bf16(Bt[n][k], At[m][k], acc[ai][bj][m][n], 0, 0, 0); __builtin_amdgcn_s_setprio(0); } while (0)
; #define PG8_WAIT_V(n) asm volatile("s_waitcnt vmcnt(" #n ")" ::: "memory")
; #define PG8_WAIT_L(n) asm volatile("s_waitcnt lgkmcnt(" #n ")" ::: "memory")
; #define PG8_BAR __builtin_amdgcn_s_barrier()
; #define PG8_SCHED __builtin_amdgcn_sched_barrier(0)
; template <class Epi, class Sched, bool ALIGN_EPI = true>
; __device__ __forceinline__ void gemm_phase(PG8_LAS unsigned char* lds, const Gemm g, const Sched& S, const Epi& E) {
;     ...
;             PG8_LDB(B0, 0, 0); PG8_LDB(B1, 0, 1); PG8_SCHED; PG8_LDA(At, 0, 0); PG8_STAGE(srdA, PG8_SA(1, 1), a1 + hstepA, voffA);
;             PG8_WAIT_V(8); PG8_WAIT_L(0); PG8_BAR; PG8_MMA(0, 0, At, B0); PG8_MMA(0, 1, At, B1); PG8_BAR; PG8_SCHED;
;             PG8_LDA(At, 0, 1); PG8_STAGE(srdB, PG8_SB(0, 0), b2, voffB); PG8_STAGE(srdB, PG8_SB(0, 1), b2 + hstepB, voffB); PG8_STAGE(srdA, PG8_SA(0, 0), a2, voffA);
;             PG8_WAIT_V(8); PG8_WAIT_L(0); PG8_BAR; PG8_MMA(1, 0, At, B0); PG8_MMA(1, 1, At, B1); PG8_BAR; PG8_SCHED;
.LBB0_189:
	ds_read_b128 v[148:151], v158
	ds_read_b128 v[170:173], v158 offset:1024
	ds_read_b128 v[174:177], v158 offset:2048
	ds_read_b128 v[178:181], v158 offset:3072
	ds_read_b128 v[182:185], v159
	ds_read_b128 v[186:189], v159 offset:1024
	ds_read_b128 v[190:193], v159 offset:2048
	ds_read_b128 v[194:197], v159 offset:3072
	s_add_i32 s14, s80, 0xfff80080
	s_cmp_eq_u32 s92, 28
	s_cselect_b32 s46, s10, s14
	s_cselect_b32 s39, s11, s91
	s_or_b32 s38, s46, 0x80
	s_mov_b32 m0, s70
	ds_read_b128 v[198:201], v161
	ds_read_b128 v[202:205], v161 offset:1024
	ds_read_b128 v[206:209], v161 offset:2048
	ds_read_b128 v[210:213], v161 offset:3072
	ds_read_b128 v[214:217], v161 offset:4096
	ds_read_b128 v[218:221], v161 offset:5120
	ds_read_b128 v[222:225], v161 offset:6144
	ds_read_b128 v[226:229], v161 offset:7168
	buffer_load_dwordx4 v129, s[20:23], s80 offen lds
	s_mov_b32 m0, s71
	s_nop 0
	buffer_load_dwordx4 v133, s[20:23], s80 offen lds
	s_waitcnt vmcnt(8)
	s_waitcnt lgkmcnt(0)
	s_barrier
	s_setprio 1
	v_mfma_f32_16x16x32_bf16 v[124:127], v[148:151], v[198:201], v[124:127]
	v_mfma_f32_16x16x32_bf16 v[120:123], v[174:177], v[198:201], v[120:123]
	v_mfma_f32_16x16x32_bf16 v[108:111], v[148:151], v[206:209], v[108:111]
	v_mfma_f32_16x16x32_bf16 v[104:107], v[174:177], v[206:209], v[104:107]
	v_mfma_f32_16x16x32_bf16 v[92:95], v[148:151], v[214:217], v[92:95]
	v_mfma_f32_16x16x32_bf16 v[88:91], v[174:177], v[214:217], v[88:91]
	v_mfma_f32_16x16x32_bf16 v[76:79], v[148:151], v[222:225], v[76:79]
	v_mfma_f32_16x16x32_bf16 v[72:75], v[174:177], v[222:225], v[72:75]
	v_mfma_f32_16x16x32_bf16 v[124:127], v[170:173], v[202:205], v[124:127]
	v_mfma_f32_16x16x32_bf16 v[120:123], v[178:181], v[202:205], v[120:123]
	v_mfma_f32_16x16x32_bf16 v[108:111], v[170:173], v[210:213], v[108:111]
	v_mfma_f32_16x16x32_bf16 v[104:107], v[178:181], v[210:213], v[104:107]
	v_mfma_f32_16x16x32_bf16 v[92:95], v[170:173], v[218:221], v[92:95]
	v_mfma_f32_16x16x32_bf16 v[88:91], v[178:181], v[218:221], v[88:91]
	v_mfma_f32_16x16x32_bf16 v[76:79], v[170:173], v[226:229], v[76:79]
	v_mfma_f32_16x16x32_bf16 v[72:75], v[178:181], v[226:229], v[72:75]
	s_setprio 0
	s_setprio 1
	v_mfma_f32_16x16x32_bf16 v[116:119], v[182:185], v[198:201], v[116:119]
	v_mfma_f32_16x16x32_bf16 v[112:115], v[190:193], v[198:201], v[112:115]
	v_mfma_f32_16x16x32_bf16 v[100:103], v[182:185], v[206:209], v[100:103]
	v_mfma_f32_16x16x32_bf16 v[96:99], v[190:193], v[206:209], v[96:99]
	v_mfma_f32_16x16x32_bf16 v[84:87], v[182:185], v[214:217], v[84:87]
	v_mfma_f32_16x16x32_bf16 v[80:83], v[190:193], v[214:217], v[80:83]
	v_mfma_f32_16x16x32_bf16 v[68:71], v[182:185], v[222:225], v[68:71]
	v_mfma_f32_16x16x32_bf16 v[64:67], v[190:193], v[222:225], v[64:67]
	v_mfma_f32_16x16x32_bf16 v[116:119], v[186:189], v[202:205], v[116:119]
	v_mfma_f32_16x16x32_bf16 v[112:115], v[194:197], v[202:205], v[112:115]
	v_mfma_f32_16x16x32_bf16 v[100:103], v[186:189], v[210:213], v[100:103]
	v_mfma_f32_16x16x32_bf16 v[96:99], v[194:197], v[210:213], v[96:99]
	v_mfma_f32_16x16x32_bf16 v[84:87], v[186:189], v[218:221], v[84:87]
	v_mfma_f32_16x16x32_bf16 v[80:83], v[194:197], v[218:221], v[80:83]
	v_mfma_f32_16x16x32_bf16 v[68:71], v[186:189], v[226:229], v[68:71]
	v_mfma_f32_16x16x32_bf16 v[64:67], v[194:197], v[226:229], v[64:67]
	s_setprio 0
	s_barrier
	s_mov_b32 m0, s25
	s_mov_b32 s14, s22
	s_mov_b32 s15, s23
	ds_read_b128 v[198:201], v161 offset:16384
	ds_read_b128 v[202:205], v161 offset:17408
	ds_read_b128 v[206:209], v161 offset:18432
	ds_read_b128 v[210:213], v161 offset:19456
	ds_read_b128 v[214:217], v161 offset:20480
	ds_read_b128 v[218:221], v161 offset:21504
	ds_read_b128 v[222:225], v161 offset:22528
	ds_read_b128 v[226:229], v161 offset:23552
	buffer_load_dwordx4 v131, s[12:15], s39 offen lds
	s_mov_b32 m0, s33
	s_add_i32 s47, s39, 0x80000
	buffer_load_dwordx4 v155, s[12:15], s39 offen lds
	s_mov_b32 m0, s34
	s_nop 0
	buffer_load_dwordx4 v131, s[12:15], s47 offen lds
	s_mov_b32 m0, s35
	s_nop 0
	buffer_load_dwordx4 v155, s[12:15], s47 offen lds
	s_mov_b32 m0, s3
	s_nop 0
	buffer_load_dwordx4 v129, s[20:23], s46 offen lds
	s_mov_b32 m0, s36
	s_nop 0
	buffer_load_dwordx4 v133, s[20:23], s46 offen lds
	s_waitcnt vmcnt(8)
	s_waitcnt lgkmcnt(0)
	s_barrier
	s_setprio 1
	v_mfma_f32_16x16x32_bf16 v[60:63], v[148:151], v[198:201], v[60:63]
	v_mfma_f32_16x16x32_bf16 v[56:59], v[174:177], v[198:201], v[56:59]
	v_mfma_f32_16x16x32_bf16 v[44:47], v[148:151], v[206:209], v[44:47]
	v_mfma_f32_16x16x32_bf16 v[40:43], v[174:177], v[206:209], v[40:43]
	v_mfma_f32_16x16x32_bf16 v[28:31], v[148:151], v[214:217], v[28:31]
	v_mfma_f32_16x16x32_bf16 v[24:27], v[174:177], v[214:217], v[24:27]
	v_mfma_f32_16x16x32_bf16 v[12:15], v[148:151], v[222:225], v[12:15]
	v_mfma_f32_16x16x32_bf16 v[8:11], v[174:177], v[222:225], v[8:11]
	v_mfma_f32_16x16x32_bf16 v[60:63], v[170:173], v[202:205], v[60:63]
	v_mfma_f32_16x16x32_bf16 v[56:59], v[178:181], v[202:205], v[56:59]
	v_mfma_f32_16x16x32_bf16 v[44:47], v[170:173], v[210:213], v[44:47]
	v_mfma_f32_16x16x32_bf16 v[40:43], v[178:181], v[210:213], v[40:43]
	v_mfma_f32_16x16x32_bf16 v[28:31], v[170:173], v[218:221], v[28:31]
	v_mfma_f32_16x16x32_bf16 v[24:27], v[178:181], v[218:221], v[24:27]
	v_mfma_f32_16x16x32_bf16 v[12:15], v[170:173], v[226:229], v[12:15]
	v_mfma_f32_16x16x32_bf16 v[8:11], v[178:181], v[226:229], v[8:11]
	s_setprio 0
	s_setprio 1
	v_mfma_f32_16x16x32_bf16 v[52:55], v[182:185], v[198:201], v[52:55]
	v_mfma_f32_16x16x32_bf16 v[48:51], v[190:193], v[198:201], v[48:51]
	v_mfma_f32_16x16x32_bf16 v[36:39], v[182:185], v[206:209], v[36:39]
	v_mfma_f32_16x16x32_bf16 v[32:35], v[190:193], v[206:209], v[32:35]
	v_mfma_f32_16x16x32_bf16 v[20:23], v[182:185], v[214:217], v[20:23]
	v_mfma_f32_16x16x32_bf16 v[16:19], v[190:193], v[214:217], v[16:19]
	v_mfma_f32_16x16x32_bf16 v[4:7], v[182:185], v[222:225], v[4:7]
	v_mfma_f32_16x16x32_bf16 v[0:3], v[190:193], v[222:225], v[0:3]
	v_mfma_f32_16x16x32_bf16 v[52:55], v[186:189], v[202:205], v[52:55]
	v_mfma_f32_16x16x32_bf16 v[48:51], v[194:197], v[202:205], v[48:51]
	v_mfma_f32_16x16x32_bf16 v[36:39], v[186:189], v[210:213], v[36:39]
	v_mfma_f32_16x16x32_bf16 v[32:35], v[194:197], v[210:213], v[32:35]
	v_mfma_f32_16x16x32_bf16 v[20:23], v[186:189], v[218:221], v[20:23]
	v_mfma_f32_16x16x32_bf16 v[16:19], v[194:197], v[218:221], v[16:19]
	v_mfma_f32_16x16x32_bf16 v[4:7], v[186:189], v[226:229], v[4:7]
	v_mfma_f32_16x16x32_bf16 v[0:3], v[194:197], v[226:229], v[0:3]
	s_setprio 0
	s_barrier
; #define PG8_STAGE(srd, bufoff, goff, voff) do { _Pragma("unroll") for (int _i = 0; _i < 2; ++_i) \
;         __builtin_amdgcn_raw_ptr_buffer_load_lds(srd, (PG8_LAS unsigned*)(lds + (bufoff) + ldsw + _i * 8192), 16, (voff)[_i], (goff), 0, 0); } while (0)
; #define PG8_LDA(dst, b, h) do { _Pragma("unroll") for (int m = 0; m < 4; ++m) _Pragma("unroll") for (int k = 0; k < 2; ++k) dst[m][k] = *(const PG8_LAS bf16x8*)(lds + PG8_SA(b, h) + aoff + m * 2048 + k * 1024); } while (0)
; #define PG8_LDB(dst, b, h) do { _Pragma("unroll") for (int n = 0; n < 2; ++n) _Pragma("unroll") for (int k = 0; k < 2; ++k) dst[n][k] = *(const PG8_LAS bf16x8*)(lds + PG8_SB(b, h) + boff + n * 2048 + k * 1024); } while (0)
; #define PG8_MMA(ai, bj, At, Bt) do { __builtin_amdgcn_s_setprio(1); _Pragma("unroll") for (int m = 0; m < 4; ++m) _Pragma("unroll") for (int n = 0; n < 2; ++n) _Pragma("unroll") for (int k = 0; k < 2; ++k) \
;         acc[ai][bj][m][n] = __builtin_amdgcn_mfma_f32_16x16x32_bf16(Bt[n][k], At[m][k], acc[ai][bj][m][n], 0, 0, 0); __builtin_amdgcn_s_setprio(0); } while (0)
; #define PG8_WAIT_V(n) asm volatile("s_waitcnt vmcnt(" #n ")" ::: "memory")
; #define PG8_WAIT_L(n) asm volatile("s_waitcnt lgkmcnt(" #n ")" ::: "memory")
; #define PG8_BAR __builtin_amdgcn_s_barrier()
; #define PG8_SCHED __builtin_amdgcn_sched_barrier(0)
; template <class Epi, class Sched, bool ALIGN_EPI = true>
; __device__ __forceinline__ void gemm_phase(PG8_LAS unsigned char* lds, const Gemm g, const Sched& S, const Epi& E) {
;     ...
;             PG8_LDB(B0, 1, 0); PG8_LDB(B1, 1, 1); PG8_SCHED; PG8_LDA(At, 1, 0); PG8_STAGE(srdA, PG8_SA(0, 1), a2 + hstepA, voffA);
;             PG8_WAIT_V(8); PG8_WAIT_L(0); PG8_BAR; PG8_MMA(0, 0, At, B0); PG8_MMA(0, 1, At, B1); PG8_BAR; PG8_SCHED;
;             PG8_LDA(At, 1, 1); PG8_STAGE(srdB, PG8_SB(1, 0), b3, voffB); PG8_STAGE(srdB, PG8_SB(1, 1), b3 + hstepB, voffB); PG8_STAGE(srdA, PG8_SA(1, 0), a3, voffA);
;             PG8_WAIT_V(8); PG8_WAIT_L(0); PG8_BAR; PG8_MMA(1, 0, At, B0); PG8_MMA(1, 1, At, B1); PG8_BAR; PG8_SCHED;
;         }
	ds_read_b128 v[148:151], v163
	ds_read_b128 v[170:173], v163 offset:1024
	ds_read_b128 v[174:177], v163 offset:2048
	ds_read_b128 v[178:181], v163 offset:3072
	ds_read_b128 v[182:185], v165
	ds_read_b128 v[186:189], v165 offset:1024
	ds_read_b128 v[190:193], v165 offset:2048
	ds_read_b128 v[194:197], v165 offset:3072
	s_add_i32 s46, s46, 0x80000
	s_mov_b32 m0, s37
	ds_read_b128 v[198:201], v161 offset:32768
	ds_read_b128 v[202:205], v161 offset:33792
	ds_read_b128 v[206:209], v161 offset:34816
	ds_read_b128 v[210:213], v161 offset:35840
	ds_read_b128 v[214:217], v161 offset:36864
	ds_read_b128 v[218:221], v161 offset:37888
	ds_read_b128 v[222:225], v161 offset:38912
	ds_read_b128 v[226:229], v161 offset:39936
	buffer_load_dwordx4 v129, s[20:23], s46 offen lds
	s_mov_b32 m0, s42
	s_nop 0
	buffer_load_dwordx4 v133, s[20:23], s46 offen lds
	s_waitcnt vmcnt(8)
	s_waitcnt lgkmcnt(0)
	s_barrier
	s_setprio 1
	v_mfma_f32_16x16x32_bf16 v[124:127], v[148:151], v[198:201], v[124:127]
	v_mfma_f32_16x16x32_bf16 v[120:123], v[174:177], v[198:201], v[120:123]
	v_mfma_f32_16x16x32_bf16 v[108:111], v[148:151], v[206:209], v[108:111]
	v_mfma_f32_16x16x32_bf16 v[104:107], v[174:177], v[206:209], v[104:107]
	v_mfma_f32_16x16x32_bf16 v[92:95], v[148:151], v[214:217], v[92:95]
	v_mfma_f32_16x16x32_bf16 v[88:91], v[174:177], v[214:217], v[88:91]
	v_mfma_f32_16x16x32_bf16 v[76:79], v[148:151], v[222:225], v[76:79]
	v_mfma_f32_16x16x32_bf16 v[72:75], v[174:177], v[222:225], v[72:75]
	v_mfma_f32_16x16x32_bf16 v[124:127], v[170:173], v[202:205], v[124:127]
	v_mfma_f32_16x16x32_bf16 v[120:123], v[178:181], v[202:205], v[120:123]
	v_mfma_f32_16x16x32_bf16 v[108:111], v[170:173], v[210:213], v[108:111]
	v_mfma_f32_16x16x32_bf16 v[104:107], v[178:181], v[210:213], v[104:107]
	v_mfma_f32_16x16x32_bf16 v[92:95], v[170:173], v[218:221], v[92:95]
	v_mfma_f32_16x16x32_bf16 v[88:91], v[178:181], v[218:221], v[88:91]
	v_mfma_f32_16x16x32_bf16 v[76:79], v[170:173], v[226:229], v[76:79]
	v_mfma_f32_16x16x32_bf16 v[72:75], v[178:181], v[226:229], v[72:75]
	s_setprio 0
	s_setprio 1
	v_mfma_f32_16x16x32_bf16 v[116:119], v[182:185], v[198:201], v[116:119]
	v_mfma_f32_16x16x32_bf16 v[112:115], v[190:193], v[198:201], v[112:115]
	v_mfma_f32_16x16x32_bf16 v[100:103], v[182:185], v[206:209], v[100:103]
	v_mfma_f32_16x16x32_bf16 v[96:99], v[190:193], v[206:209], v[96:99]
	v_mfma_f32_16x16x32_bf16 v[84:87], v[182:185], v[214:217], v[84:87]
	v_mfma_f32_16x16x32_bf16 v[80:83], v[190:193], v[214:217], v[80:83]
	v_mfma_f32_16x16x32_bf16 v[68:71], v[182:185], v[222:225], v[68:71]
	v_mfma_f32_16x16x32_bf16 v[64:67], v[190:193], v[222:225], v[64:67]
	v_mfma_f32_16x16x32_bf16 v[116:119], v[186:189], v[202:205], v[116:119]
	v_mfma_f32_16x16x32_bf16 v[112:115], v[194:197], v[202:205], v[112:115]
	v_mfma_f32_16x16x32_bf16 v[100:103], v[186:189], v[210:213], v[100:103]
	v_mfma_f32_16x16x32_bf16 v[96:99], v[194:197], v[210:213], v[96:99]
	v_mfma_f32_16x16x32_bf16 v[84:87], v[186:189], v[218:221], v[84:87]
	v_mfma_f32_16x16x32_bf16 v[80:83], v[194:197], v[218:221], v[80:83]
	v_mfma_f32_16x16x32_bf16 v[68:71], v[186:189], v[226:229], v[68:71]
	v_mfma_f32_16x16x32_bf16 v[64:67], v[194:197], v[226:229], v[64:67]
	s_setprio 0
	s_barrier
	s_mov_b32 m0, s45
	s_or_b32 s46, s39, 0x80
	ds_read_b128 v[198:201], v161 offset:49152
	ds_read_b128 v[202:205], v161 offset:50176
	ds_read_b128 v[206:209], v161 offset:51200
	ds_read_b128 v[210:213], v161 offset:52224
	ds_read_b128 v[214:217], v161 offset:53248
	ds_read_b128 v[218:221], v161 offset:54272
	ds_read_b128 v[222:225], v161 offset:55296
	ds_read_b128 v[226:229], v161 offset:56320
	buffer_load_dwordx4 v131, s[12:15], s46 offen lds
	s_mov_b32 m0, s64
	s_add_i32 s39, s39, 0x80080
	buffer_load_dwordx4 v155, s[12:15], s46 offen lds
	s_mov_b32 m0, s67
	s_nop 0
	buffer_load_dwordx4 v131, s[12:15], s39 offen lds
	s_mov_b32 m0, s68
	s_nop 0
	buffer_load_dwordx4 v155, s[12:15], s39 offen lds
	s_mov_b32 m0, s65
	s_nop 0
	buffer_load_dwordx4 v129, s[20:23], s38 offen lds
	s_mov_b32 m0, s66
	s_nop 0
	buffer_load_dwordx4 v133, s[20:23], s38 offen lds
	s_waitcnt vmcnt(8)
	s_waitcnt lgkmcnt(0)
	s_barrier
	s_setprio 1
	v_mfma_f32_16x16x32_bf16 v[60:63], v[148:151], v[198:201], v[60:63]
	v_mfma_f32_16x16x32_bf16 v[56:59], v[174:177], v[198:201], v[56:59]
	v_mfma_f32_16x16x32_bf16 v[44:47], v[148:151], v[206:209], v[44:47]
	v_mfma_f32_16x16x32_bf16 v[40:43], v[174:177], v[206:209], v[40:43]
	v_mfma_f32_16x16x32_bf16 v[28:31], v[148:151], v[214:217], v[28:31]
	v_mfma_f32_16x16x32_bf16 v[24:27], v[174:177], v[214:217], v[24:27]
	v_mfma_f32_16x16x32_bf16 v[12:15], v[148:151], v[222:225], v[12:15]
	v_mfma_f32_16x16x32_bf16 v[8:11], v[174:177], v[222:225], v[8:11]
	v_mfma_f32_16x16x32_bf16 v[60:63], v[170:173], v[202:205], v[60:63]
	v_mfma_f32_16x16x32_bf16 v[56:59], v[178:181], v[202:205], v[56:59]
	v_mfma_f32_16x16x32_bf16 v[44:47], v[170:173], v[210:213], v[44:47]
	v_mfma_f32_16x16x32_bf16 v[40:43], v[178:181], v[210:213], v[40:43]
	v_mfma_f32_16x16x32_bf16 v[28:31], v[170:173], v[218:221], v[28:31]
	v_mfma_f32_16x16x32_bf16 v[24:27], v[178:181], v[218:221], v[24:27]
	v_mfma_f32_16x16x32_bf16 v[12:15], v[170:173], v[226:229], v[12:15]
	v_mfma_f32_16x16x32_bf16 v[8:11], v[178:181], v[226:229], v[8:11]
	s_setprio 0
	s_setprio 1
	v_mfma_f32_16x16x32_bf16 v[52:55], v[182:185], v[198:201], v[52:55]
	v_mfma_f32_16x16x32_bf16 v[48:51], v[190:193], v[198:201], v[48:51]
	v_mfma_f32_16x16x32_bf16 v[36:39], v[182:185], v[206:209], v[36:39]
	v_mfma_f32_16x16x32_bf16 v[32:35], v[190:193], v[206:209], v[32:35]
	v_mfma_f32_16x16x32_bf16 v[20:23], v[182:185], v[214:217], v[20:23]
	v_mfma_f32_16x16x32_bf16 v[16:19], v[190:193], v[214:217], v[16:19]
	v_mfma_f32_16x16x32_bf16 v[4:7], v[182:185], v[222:225], v[4:7]
	v_mfma_f32_16x16x32_bf16 v[0:3], v[190:193], v[222:225], v[0:3]
	v_mfma_f32_16x16x32_bf16 v[52:55], v[186:189], v[202:205], v[52:55]
	v_mfma_f32_16x16x32_bf16 v[48:51], v[194:197], v[202:205], v[48:51]
	v_mfma_f32_16x16x32_bf16 v[36:39], v[186:189], v[210:213], v[36:39]
	v_mfma_f32_16x16x32_bf16 v[32:35], v[194:197], v[210:213], v[32:35]
	v_mfma_f32_16x16x32_bf16 v[20:23], v[186:189], v[218:221], v[20:23]
	v_mfma_f32_16x16x32_bf16 v[16:19], v[194:197], v[218:221], v[16:19]
	v_mfma_f32_16x16x32_bf16 v[4:7], v[186:189], v[226:229], v[4:7]
	v_mfma_f32_16x16x32_bf16 v[0:3], v[194:197], v[226:229], v[0:3]
	s_setprio 0
	s_barrier
	s_add_i32 s92, s92, 2
	s_addk_i32 s80, 0x100
	s_addk_i32 s91, 0x100
	s_cmp_gt_u32 s92, 29
	s_cbranch_scc0 .LBB0_189
	s_and_b64 vcc, exec, s[26:27]
	s_cbranch_vccnz .LBB0_194
	s_cmp_gt_i32 s90, 2
	s_mov_b64 s[10:11], -1
	s_cbranch_scc1 .LBB0_195

; #define PG8_STAGE(srd, bufoff, goff, voff) do { _Pragma("unroll") for (int _i = 0; _i < 2; ++_i) \
;         __builtin_amdgcn_raw_ptr_buffer_load_lds(srd, (PG8_LAS unsigned*)(lds + (bufoff) + ldsw + _i * 8192), 16, (voff)[_i], (goff), 0, 0); } while (0)
; #define PG8_LDA(dst, b, h) do { _Pragma("unroll") for (int m = 0; m < 4; ++m) _Pragma("unroll") for (int k = 0; k < 2; ++k) dst[m][k] = *(const PG8_LAS bf16x8*)(lds + PG8_SA(b, h) + aoff + m * 2048 + k * 1024); } while (0)
; #define PG8_LDB(dst, b, h) do { _Pragma("unroll") for (int n = 0; n < 2; ++n) _Pragma("unroll") for (int k = 0; k < 2; ++k) dst[n][k] = *(const PG8_LAS bf16x8*)(lds + PG8_SB(b, h) + boff + n * 2048 + k * 1024); } while (0)
; #define PG8_MMA(ai, bj, At, Bt) do { __builtin_amdgcn_s_setprio(1); _Pragma("unroll") for (int m = 0; m < 4; ++m) _Pragma("unroll") for (int n = 0; n < 2; ++n) _Pragma("unroll") for (int k = 0; k < 2; ++k) \
;         acc[ai][bj][m][n] = __builtin_amdgcn_mfma_f32_16x16x32_bf16(Bt[n][k], At[m][k], acc[ai][bj][m][n], 0, 0, 0); __builtin_amdgcn_s_setprio(0); } while (0)
; #define PG8_WAIT_V(n) asm volatile("s_waitcnt vmcnt(" #n ")" ::: "memory")
; #define PG8_WAIT_L(n) asm volatile("s_waitcnt lgkmcnt(" #n ")" ::: "memory")
; #define PG8_BAR __builtin_amdgcn_s_barrier()
; #define PG8_SCHED __builtin_amdgcn_sched_barrier(0)
; template <class Epi, class Sched, bool ALIGN_EPI = true>
; __device__ __forceinline__ void gemm_phase(PG8_LAS unsigned char* lds, const Gemm g, const Sched& S, const Epi& E) {
;     ...
;             PG8_LDB(B0, 0, 0); PG8_LDB(B1, 0, 1); PG8_SCHED; PG8_LDA(At, 0, 0); PG8_STAGE(srdA, PG8_SA(1, 1), a1 + hstepA, voffA);
;             PG8_WAIT_V(8); PG8_WAIT_L(0); PG8_BAR; PG8_MMA(0, 0, At, B0); PG8_MMA(0, 1, At, B1); PG8_BAR; PG8_SCHED;
;             PG8_LDA(At, 0, 1); PG8_STAGE(srdB, PG8_SB(0, 0), b2, voffB); PG8_STAGE(srdB, PG8_SB(0, 1), b2 + hstepB, voffB); PG8_STAGE(srdA, PG8_SA(0, 0), a2, voffA);
;             PG8_WAIT_V(8); PG8_WAIT_L(0); PG8_BAR; PG8_MMA(1, 0, At, B0); PG8_MMA(1, 1, At, B1); PG8_BAR; PG8_SCHED;
.LBB0_288:
	ds_read_b128 v[146:149], v140
	ds_read_b128 v[150:153], v140 offset:1024
	ds_read_b128 v[156:159], v140 offset:2048
	ds_read_b128 v[170:173], v140 offset:3072
	ds_read_b128 v[174:177], v141
	ds_read_b128 v[178:181], v141 offset:1024
	ds_read_b128 v[182:185], v141 offset:2048
	ds_read_b128 v[186:189], v141 offset:3072
	s_add_i32 s38, s9, 0xfffd0080
	s_cmp_eq_u32 s75, 4
	s_cselect_b32 s39, s71, s38
	s_cselect_b32 s46, s8, s74
	s_add_i32 s38, s39, 0x80
	s_mov_b32 m0, s45
	ds_read_b128 v[190:193], v142
	ds_read_b128 v[194:197], v142 offset:1024
	ds_read_b128 v[198:201], v142 offset:2048
	ds_read_b128 v[202:205], v142 offset:3072
	ds_read_b128 v[206:209], v142 offset:4096
	ds_read_b128 v[210:213], v142 offset:5120
	ds_read_b128 v[214:217], v142 offset:6144
	ds_read_b128 v[218:221], v142 offset:7168
	buffer_load_dwordx4 v129, s[40:43], s9 offen lds
	s_mov_b32 m0, s68
	s_nop 0
	buffer_load_dwordx4 v134, s[40:43], s9 offen lds
	s_waitcnt vmcnt(8)
	s_waitcnt lgkmcnt(0)
	s_barrier
	s_setprio 1
	v_mfma_f32_16x16x32_bf16 v[124:127], v[146:149], v[190:193], v[124:127]
	v_mfma_f32_16x16x32_bf16 v[120:123], v[156:159], v[190:193], v[120:123]
	v_mfma_f32_16x16x32_bf16 v[116:119], v[146:149], v[198:201], v[116:119]
	v_mfma_f32_16x16x32_bf16 v[112:115], v[156:159], v[198:201], v[112:115]
	v_mfma_f32_16x16x32_bf16 v[100:103], v[146:149], v[206:209], v[100:103]
	v_mfma_f32_16x16x32_bf16 v[96:99], v[156:159], v[206:209], v[96:99]
	v_mfma_f32_16x16x32_bf16 v[84:87], v[146:149], v[214:217], v[84:87]
	v_mfma_f32_16x16x32_bf16 v[80:83], v[156:159], v[214:217], v[80:83]
	v_mfma_f32_16x16x32_bf16 v[124:127], v[150:153], v[194:197], v[124:127]
	v_mfma_f32_16x16x32_bf16 v[120:123], v[170:173], v[194:197], v[120:123]
	v_mfma_f32_16x16x32_bf16 v[116:119], v[150:153], v[202:205], v[116:119]
	v_mfma_f32_16x16x32_bf16 v[112:115], v[170:173], v[202:205], v[112:115]
	v_mfma_f32_16x16x32_bf16 v[100:103], v[150:153], v[210:213], v[100:103]
	v_mfma_f32_16x16x32_bf16 v[96:99], v[170:173], v[210:213], v[96:99]
	v_mfma_f32_16x16x32_bf16 v[84:87], v[150:153], v[218:221], v[84:87]
	v_mfma_f32_16x16x32_bf16 v[80:83], v[170:173], v[218:221], v[80:83]
	s_setprio 0
	s_setprio 1
	v_mfma_f32_16x16x32_bf16 v[108:111], v[174:177], v[190:193], v[108:111]
	v_mfma_f32_16x16x32_bf16 v[104:107], v[182:185], v[190:193], v[104:107]
	v_mfma_f32_16x16x32_bf16 v[92:95], v[174:177], v[198:201], v[92:95]
	v_mfma_f32_16x16x32_bf16 v[88:91], v[182:185], v[198:201], v[88:91]
	v_mfma_f32_16x16x32_bf16 v[76:79], v[174:177], v[206:209], v[76:79]
	v_mfma_f32_16x16x32_bf16 v[72:75], v[182:185], v[206:209], v[72:75]
	v_mfma_f32_16x16x32_bf16 v[68:71], v[174:177], v[214:217], v[68:71]
	v_mfma_f32_16x16x32_bf16 v[64:67], v[182:185], v[214:217], v[64:67]
	v_mfma_f32_16x16x32_bf16 v[108:111], v[178:181], v[194:197], v[108:111]
	v_mfma_f32_16x16x32_bf16 v[104:107], v[186:189], v[194:197], v[104:107]
	v_mfma_f32_16x16x32_bf16 v[92:95], v[178:181], v[202:205], v[92:95]
	v_mfma_f32_16x16x32_bf16 v[88:91], v[186:189], v[202:205], v[88:91]
	v_mfma_f32_16x16x32_bf16 v[76:79], v[178:181], v[210:213], v[76:79]
	v_mfma_f32_16x16x32_bf16 v[72:75], v[186:189], v[210:213], v[72:75]
	v_mfma_f32_16x16x32_bf16 v[68:71], v[178:181], v[218:221], v[68:71]
	v_mfma_f32_16x16x32_bf16 v[64:67], v[186:189], v[218:221], v[64:67]
	s_setprio 0
	s_barrier
	s_mov_b32 m0, s10
	ds_read_b128 v[190:193], v142 offset:16384
	ds_read_b128 v[194:197], v142 offset:17408
	ds_read_b128 v[198:201], v142 offset:18432
	ds_read_b128 v[202:205], v142 offset:19456
	ds_read_b128 v[206:209], v142 offset:20480
	ds_read_b128 v[210:213], v142 offset:21504
	ds_read_b128 v[214:217], v142 offset:22528
	ds_read_b128 v[218:221], v142 offset:23552
	buffer_load_dwordx4 v131, s[64:67], s46 offen lds
	s_mov_b32 m0, s11
	s_add_i32 s47, s46, 0x20000
	buffer_load_dwordx4 v135, s[64:67], s46 offen lds
	s_mov_b32 m0, s14
	s_nop 0
	buffer_load_dwordx4 v131, s[64:67], s47 offen lds
	s_mov_b32 m0, s15
	s_nop 0
	buffer_load_dwordx4 v135, s[64:67], s47 offen lds
	s_mov_b32 m0, s3
	s_nop 0
	buffer_load_dwordx4 v129, s[40:43], s39 offen lds
	s_mov_b32 m0, s21
	s_nop 0
	buffer_load_dwordx4 v134, s[40:43], s39 offen lds
	s_waitcnt vmcnt(8)
	s_waitcnt lgkmcnt(0)
	s_barrier
	s_setprio 1
	v_mfma_f32_16x16x32_bf16 v[60:63], v[146:149], v[190:193], v[60:63]
	v_mfma_f32_16x16x32_bf16 v[56:59], v[156:159], v[190:193], v[56:59]
	v_mfma_f32_16x16x32_bf16 v[52:55], v[146:149], v[198:201], v[52:55]
	v_mfma_f32_16x16x32_bf16 v[48:51], v[156:159], v[198:201], v[48:51]
	v_mfma_f32_16x16x32_bf16 v[36:39], v[146:149], v[206:209], v[36:39]
	v_mfma_f32_16x16x32_bf16 v[32:35], v[156:159], v[206:209], v[32:35]
	v_mfma_f32_16x16x32_bf16 v[20:23], v[146:149], v[214:217], v[20:23]
	v_mfma_f32_16x16x32_bf16 v[16:19], v[156:159], v[214:217], v[16:19]
	v_mfma_f32_16x16x32_bf16 v[60:63], v[150:153], v[194:197], v[60:63]
	v_mfma_f32_16x16x32_bf16 v[56:59], v[170:173], v[194:197], v[56:59]
	v_mfma_f32_16x16x32_bf16 v[52:55], v[150:153], v[202:205], v[52:55]
	v_mfma_f32_16x16x32_bf16 v[48:51], v[170:173], v[202:205], v[48:51]
	v_mfma_f32_16x16x32_bf16 v[36:39], v[150:153], v[210:213], v[36:39]
	v_mfma_f32_16x16x32_bf16 v[32:35], v[170:173], v[210:213], v[32:35]
	v_mfma_f32_16x16x32_bf16 v[20:23], v[150:153], v[218:221], v[20:23]
	v_mfma_f32_16x16x32_bf16 v[16:19], v[170:173], v[218:221], v[16:19]
	s_setprio 0
	s_setprio 1
	v_mfma_f32_16x16x32_bf16 v[44:47], v[174:177], v[190:193], v[44:47]
	v_mfma_f32_16x16x32_bf16 v[40:43], v[182:185], v[190:193], v[40:43]
	v_mfma_f32_16x16x32_bf16 v[28:31], v[174:177], v[198:201], v[28:31]
	v_mfma_f32_16x16x32_bf16 v[24:27], v[182:185], v[198:201], v[24:27]
	v_mfma_f32_16x16x32_bf16 v[12:15], v[174:177], v[206:209], v[12:15]
	v_mfma_f32_16x16x32_bf16 v[8:11], v[182:185], v[206:209], v[8:11]
	v_mfma_f32_16x16x32_bf16 v[4:7], v[174:177], v[214:217], v[4:7]
	v_mfma_f32_16x16x32_bf16 v[0:3], v[182:185], v[214:217], v[0:3]
	v_mfma_f32_16x16x32_bf16 v[44:47], v[178:181], v[194:197], v[44:47]
	v_mfma_f32_16x16x32_bf16 v[40:43], v[186:189], v[194:197], v[40:43]
	v_mfma_f32_16x16x32_bf16 v[28:31], v[178:181], v[202:205], v[28:31]
	v_mfma_f32_16x16x32_bf16 v[24:27], v[186:189], v[202:205], v[24:27]
	v_mfma_f32_16x16x32_bf16 v[12:15], v[178:181], v[210:213], v[12:15]
	v_mfma_f32_16x16x32_bf16 v[8:11], v[186:189], v[210:213], v[8:11]
	v_mfma_f32_16x16x32_bf16 v[4:7], v[178:181], v[218:221], v[4:7]
	v_mfma_f32_16x16x32_bf16 v[0:3], v[186:189], v[218:221], v[0:3]
	s_setprio 0
	s_barrier
; #define PG8_STAGE(srd, bufoff, goff, voff) do { _Pragma("unroll") for (int _i = 0; _i < 2; ++_i) \
;         __builtin_amdgcn_raw_ptr_buffer_load_lds(srd, (PG8_LAS unsigned*)(lds + (bufoff) + ldsw + _i * 8192), 16, (voff)[_i], (goff), 0, 0); } while (0)
; #define PG8_LDA(dst, b, h) do { _Pragma("unroll") for (int m = 0; m < 4; ++m) _Pragma("unroll") for (int k = 0; k < 2; ++k) dst[m][k] = *(const PG8_LAS bf16x8*)(lds + PG8_SA(b, h) + aoff + m * 2048 + k * 1024); } while (0)
; #define PG8_LDB(dst, b, h) do { _Pragma("unroll") for (int n = 0; n < 2; ++n) _Pragma("unroll") for (int k = 0; k < 2; ++k) dst[n][k] = *(const PG8_LAS bf16x8*)(lds + PG8_SB(b, h) + boff + n * 2048 + k * 1024); } while (0)
; #define PG8_MMA(ai, bj, At, Bt) do { __builtin_amdgcn_s_setprio(1); _Pragma("unroll") for (int m = 0; m < 4; ++m) _Pragma("unroll") for (int n = 0; n < 2; ++n) _Pragma("unroll") for (int k = 0; k < 2; ++k) \
;         acc[ai][bj][m][n] = __builtin_amdgcn_mfma_f32_16x16x32_bf16(Bt[n][k], At[m][k], acc[ai][bj][m][n], 0, 0, 0); __builtin_amdgcn_s_setprio(0); } while (0)
; #define PG8_WAIT_V(n) asm volatile("s_waitcnt vmcnt(" #n ")" ::: "memory")
; #define PG8_WAIT_L(n) asm volatile("s_waitcnt lgkmcnt(" #n ")" ::: "memory")
; #define PG8_BAR __builtin_amdgcn_s_barrier()
; #define PG8_SCHED __builtin_amdgcn_sched_barrier(0)
; template <class Epi, class Sched, bool ALIGN_EPI = true>
; __device__ __forceinline__ void gemm_phase(PG8_LAS unsigned char* lds, const Gemm g, const Sched& S, const Epi& E) {
;     ...
;             PG8_LDB(B0, 1, 0); PG8_LDB(B1, 1, 1); PG8_SCHED; PG8_LDA(At, 1, 0); PG8_STAGE(srdA, PG8_SA(0, 1), a2 + hstepA, voffA);
;             PG8_WAIT_V(8); PG8_WAIT_L(0); PG8_BAR; PG8_MMA(0, 0, At, B0); PG8_MMA(0, 1, At, B1); PG8_BAR; PG8_SCHED;
;             PG8_LDA(At, 1, 1); PG8_STAGE(srdB, PG8_SB(1, 0), b3, voffB); PG8_STAGE(srdB, PG8_SB(1, 1), b3 + hstepB, voffB); PG8_STAGE(srdA, PG8_SA(1, 0), a3, voffA);
;             PG8_WAIT_V(8); PG8_WAIT_L(0); PG8_BAR; PG8_MMA(1, 0, At, B0); PG8_MMA(1, 1, At, B1); PG8_BAR; PG8_SCHED;
;         }
	ds_read_b128 v[146:149], v143
	ds_read_b128 v[150:153], v143 offset:1024
	ds_read_b128 v[156:159], v143 offset:2048
	ds_read_b128 v[170:173], v143 offset:3072
	ds_read_b128 v[174:177], v144
	ds_read_b128 v[178:181], v144 offset:1024
	ds_read_b128 v[182:185], v144 offset:2048
	ds_read_b128 v[186:189], v144 offset:3072
	s_add_i32 s39, s39, 0x30000
	s_mov_b32 m0, s25
	ds_read_b128 v[190:193], v142 offset:32768
	ds_read_b128 v[194:197], v142 offset:33792
	ds_read_b128 v[198:201], v142 offset:34816
	ds_read_b128 v[202:205], v142 offset:35840
	ds_read_b128 v[206:209], v142 offset:36864
	ds_read_b128 v[210:213], v142 offset:37888
	ds_read_b128 v[214:217], v142 offset:38912
	ds_read_b128 v[218:221], v142 offset:39936
	buffer_load_dwordx4 v129, s[40:43], s39 offen lds
	s_mov_b32 m0, s26
	s_nop 0
	buffer_load_dwordx4 v134, s[40:43], s39 offen lds
	s_waitcnt vmcnt(8)
	s_waitcnt lgkmcnt(0)
	s_barrier
	s_setprio 1
	v_mfma_f32_16x16x32_bf16 v[124:127], v[146:149], v[190:193], v[124:127]
	v_mfma_f32_16x16x32_bf16 v[120:123], v[156:159], v[190:193], v[120:123]
	v_mfma_f32_16x16x32_bf16 v[116:119], v[146:149], v[198:201], v[116:119]
	v_mfma_f32_16x16x32_bf16 v[112:115], v[156:159], v[198:201], v[112:115]
	v_mfma_f32_16x16x32_bf16 v[100:103], v[146:149], v[206:209], v[100:103]
	v_mfma_f32_16x16x32_bf16 v[96:99], v[156:159], v[206:209], v[96:99]
	v_mfma_f32_16x16x32_bf16 v[84:87], v[146:149], v[214:217], v[84:87]
	v_mfma_f32_16x16x32_bf16 v[80:83], v[156:159], v[214:217], v[80:83]
	v_mfma_f32_16x16x32_bf16 v[124:127], v[150:153], v[194:197], v[124:127]
	v_mfma_f32_16x16x32_bf16 v[120:123], v[170:173], v[194:197], v[120:123]
	v_mfma_f32_16x16x32_bf16 v[116:119], v[150:153], v[202:205], v[116:119]
	v_mfma_f32_16x16x32_bf16 v[112:115], v[170:173], v[202:205], v[112:115]
	v_mfma_f32_16x16x32_bf16 v[100:103], v[150:153], v[210:213], v[100:103]
	v_mfma_f32_16x16x32_bf16 v[96:99], v[170:173], v[210:213], v[96:99]
	v_mfma_f32_16x16x32_bf16 v[84:87], v[150:153], v[218:221], v[84:87]
	v_mfma_f32_16x16x32_bf16 v[80:83], v[170:173], v[218:221], v[80:83]
	s_setprio 0
	s_setprio 1
	v_mfma_f32_16x16x32_bf16 v[108:111], v[174:177], v[190:193], v[108:111]
	v_mfma_f32_16x16x32_bf16 v[104:107], v[182:185], v[190:193], v[104:107]
	v_mfma_f32_16x16x32_bf16 v[92:95], v[174:177], v[198:201], v[92:95]
	v_mfma_f32_16x16x32_bf16 v[88:91], v[182:185], v[198:201], v[88:91]
	v_mfma_f32_16x16x32_bf16 v[76:79], v[174:177], v[206:209], v[76:79]
	v_mfma_f32_16x16x32_bf16 v[72:75], v[182:185], v[206:209], v[72:75]
	v_mfma_f32_16x16x32_bf16 v[68:71], v[174:177], v[214:217], v[68:71]
	v_mfma_f32_16x16x32_bf16 v[64:67], v[182:185], v[214:217], v[64:67]
	v_mfma_f32_16x16x32_bf16 v[108:111], v[178:181], v[194:197], v[108:111]
	v_mfma_f32_16x16x32_bf16 v[104:107], v[186:189], v[194:197], v[104:107]
	v_mfma_f32_16x16x32_bf16 v[92:95], v[178:181], v[202:205], v[92:95]
	v_mfma_f32_16x16x32_bf16 v[88:91], v[186:189], v[202:205], v[88:91]
	v_mfma_f32_16x16x32_bf16 v[76:79], v[178:181], v[210:213], v[76:79]
	v_mfma_f32_16x16x32_bf16 v[72:75], v[186:189], v[210:213], v[72:75]
	v_mfma_f32_16x16x32_bf16 v[68:71], v[178:181], v[218:221], v[68:71]
	v_mfma_f32_16x16x32_bf16 v[64:67], v[186:189], v[218:221], v[64:67]
	s_setprio 0
	s_barrier
	s_mov_b32 m0, s33
	s_or_b32 s39, s46, 0x80
	ds_read_b128 v[190:193], v142 offset:49152
	ds_read_b128 v[194:197], v142 offset:50176
	ds_read_b128 v[198:201], v142 offset:51200
	ds_read_b128 v[202:205], v142 offset:52224
	ds_read_b128 v[206:209], v142 offset:53248
	ds_read_b128 v[210:213], v142 offset:54272
	ds_read_b128 v[214:217], v142 offset:55296
	ds_read_b128 v[218:221], v142 offset:56320
	buffer_load_dwordx4 v131, s[64:67], s39 offen lds
	s_mov_b32 m0, s34
	s_add_i32 s46, s46, 0x20080
	buffer_load_dwordx4 v135, s[64:67], s39 offen lds
	s_mov_b32 m0, s37
	s_nop 0
	buffer_load_dwordx4 v131, s[64:67], s46 offen lds
	s_mov_b32 m0, s44
	s_nop 0
	buffer_load_dwordx4 v135, s[64:67], s46 offen lds
	s_mov_b32 m0, s35
	s_nop 0
	buffer_load_dwordx4 v129, s[40:43], s38 offen lds
	s_mov_b32 m0, s36
	s_nop 0
	buffer_load_dwordx4 v134, s[40:43], s38 offen lds
	s_waitcnt vmcnt(8)
	s_waitcnt lgkmcnt(0)
	s_barrier
	s_setprio 1
	v_mfma_f32_16x16x32_bf16 v[60:63], v[146:149], v[190:193], v[60:63]
	v_mfma_f32_16x16x32_bf16 v[56:59], v[156:159], v[190:193], v[56:59]
	v_mfma_f32_16x16x32_bf16 v[52:55], v[146:149], v[198:201], v[52:55]
	v_mfma_f32_16x16x32_bf16 v[48:51], v[156:159], v[198:201], v[48:51]
	v_mfma_f32_16x16x32_bf16 v[36:39], v[146:149], v[206:209], v[36:39]
	v_mfma_f32_16x16x32_bf16 v[32:35], v[156:159], v[206:209], v[32:35]
	v_mfma_f32_16x16x32_bf16 v[20:23], v[146:149], v[214:217], v[20:23]
	v_mfma_f32_16x16x32_bf16 v[16:19], v[156:159], v[214:217], v[16:19]
	v_mfma_f32_16x16x32_bf16 v[60:63], v[150:153], v[194:197], v[60:63]
	v_mfma_f32_16x16x32_bf16 v[56:59], v[170:173], v[194:197], v[56:59]
	v_mfma_f32_16x16x32_bf16 v[52:55], v[150:153], v[202:205], v[52:55]
	v_mfma_f32_16x16x32_bf16 v[48:51], v[170:173], v[202:205], v[48:51]
	v_mfma_f32_16x16x32_bf16 v[36:39], v[150:153], v[210:213], v[36:39]
	v_mfma_f32_16x16x32_bf16 v[32:35], v[170:173], v[210:213], v[32:35]
	v_mfma_f32_16x16x32_bf16 v[20:23], v[150:153], v[218:221], v[20:23]
	v_mfma_f32_16x16x32_bf16 v[16:19], v[170:173], v[218:221], v[16:19]
	s_setprio 0
	s_setprio 1
	v_mfma_f32_16x16x32_bf16 v[44:47], v[174:177], v[190:193], v[44:47]
	v_mfma_f32_16x16x32_bf16 v[40:43], v[182:185], v[190:193], v[40:43]
	v_mfma_f32_16x16x32_bf16 v[28:31], v[174:177], v[198:201], v[28:31]
	v_mfma_f32_16x16x32_bf16 v[24:27], v[182:185], v[198:201], v[24:27]
	v_mfma_f32_16x16x32_bf16 v[12:15], v[174:177], v[206:209], v[12:15]
	v_mfma_f32_16x16x32_bf16 v[8:11], v[182:185], v[206:209], v[8:11]
	v_mfma_f32_16x16x32_bf16 v[4:7], v[174:177], v[214:217], v[4:7]
	v_mfma_f32_16x16x32_bf16 v[0:3], v[182:185], v[214:217], v[0:3]
	v_mfma_f32_16x16x32_bf16 v[44:47], v[178:181], v[194:197], v[44:47]
	v_mfma_f32_16x16x32_bf16 v[40:43], v[186:189], v[194:197], v[40:43]
	v_mfma_f32_16x16x32_bf16 v[28:31], v[178:181], v[202:205], v[28:31]
	v_mfma_f32_16x16x32_bf16 v[24:27], v[186:189], v[202:205], v[24:27]
	v_mfma_f32_16x16x32_bf16 v[12:15], v[178:181], v[210:213], v[12:15]
	v_mfma_f32_16x16x32_bf16 v[8:11], v[186:189], v[210:213], v[8:11]
	v_mfma_f32_16x16x32_bf16 v[4:7], v[178:181], v[218:221], v[4:7]
	v_mfma_f32_16x16x32_bf16 v[0:3], v[186:189], v[218:221], v[0:3]
	s_setprio 0
	s_barrier
	s_add_i32 s75, s75, 2
	s_addk_i32 s9, 0x100
	s_addk_i32 s74, 0x100
	s_cmp_gt_u32 s75, 5
	s_cbranch_scc0 .LBB0_288
	s_and_b64 vcc, exec, s[6:7]
	s_cbranch_vccz .LBB0_291
	s_barrier

; #define PG8_STAGE(srd, bufoff, goff, voff) do { _Pragma("unroll") for (int _i = 0; _i < 2; ++_i) \
;         __builtin_amdgcn_raw_ptr_buffer_load_lds(srd, (PG8_LAS unsigned*)(lds + (bufoff) + ldsw + _i * 8192), 16, (voff)[_i], (goff), 0, 0); } while (0)
; #define PG8_LDA(dst, b, h) do { _Pragma("unroll") for (int m = 0; m < 4; ++m) _Pragma("unroll") for (int k = 0; k < 2; ++k) dst[m][k] = *(const PG8_LAS bf16x8*)(lds + PG8_SA(b, h) + aoff + m * 2048 + k * 1024); } while (0)
; #define PG8_LDB(dst, b, h) do { _Pragma("unroll") for (int n = 0; n < 2; ++n) _Pragma("unroll") for (int k = 0; k < 2; ++k) dst[n][k] = *(const PG8_LAS bf16x8*)(lds + PG8_SB(b, h) + boff + n * 2048 + k * 1024); } while (0)
; #define PG8_MMA(ai, bj, At, Bt) do { __builtin_amdgcn_s_setprio(1); _Pragma("unroll") for (int m = 0; m < 4; ++m) _Pragma("unroll") for (int n = 0; n < 2; ++n) _Pragma("unroll") for (int k = 0; k < 2; ++k) \
;         acc[ai][bj][m][n] = __builtin_amdgcn_mfma_f32_16x16x32_bf16(Bt[n][k], At[m][k], acc[ai][bj][m][n], 0, 0, 0); __builtin_amdgcn_s_setprio(0); } while (0)
; #define PG8_WAIT_V(n) asm volatile("s_waitcnt vmcnt(" #n ")" ::: "memory")
; #define PG8_WAIT_L(n) asm volatile("s_waitcnt lgkmcnt(" #n ")" ::: "memory")
; #define PG8_BAR __builtin_amdgcn_s_barrier()
; #define PG8_SCHED __builtin_amdgcn_sched_barrier(0)
; template <class Epi, class Sched, bool ALIGN_EPI = true>
; __device__ __forceinline__ void gemm_phase(PG8_LAS unsigned char* lds, const Gemm g, const Sched& S, const Epi& E) {
;     ...
;             PG8_LDB(B0, 0, 0); PG8_LDB(B1, 0, 1); PG8_SCHED; PG8_LDA(At, 0, 0); PG8_STAGE(srdA, PG8_SA(1, 1), a1 + hstepA, voffA);
;             PG8_WAIT_V(8); PG8_WAIT_L(0); PG8_BAR; PG8_MMA(0, 0, At, B0); PG8_MMA(0, 1, At, B1); PG8_BAR; PG8_SCHED;
;             PG8_LDA(At, 0, 1); PG8_STAGE(srdB, PG8_SB(0, 0), b2, voffB); PG8_STAGE(srdB, PG8_SB(0, 1), b2 + hstepB, voffB); PG8_STAGE(srdA, PG8_SA(0, 0), a2, voffA);
;             PG8_WAIT_V(8); PG8_WAIT_L(0); PG8_BAR; PG8_MMA(1, 0, At, B0); PG8_MMA(1, 1, At, B1); PG8_BAR; PG8_SCHED;
.LBB0_306:
	ds_read_b128 v[138:141], v152
	ds_read_b128 v[142:145], v152 offset:1024
	ds_read_b128 v[170:173], v152 offset:2048
	ds_read_b128 v[174:177], v152 offset:3072
	ds_read_b128 v[178:181], v153
	ds_read_b128 v[182:185], v153 offset:1024
	ds_read_b128 v[186:189], v153 offset:2048
	ds_read_b128 v[190:193], v153 offset:3072
	s_add_i32 s38, s80, 0xfffe0080
	s_cmp_eq_u32 vcc_lo, 4
	s_cselect_b32 s46, s0, s38
	s_cselect_b32 s39, s1, s97
	s_or_b32 s38, s46, 0x80
	s_mov_b32 m0, s81
	ds_read_b128 v[194:197], v155
	ds_read_b128 v[198:201], v155 offset:1024
	ds_read_b128 v[202:205], v155 offset:2048
	ds_read_b128 v[206:209], v155 offset:3072
	ds_read_b128 v[210:213], v155 offset:4096
	ds_read_b128 v[214:217], v155 offset:5120
	ds_read_b128 v[218:221], v155 offset:6144
	ds_read_b128 v[222:225], v155 offset:7168
	buffer_load_dwordx4 v129, s[24:27], s80 offen lds
	s_mov_b32 m0, s82
	s_nop 0
	buffer_load_dwordx4 v148, s[24:27], s80 offen lds
	s_waitcnt vmcnt(8)
	s_waitcnt lgkmcnt(0)
	s_barrier
	s_setprio 1
	v_mfma_f32_16x16x32_bf16 v[124:127], v[138:141], v[194:197], v[124:127]
	v_mfma_f32_16x16x32_bf16 v[120:123], v[170:173], v[194:197], v[120:123]
	v_mfma_f32_16x16x32_bf16 v[108:111], v[138:141], v[202:205], v[108:111]
	v_mfma_f32_16x16x32_bf16 v[104:107], v[170:173], v[202:205], v[104:107]
	v_mfma_f32_16x16x32_bf16 v[92:95], v[138:141], v[210:213], v[92:95]
	v_mfma_f32_16x16x32_bf16 v[88:91], v[170:173], v[210:213], v[88:91]
	v_mfma_f32_16x16x32_bf16 v[76:79], v[138:141], v[218:221], v[76:79]
	v_mfma_f32_16x16x32_bf16 v[72:75], v[170:173], v[218:221], v[72:75]
	v_mfma_f32_16x16x32_bf16 v[124:127], v[142:145], v[198:201], v[124:127]
	v_mfma_f32_16x16x32_bf16 v[120:123], v[174:177], v[198:201], v[120:123]
	v_mfma_f32_16x16x32_bf16 v[108:111], v[142:145], v[206:209], v[108:111]
	v_mfma_f32_16x16x32_bf16 v[104:107], v[174:177], v[206:209], v[104:107]
	v_mfma_f32_16x16x32_bf16 v[92:95], v[142:145], v[214:217], v[92:95]
	v_mfma_f32_16x16x32_bf16 v[88:91], v[174:177], v[214:217], v[88:91]
	v_mfma_f32_16x16x32_bf16 v[76:79], v[142:145], v[222:225], v[76:79]
	v_mfma_f32_16x16x32_bf16 v[72:75], v[174:177], v[222:225], v[72:75]
	s_setprio 0
	s_setprio 1
	v_mfma_f32_16x16x32_bf16 v[116:119], v[178:181], v[194:197], v[116:119]
	v_mfma_f32_16x16x32_bf16 v[112:115], v[186:189], v[194:197], v[112:115]
	v_mfma_f32_16x16x32_bf16 v[100:103], v[178:181], v[202:205], v[100:103]
	v_mfma_f32_16x16x32_bf16 v[96:99], v[186:189], v[202:205], v[96:99]
	v_mfma_f32_16x16x32_bf16 v[84:87], v[178:181], v[210:213], v[84:87]
	v_mfma_f32_16x16x32_bf16 v[80:83], v[186:189], v[210:213], v[80:83]
	v_mfma_f32_16x16x32_bf16 v[68:71], v[178:181], v[218:221], v[68:71]
	v_mfma_f32_16x16x32_bf16 v[64:67], v[186:189], v[218:221], v[64:67]
	v_mfma_f32_16x16x32_bf16 v[116:119], v[182:185], v[198:201], v[116:119]
	v_mfma_f32_16x16x32_bf16 v[112:115], v[190:193], v[198:201], v[112:115]
	v_mfma_f32_16x16x32_bf16 v[100:103], v[182:185], v[206:209], v[100:103]
	v_mfma_f32_16x16x32_bf16 v[96:99], v[190:193], v[206:209], v[96:99]
	v_mfma_f32_16x16x32_bf16 v[84:87], v[182:185], v[214:217], v[84:87]
	v_mfma_f32_16x16x32_bf16 v[80:83], v[190:193], v[214:217], v[80:83]
	v_mfma_f32_16x16x32_bf16 v[68:71], v[182:185], v[222:225], v[68:71]
	v_mfma_f32_16x16x32_bf16 v[64:67], v[190:193], v[222:225], v[64:67]
	s_setprio 0
	s_barrier
	s_mov_b32 m0, s11
	s_mov_b32 s66, s26
	s_mov_b32 s67, s27
	ds_read_b128 v[194:197], v155 offset:16384
	ds_read_b128 v[198:201], v155 offset:17408
	ds_read_b128 v[202:205], v155 offset:18432
	ds_read_b128 v[206:209], v155 offset:19456
	ds_read_b128 v[210:213], v155 offset:20480
	ds_read_b128 v[214:217], v155 offset:21504
	ds_read_b128 v[218:221], v155 offset:22528
	ds_read_b128 v[222:225], v155 offset:23552
	buffer_load_dwordx4 v131, s[64:67], s39 offen lds
	s_mov_b32 m0, s21
	s_add_i32 s47, s39, 0x20000
	buffer_load_dwordx4 v149, s[64:67], s39 offen lds
	s_mov_b32 m0, s29
	s_nop 0
	buffer_load_dwordx4 v131, s[64:67], s47 offen lds
	s_mov_b32 m0, s33
	s_nop 0
	buffer_load_dwordx4 v149, s[64:67], s47 offen lds
	s_mov_b32 m0, s10
	s_nop 0
	buffer_load_dwordx4 v129, s[24:27], s46 offen lds
	s_mov_b32 m0, s34
	s_nop 0
	buffer_load_dwordx4 v148, s[24:27], s46 offen lds
	s_waitcnt vmcnt(8)
	s_waitcnt lgkmcnt(0)
	s_barrier
	s_setprio 1
	v_mfma_f32_16x16x32_bf16 v[60:63], v[138:141], v[194:197], v[60:63]
	v_mfma_f32_16x16x32_bf16 v[56:59], v[170:173], v[194:197], v[56:59]
	v_mfma_f32_16x16x32_bf16 v[44:47], v[138:141], v[202:205], v[44:47]
	v_mfma_f32_16x16x32_bf16 v[40:43], v[170:173], v[202:205], v[40:43]
	v_mfma_f32_16x16x32_bf16 v[28:31], v[138:141], v[210:213], v[28:31]
	v_mfma_f32_16x16x32_bf16 v[24:27], v[170:173], v[210:213], v[24:27]
	v_mfma_f32_16x16x32_bf16 v[12:15], v[138:141], v[218:221], v[12:15]
	v_mfma_f32_16x16x32_bf16 v[8:11], v[170:173], v[218:221], v[8:11]
	v_mfma_f32_16x16x32_bf16 v[60:63], v[142:145], v[198:201], v[60:63]
	v_mfma_f32_16x16x32_bf16 v[56:59], v[174:177], v[198:201], v[56:59]
	v_mfma_f32_16x16x32_bf16 v[44:47], v[142:145], v[206:209], v[44:47]
	v_mfma_f32_16x16x32_bf16 v[40:43], v[174:177], v[206:209], v[40:43]
	v_mfma_f32_16x16x32_bf16 v[28:31], v[142:145], v[214:217], v[28:31]
	v_mfma_f32_16x16x32_bf16 v[24:27], v[174:177], v[214:217], v[24:27]
	v_mfma_f32_16x16x32_bf16 v[12:15], v[142:145], v[222:225], v[12:15]
	v_mfma_f32_16x16x32_bf16 v[8:11], v[174:177], v[222:225], v[8:11]
	s_setprio 0
	s_setprio 1
	v_mfma_f32_16x16x32_bf16 v[52:55], v[178:181], v[194:197], v[52:55]
	v_mfma_f32_16x16x32_bf16 v[48:51], v[186:189], v[194:197], v[48:51]
	v_mfma_f32_16x16x32_bf16 v[36:39], v[178:181], v[202:205], v[36:39]
	v_mfma_f32_16x16x32_bf16 v[32:35], v[186:189], v[202:205], v[32:35]
	v_mfma_f32_16x16x32_bf16 v[20:23], v[178:181], v[210:213], v[20:23]
	v_mfma_f32_16x16x32_bf16 v[16:19], v[186:189], v[210:213], v[16:19]
	v_mfma_f32_16x16x32_bf16 v[4:7], v[178:181], v[218:221], v[4:7]
	v_mfma_f32_16x16x32_bf16 v[0:3], v[186:189], v[218:221], v[0:3]
	v_mfma_f32_16x16x32_bf16 v[52:55], v[182:185], v[198:201], v[52:55]
	v_mfma_f32_16x16x32_bf16 v[48:51], v[190:193], v[198:201], v[48:51]
	v_mfma_f32_16x16x32_bf16 v[36:39], v[182:185], v[206:209], v[36:39]
	v_mfma_f32_16x16x32_bf16 v[32:35], v[190:193], v[206:209], v[32:35]
	v_mfma_f32_16x16x32_bf16 v[20:23], v[182:185], v[214:217], v[20:23]
	v_mfma_f32_16x16x32_bf16 v[16:19], v[190:193], v[214:217], v[16:19]
	v_mfma_f32_16x16x32_bf16 v[4:7], v[182:185], v[222:225], v[4:7]
	v_mfma_f32_16x16x32_bf16 v[0:3], v[190:193], v[222:225], v[0:3]
	s_setprio 0
	s_barrier
; #define PG8_STAGE(srd, bufoff, goff, voff) do { _Pragma("unroll") for (int _i = 0; _i < 2; ++_i) \
;         __builtin_amdgcn_raw_ptr_buffer_load_lds(srd, (PG8_LAS unsigned*)(lds + (bufoff) + ldsw + _i * 8192), 16, (voff)[_i], (goff), 0, 0); } while (0)
; #define PG8_LDA(dst, b, h) do { _Pragma("unroll") for (int m = 0; m < 4; ++m) _Pragma("unroll") for (int k = 0; k < 2; ++k) dst[m][k] = *(const PG8_LAS bf16x8*)(lds + PG8_SA(b, h) + aoff + m * 2048 + k * 1024); } while (0)
; #define PG8_LDB(dst, b, h) do { _Pragma("unroll") for (int n = 0; n < 2; ++n) _Pragma("unroll") for (int k = 0; k < 2; ++k) dst[n][k] = *(const PG8_LAS bf16x8*)(lds + PG8_SB(b, h) + boff + n * 2048 + k * 1024); } while (0)
; #define PG8_MMA(ai, bj, At, Bt) do { __builtin_amdgcn_s_setprio(1); _Pragma("unroll") for (int m = 0; m < 4; ++m) _Pragma("unroll") for (int n = 0; n < 2; ++n) _Pragma("unroll") for (int k = 0; k < 2; ++k) \
;         acc[ai][bj][m][n] = __builtin_amdgcn_mfma_f32_16x16x32_bf16(Bt[n][k], At[m][k], acc[ai][bj][m][n], 0, 0, 0); __builtin_amdgcn_s_setprio(0); } while (0)
; #define PG8_WAIT_V(n) asm volatile("s_waitcnt vmcnt(" #n ")" ::: "memory")
; #define PG8_WAIT_L(n) asm volatile("s_waitcnt lgkmcnt(" #n ")" ::: "memory")
; #define PG8_BAR __builtin_amdgcn_s_barrier()
; #define PG8_SCHED __builtin_amdgcn_sched_barrier(0)
; template <class Epi, class Sched, bool ALIGN_EPI = true>
; __device__ __forceinline__ void gemm_phase(PG8_LAS unsigned char* lds, const Gemm g, const Sched& S, const Epi& E) {
;     ...
;             PG8_LDB(B0, 1, 0); PG8_LDB(B1, 1, 1); PG8_SCHED; PG8_LDA(At, 1, 0); PG8_STAGE(srdA, PG8_SA(0, 1), a2 + hstepA, voffA);
;             PG8_WAIT_V(8); PG8_WAIT_L(0); PG8_BAR; PG8_MMA(0, 0, At, B0); PG8_MMA(0, 1, At, B1); PG8_BAR; PG8_SCHED;
;             PG8_LDA(At, 1, 1); PG8_STAGE(srdB, PG8_SB(1, 0), b3, voffB); PG8_STAGE(srdB, PG8_SB(1, 1), b3 + hstepB, voffB); PG8_STAGE(srdA, PG8_SA(1, 0), a3, voffA);
;             PG8_WAIT_V(8); PG8_WAIT_L(0); PG8_BAR; PG8_MMA(1, 0, At, B0); PG8_MMA(1, 1, At, B1); PG8_BAR; PG8_SCHED;
;         }
	ds_read_b128 v[138:141], v156
	ds_read_b128 v[142:145], v156 offset:1024
	ds_read_b128 v[170:173], v156 offset:2048
	ds_read_b128 v[174:177], v156 offset:3072
	ds_read_b128 v[178:181], v157
	ds_read_b128 v[182:185], v157 offset:1024
	ds_read_b128 v[186:189], v157 offset:2048
	ds_read_b128 v[190:193], v157 offset:3072
	s_add_i32 s46, s46, 0x20000
	s_mov_b32 m0, s35
	ds_read_b128 v[194:197], v155 offset:32768
	ds_read_b128 v[198:201], v155 offset:33792
	ds_read_b128 v[202:205], v155 offset:34816
	ds_read_b128 v[206:209], v155 offset:35840
	ds_read_b128 v[210:213], v155 offset:36864
	ds_read_b128 v[214:217], v155 offset:37888
	ds_read_b128 v[218:221], v155 offset:38912
	ds_read_b128 v[222:225], v155 offset:39936
	buffer_load_dwordx4 v129, s[24:27], s46 offen lds
	s_mov_b32 m0, s44
	s_nop 0
	buffer_load_dwordx4 v148, s[24:27], s46 offen lds
	s_waitcnt vmcnt(8)
	s_waitcnt lgkmcnt(0)
	s_barrier
	s_setprio 1
	v_mfma_f32_16x16x32_bf16 v[124:127], v[138:141], v[194:197], v[124:127]
	v_mfma_f32_16x16x32_bf16 v[120:123], v[170:173], v[194:197], v[120:123]
	v_mfma_f32_16x16x32_bf16 v[108:111], v[138:141], v[202:205], v[108:111]
	v_mfma_f32_16x16x32_bf16 v[104:107], v[170:173], v[202:205], v[104:107]
	v_mfma_f32_16x16x32_bf16 v[92:95], v[138:141], v[210:213], v[92:95]
	v_mfma_f32_16x16x32_bf16 v[88:91], v[170:173], v[210:213], v[88:91]
	v_mfma_f32_16x16x32_bf16 v[76:79], v[138:141], v[218:221], v[76:79]
	v_mfma_f32_16x16x32_bf16 v[72:75], v[170:173], v[218:221], v[72:75]
	v_mfma_f32_16x16x32_bf16 v[124:127], v[142:145], v[198:201], v[124:127]
	v_mfma_f32_16x16x32_bf16 v[120:123], v[174:177], v[198:201], v[120:123]
	v_mfma_f32_16x16x32_bf16 v[108:111], v[142:145], v[206:209], v[108:111]
	v_mfma_f32_16x16x32_bf16 v[104:107], v[174:177], v[206:209], v[104:107]
	v_mfma_f32_16x16x32_bf16 v[92:95], v[142:145], v[214:217], v[92:95]
	v_mfma_f32_16x16x32_bf16 v[88:91], v[174:177], v[214:217], v[88:91]
	v_mfma_f32_16x16x32_bf16 v[76:79], v[142:145], v[222:225], v[76:79]
	v_mfma_f32_16x16x32_bf16 v[72:75], v[174:177], v[222:225], v[72:75]
	s_setprio 0
	s_setprio 1
	v_mfma_f32_16x16x32_bf16 v[116:119], v[178:181], v[194:197], v[116:119]
	v_mfma_f32_16x16x32_bf16 v[112:115], v[186:189], v[194:197], v[112:115]
	v_mfma_f32_16x16x32_bf16 v[100:103], v[178:181], v[202:205], v[100:103]
	v_mfma_f32_16x16x32_bf16 v[96:99], v[186:189], v[202:205], v[96:99]
	v_mfma_f32_16x16x32_bf16 v[84:87], v[178:181], v[210:213], v[84:87]
	v_mfma_f32_16x16x32_bf16 v[80:83], v[186:189], v[210:213], v[80:83]
	v_mfma_f32_16x16x32_bf16 v[68:71], v[178:181], v[218:221], v[68:71]
	v_mfma_f32_16x16x32_bf16 v[64:67], v[186:189], v[218:221], v[64:67]
	v_mfma_f32_16x16x32_bf16 v[116:119], v[182:185], v[198:201], v[116:119]
	v_mfma_f32_16x16x32_bf16 v[112:115], v[190:193], v[198:201], v[112:115]
	v_mfma_f32_16x16x32_bf16 v[100:103], v[182:185], v[206:209], v[100:103]
	v_mfma_f32_16x16x32_bf16 v[96:99], v[190:193], v[206:209], v[96:99]
	v_mfma_f32_16x16x32_bf16 v[84:87], v[182:185], v[214:217], v[84:87]
	v_mfma_f32_16x16x32_bf16 v[80:83], v[190:193], v[214:217], v[80:83]
	v_mfma_f32_16x16x32_bf16 v[68:71], v[182:185], v[222:225], v[68:71]
	v_mfma_f32_16x16x32_bf16 v[64:67], v[190:193], v[222:225], v[64:67]
	s_setprio 0
	s_barrier
	s_mov_b32 m0, s70
	s_or_b32 s46, s39, 0x80
	ds_read_b128 v[194:197], v155 offset:49152
	ds_read_b128 v[198:201], v155 offset:50176
	ds_read_b128 v[202:205], v155 offset:51200
	ds_read_b128 v[206:209], v155 offset:52224
	ds_read_b128 v[210:213], v155 offset:53248
	ds_read_b128 v[214:217], v155 offset:54272
	ds_read_b128 v[218:221], v155 offset:55296
	ds_read_b128 v[222:225], v155 offset:56320
	buffer_load_dwordx4 v131, s[64:67], s46 offen lds
	s_mov_b32 m0, s71
	s_add_i32 s39, s39, 0x20080
	buffer_load_dwordx4 v149, s[64:67], s46 offen lds
	s_mov_b32 m0, s74
	s_nop 0
	buffer_load_dwordx4 v131, s[64:67], s39 offen lds
	s_mov_b32 m0, s75
	s_nop 0
	buffer_load_dwordx4 v149, s[64:67], s39 offen lds
	s_mov_b32 m0, s72
	s_nop 0
	buffer_load_dwordx4 v129, s[24:27], s38 offen lds
	s_mov_b32 m0, s73
	s_nop 0
	buffer_load_dwordx4 v148, s[24:27], s38 offen lds
	s_waitcnt vmcnt(8)
	s_waitcnt lgkmcnt(0)
	s_barrier
	s_setprio 1
	v_mfma_f32_16x16x32_bf16 v[60:63], v[138:141], v[194:197], v[60:63]
	v_mfma_f32_16x16x32_bf16 v[56:59], v[170:173], v[194:197], v[56:59]
	v_mfma_f32_16x16x32_bf16 v[44:47], v[138:141], v[202:205], v[44:47]
	v_mfma_f32_16x16x32_bf16 v[40:43], v[170:173], v[202:205], v[40:43]
	v_mfma_f32_16x16x32_bf16 v[28:31], v[138:141], v[210:213], v[28:31]
	v_mfma_f32_16x16x32_bf16 v[24:27], v[170:173], v[210:213], v[24:27]
	v_mfma_f32_16x16x32_bf16 v[12:15], v[138:141], v[218:221], v[12:15]
	v_mfma_f32_16x16x32_bf16 v[8:11], v[170:173], v[218:221], v[8:11]
	v_mfma_f32_16x16x32_bf16 v[60:63], v[142:145], v[198:201], v[60:63]
	v_mfma_f32_16x16x32_bf16 v[56:59], v[174:177], v[198:201], v[56:59]
	v_mfma_f32_16x16x32_bf16 v[44:47], v[142:145], v[206:209], v[44:47]
	v_mfma_f32_16x16x32_bf16 v[40:43], v[174:177], v[206:209], v[40:43]
	v_mfma_f32_16x16x32_bf16 v[28:31], v[142:145], v[214:217], v[28:31]
	v_mfma_f32_16x16x32_bf16 v[24:27], v[174:177], v[214:217], v[24:27]
	v_mfma_f32_16x16x32_bf16 v[12:15], v[142:145], v[222:225], v[12:15]
	v_mfma_f32_16x16x32_bf16 v[8:11], v[174:177], v[222:225], v[8:11]
	s_setprio 0
	s_setprio 1
	v_mfma_f32_16x16x32_bf16 v[52:55], v[178:181], v[194:197], v[52:55]
	v_mfma_f32_16x16x32_bf16 v[48:51], v[186:189], v[194:197], v[48:51]
	v_mfma_f32_16x16x32_bf16 v[36:39], v[178:181], v[202:205], v[36:39]
	v_mfma_f32_16x16x32_bf16 v[32:35], v[186:189], v[202:205], v[32:35]
	v_mfma_f32_16x16x32_bf16 v[20:23], v[178:181], v[210:213], v[20:23]
	v_mfma_f32_16x16x32_bf16 v[16:19], v[186:189], v[210:213], v[16:19]
	v_mfma_f32_16x16x32_bf16 v[4:7], v[178:181], v[218:221], v[4:7]
	v_mfma_f32_16x16x32_bf16 v[0:3], v[186:189], v[218:221], v[0:3]
	v_mfma_f32_16x16x32_bf16 v[52:55], v[182:185], v[198:201], v[52:55]
	v_mfma_f32_16x16x32_bf16 v[48:51], v[190:193], v[198:201], v[48:51]
	v_mfma_f32_16x16x32_bf16 v[36:39], v[182:185], v[206:209], v[36:39]
	v_mfma_f32_16x16x32_bf16 v[32:35], v[190:193], v[206:209], v[32:35]
	v_mfma_f32_16x16x32_bf16 v[20:23], v[182:185], v[214:217], v[20:23]
	v_mfma_f32_16x16x32_bf16 v[16:19], v[190:193], v[214:217], v[16:19]
	v_mfma_f32_16x16x32_bf16 v[4:7], v[182:185], v[222:225], v[4:7]
	v_mfma_f32_16x16x32_bf16 v[0:3], v[190:193], v[222:225], v[0:3]
	s_setprio 0
	s_barrier
	s_add_i32 vcc_lo, vcc_lo, 2
	s_addk_i32 s80, 0x100
	s_addk_i32 s97, 0x100
	s_cmp_gt_u32 vcc_lo, 5
	s_cbranch_scc0 .LBB0_306
	s_and_b64 vcc, exec, s[36:37]
	s_cbranch_vccz .LBB0_309
	s_barrier

; #define PG8_STAGE(srd, bufoff, goff, voff) do { _Pragma("unroll") for (int _i = 0; _i < 2; ++_i) \
;         __builtin_amdgcn_raw_ptr_buffer_load_lds(srd, (PG8_LAS unsigned*)(lds + (bufoff) + ldsw + _i * 8192), 16, (voff)[_i], (goff), 0, 0); } while (0)
; #define PG8_LDA(dst, b, h) do { _Pragma("unroll") for (int m = 0; m < 4; ++m) _Pragma("unroll") for (int k = 0; k < 2; ++k) dst[m][k] = *(const PG8_LAS bf16x8*)(lds + PG8_SA(b, h) + aoff + m * 2048 + k * 1024); } while (0)
; #define PG8_LDB(dst, b, h) do { _Pragma("unroll") for (int n = 0; n < 2; ++n) _Pragma("unroll") for (int k = 0; k < 2; ++k) dst[n][k] = *(const PG8_LAS bf16x8*)(lds + PG8_SB(b, h) + boff + n * 2048 + k * 1024); } while (0)
; #define PG8_MMA(ai, bj, At, Bt) do { __builtin_amdgcn_s_setprio(1); _Pragma("unroll") for (int m = 0; m < 4; ++m) _Pragma("unroll") for (int n = 0; n < 2; ++n) _Pragma("unroll") for (int k = 0; k < 2; ++k) \
;         acc[ai][bj][m][n] = __builtin_amdgcn_mfma_f32_16x16x32_bf16(Bt[n][k], At[m][k], acc[ai][bj][m][n], 0, 0, 0); __builtin_amdgcn_s_setprio(0); } while (0)
; #define PG8_WAIT_V(n) asm volatile("s_waitcnt vmcnt(" #n ")" ::: "memory")
; #define PG8_WAIT_L(n) asm volatile("s_waitcnt lgkmcnt(" #n ")" ::: "memory")
; #define PG8_BAR __builtin_amdgcn_s_barrier()
; #define PG8_SCHED __builtin_amdgcn_sched_barrier(0)
; template <class Epi, class Sched, bool ALIGN_EPI = true>
; __device__ __forceinline__ void gemm_phase(PG8_LAS unsigned char* lds, const Gemm g, const Sched& S, const Epi& E) {
;     ...
;             PG8_LDB(B0, 0, 0); PG8_LDB(B1, 0, 1); PG8_SCHED; PG8_LDA(At, 0, 0); PG8_STAGE(srdA, PG8_SA(1, 1), a1 + hstepA, voffA);
;             PG8_WAIT_V(8); PG8_WAIT_L(0); PG8_BAR; PG8_MMA(0, 0, At, B0); PG8_MMA(0, 1, At, B1); PG8_BAR; PG8_SCHED;
;             PG8_LDA(At, 0, 1); PG8_STAGE(srdB, PG8_SB(0, 0), b2, voffB); PG8_STAGE(srdB, PG8_SB(0, 1), b2 + hstepB, voffB); PG8_STAGE(srdA, PG8_SA(0, 0), a2, voffA);
;             PG8_WAIT_V(8); PG8_WAIT_L(0); PG8_BAR; PG8_MMA(1, 0, At, B0); PG8_MMA(1, 1, At, B1); PG8_BAR; PG8_SCHED;
.LBB0_513:
	ds_read_b128 v[148:151], v143
	ds_read_b128 v[156:159], v143 offset:1024
	ds_read_b128 v[170:173], v143 offset:2048
	ds_read_b128 v[174:177], v143 offset:3072
	ds_read_b128 v[178:181], v144
	ds_read_b128 v[182:185], v144 offset:1024
	ds_read_b128 v[186:189], v144 offset:2048
	ds_read_b128 v[190:193], v144 offset:3072
	s_add_i32 s38, s10, 0xfffd0080
	s_cmp_eq_u32 s71, 8
	s_cselect_b32 s39, s68, s38
	s_cselect_b32 s46, s69, s11
	s_add_i32 s38, s39, 0x80
	s_mov_b32 m0, s63
	ds_read_b128 v[194:197], v145
	ds_read_b128 v[198:201], v145 offset:1024
	ds_read_b128 v[202:205], v145 offset:2048
	ds_read_b128 v[206:209], v145 offset:3072
	ds_read_b128 v[210:213], v145 offset:4096
	ds_read_b128 v[214:217], v145 offset:5120
	ds_read_b128 v[218:221], v145 offset:6144
	ds_read_b128 v[222:225], v145 offset:7168
	buffer_load_dwordx4 v130, s[40:43], s10 offen lds
	s_mov_b32 m0, s64
	s_nop 0
	buffer_load_dwordx4 v132, s[40:43], s10 offen lds
	s_waitcnt vmcnt(8)
	s_waitcnt lgkmcnt(0)
	s_barrier
	s_setprio 1
	v_mfma_f32_16x16x32_bf16 v[124:127], v[148:151], v[194:197], v[124:127]
	v_mfma_f32_16x16x32_bf16 v[120:123], v[170:173], v[194:197], v[120:123]
	v_mfma_f32_16x16x32_bf16 v[108:111], v[148:151], v[202:205], v[108:111]
	v_mfma_f32_16x16x32_bf16 v[104:107], v[170:173], v[202:205], v[104:107]
	v_mfma_f32_16x16x32_bf16 v[92:95], v[148:151], v[210:213], v[92:95]
	v_mfma_f32_16x16x32_bf16 v[88:91], v[170:173], v[210:213], v[88:91]
	v_mfma_f32_16x16x32_bf16 v[76:79], v[148:151], v[218:221], v[76:79]
	v_mfma_f32_16x16x32_bf16 v[72:75], v[170:173], v[218:221], v[72:75]
	v_mfma_f32_16x16x32_bf16 v[124:127], v[156:159], v[198:201], v[124:127]
	v_mfma_f32_16x16x32_bf16 v[120:123], v[174:177], v[198:201], v[120:123]
	v_mfma_f32_16x16x32_bf16 v[108:111], v[156:159], v[206:209], v[108:111]
	v_mfma_f32_16x16x32_bf16 v[104:107], v[174:177], v[206:209], v[104:107]
	v_mfma_f32_16x16x32_bf16 v[92:95], v[156:159], v[214:217], v[92:95]
	v_mfma_f32_16x16x32_bf16 v[88:91], v[174:177], v[214:217], v[88:91]
	v_mfma_f32_16x16x32_bf16 v[76:79], v[156:159], v[222:225], v[76:79]
	v_mfma_f32_16x16x32_bf16 v[72:75], v[174:177], v[222:225], v[72:75]
	s_setprio 0
	s_setprio 1
	v_mfma_f32_16x16x32_bf16 v[116:119], v[178:181], v[194:197], v[116:119]
	v_mfma_f32_16x16x32_bf16 v[112:115], v[186:189], v[194:197], v[112:115]
	v_mfma_f32_16x16x32_bf16 v[100:103], v[178:181], v[202:205], v[100:103]
	v_mfma_f32_16x16x32_bf16 v[96:99], v[186:189], v[202:205], v[96:99]
	v_mfma_f32_16x16x32_bf16 v[84:87], v[178:181], v[210:213], v[84:87]
	v_mfma_f32_16x16x32_bf16 v[80:83], v[186:189], v[210:213], v[80:83]
	v_mfma_f32_16x16x32_bf16 v[68:71], v[178:181], v[218:221], v[68:71]
	v_mfma_f32_16x16x32_bf16 v[64:67], v[186:189], v[218:221], v[64:67]
	v_mfma_f32_16x16x32_bf16 v[116:119], v[182:185], v[198:201], v[116:119]
	v_mfma_f32_16x16x32_bf16 v[112:115], v[190:193], v[198:201], v[112:115]
	v_mfma_f32_16x16x32_bf16 v[100:103], v[182:185], v[206:209], v[100:103]
	v_mfma_f32_16x16x32_bf16 v[96:99], v[190:193], v[206:209], v[96:99]
	v_mfma_f32_16x16x32_bf16 v[84:87], v[182:185], v[214:217], v[84:87]
	v_mfma_f32_16x16x32_bf16 v[80:83], v[190:193], v[214:217], v[80:83]
	v_mfma_f32_16x16x32_bf16 v[68:71], v[182:185], v[222:225], v[68:71]
	v_mfma_f32_16x16x32_bf16 v[64:67], v[190:193], v[222:225], v[64:67]
	s_setprio 0
	s_barrier
	s_mov_b32 m0, s21
	ds_read_b128 v[194:197], v145 offset:16384
	ds_read_b128 v[198:201], v145 offset:17408
	ds_read_b128 v[202:205], v145 offset:18432
	ds_read_b128 v[206:209], v145 offset:19456
	ds_read_b128 v[210:213], v145 offset:20480
	ds_read_b128 v[214:217], v145 offset:21504
	ds_read_b128 v[218:221], v145 offset:22528
	ds_read_b128 v[222:225], v145 offset:23552
	buffer_load_dwordx4 v131, s[52:55], s46 offen lds
	s_mov_b32 m0, s29
	s_add_i32 s47, s46, 0x30000
	buffer_load_dwordx4 v133, s[52:55], s46 offen lds
	s_mov_b32 m0, s33
	s_nop 0
	buffer_load_dwordx4 v131, s[52:55], s47 offen lds
	s_mov_b32 m0, s34
	s_nop 0
	buffer_load_dwordx4 v133, s[52:55], s47 offen lds
	s_mov_b32 m0, s3
	s_nop 0
	buffer_load_dwordx4 v130, s[40:43], s39 offen lds
	s_mov_b32 m0, s35
	s_nop 0
	buffer_load_dwordx4 v132, s[40:43], s39 offen lds
	s_waitcnt vmcnt(8)
	s_waitcnt lgkmcnt(0)
	s_barrier
	s_setprio 1
	v_mfma_f32_16x16x32_bf16 v[60:63], v[148:151], v[194:197], v[60:63]
	v_mfma_f32_16x16x32_bf16 v[56:59], v[170:173], v[194:197], v[56:59]
	v_mfma_f32_16x16x32_bf16 v[44:47], v[148:151], v[202:205], v[44:47]
	v_mfma_f32_16x16x32_bf16 v[40:43], v[170:173], v[202:205], v[40:43]
	v_mfma_f32_16x16x32_bf16 v[28:31], v[148:151], v[210:213], v[28:31]
	v_mfma_f32_16x16x32_bf16 v[24:27], v[170:173], v[210:213], v[24:27]
	v_mfma_f32_16x16x32_bf16 v[12:15], v[148:151], v[218:221], v[12:15]
	v_mfma_f32_16x16x32_bf16 v[8:11], v[170:173], v[218:221], v[8:11]
	v_mfma_f32_16x16x32_bf16 v[60:63], v[156:159], v[198:201], v[60:63]
	v_mfma_f32_16x16x32_bf16 v[56:59], v[174:177], v[198:201], v[56:59]
	v_mfma_f32_16x16x32_bf16 v[44:47], v[156:159], v[206:209], v[44:47]
	v_mfma_f32_16x16x32_bf16 v[40:43], v[174:177], v[206:209], v[40:43]
	v_mfma_f32_16x16x32_bf16 v[28:31], v[156:159], v[214:217], v[28:31]
	v_mfma_f32_16x16x32_bf16 v[24:27], v[174:177], v[214:217], v[24:27]
	v_mfma_f32_16x16x32_bf16 v[12:15], v[156:159], v[222:225], v[12:15]
	v_mfma_f32_16x16x32_bf16 v[8:11], v[174:177], v[222:225], v[8:11]
	s_setprio 0
	s_setprio 1
	v_mfma_f32_16x16x32_bf16 v[52:55], v[178:181], v[194:197], v[52:55]
	v_mfma_f32_16x16x32_bf16 v[48:51], v[186:189], v[194:197], v[48:51]
	v_mfma_f32_16x16x32_bf16 v[36:39], v[178:181], v[202:205], v[36:39]
	v_mfma_f32_16x16x32_bf16 v[32:35], v[186:189], v[202:205], v[32:35]
	v_mfma_f32_16x16x32_bf16 v[20:23], v[178:181], v[210:213], v[20:23]
	v_mfma_f32_16x16x32_bf16 v[16:19], v[186:189], v[210:213], v[16:19]
	v_mfma_f32_16x16x32_bf16 v[4:7], v[178:181], v[218:221], v[4:7]
	v_mfma_f32_16x16x32_bf16 v[0:3], v[186:189], v[218:221], v[0:3]
	v_mfma_f32_16x16x32_bf16 v[52:55], v[182:185], v[198:201], v[52:55]
	v_mfma_f32_16x16x32_bf16 v[48:51], v[190:193], v[198:201], v[48:51]
	v_mfma_f32_16x16x32_bf16 v[36:39], v[182:185], v[206:209], v[36:39]
	v_mfma_f32_16x16x32_bf16 v[32:35], v[190:193], v[206:209], v[32:35]
	v_mfma_f32_16x16x32_bf16 v[20:23], v[182:185], v[214:217], v[20:23]
	v_mfma_f32_16x16x32_bf16 v[16:19], v[190:193], v[214:217], v[16:19]
	v_mfma_f32_16x16x32_bf16 v[4:7], v[182:185], v[222:225], v[4:7]
	v_mfma_f32_16x16x32_bf16 v[0:3], v[190:193], v[222:225], v[0:3]
	s_setprio 0
	s_barrier
; #define PG8_STAGE(srd, bufoff, goff, voff) do { _Pragma("unroll") for (int _i = 0; _i < 2; ++_i) \
;         __builtin_amdgcn_raw_ptr_buffer_load_lds(srd, (PG8_LAS unsigned*)(lds + (bufoff) + ldsw + _i * 8192), 16, (voff)[_i], (goff), 0, 0); } while (0)
; #define PG8_LDA(dst, b, h) do { _Pragma("unroll") for (int m = 0; m < 4; ++m) _Pragma("unroll") for (int k = 0; k < 2; ++k) dst[m][k] = *(const PG8_LAS bf16x8*)(lds + PG8_SA(b, h) + aoff + m * 2048 + k * 1024); } while (0)
; #define PG8_LDB(dst, b, h) do { _Pragma("unroll") for (int n = 0; n < 2; ++n) _Pragma("unroll") for (int k = 0; k < 2; ++k) dst[n][k] = *(const PG8_LAS bf16x8*)(lds + PG8_SB(b, h) + boff + n * 2048 + k * 1024); } while (0)
; #define PG8_MMA(ai, bj, At, Bt) do { __builtin_amdgcn_s_setprio(1); _Pragma("unroll") for (int m = 0; m < 4; ++m) _Pragma("unroll") for (int n = 0; n < 2; ++n) _Pragma("unroll") for (int k = 0; k < 2; ++k) \
;         acc[ai][bj][m][n] = __builtin_amdgcn_mfma_f32_16x16x32_bf16(Bt[n][k], At[m][k], acc[ai][bj][m][n], 0, 0, 0); __builtin_amdgcn_s_setprio(0); } while (0)
; #define PG8_WAIT_V(n) asm volatile("s_waitcnt vmcnt(" #n ")" ::: "memory")
; #define PG8_WAIT_L(n) asm volatile("s_waitcnt lgkmcnt(" #n ")" ::: "memory")
; #define PG8_BAR __builtin_amdgcn_s_barrier()
; #define PG8_SCHED __builtin_amdgcn_sched_barrier(0)
; template <class Epi, class Sched, bool ALIGN_EPI = true>
; __device__ __forceinline__ void gemm_phase(PG8_LAS unsigned char* lds, const Gemm g, const Sched& S, const Epi& E) {
;     ...
;             PG8_LDB(B0, 1, 0); PG8_LDB(B1, 1, 1); PG8_SCHED; PG8_LDA(At, 1, 0); PG8_STAGE(srdA, PG8_SA(0, 1), a2 + hstepA, voffA);
;             PG8_WAIT_V(8); PG8_WAIT_L(0); PG8_BAR; PG8_MMA(0, 0, At, B0); PG8_MMA(0, 1, At, B1); PG8_BAR; PG8_SCHED;
;             PG8_LDA(At, 1, 1); PG8_STAGE(srdB, PG8_SB(1, 0), b3, voffB); PG8_STAGE(srdB, PG8_SB(1, 1), b3 + hstepB, voffB); PG8_STAGE(srdA, PG8_SA(1, 0), a3, voffA);
;             PG8_WAIT_V(8); PG8_WAIT_L(0); PG8_BAR; PG8_MMA(1, 0, At, B0); PG8_MMA(1, 1, At, B1); PG8_BAR; PG8_SCHED;
;         }
	ds_read_b128 v[148:151], v146
	ds_read_b128 v[156:159], v146 offset:1024
	ds_read_b128 v[170:173], v146 offset:2048
	ds_read_b128 v[174:177], v146 offset:3072
	ds_read_b128 v[178:181], v147
	ds_read_b128 v[182:185], v147 offset:1024
	ds_read_b128 v[186:189], v147 offset:2048
	ds_read_b128 v[190:193], v147 offset:3072
	s_add_i32 s39, s39, 0x30000
	s_mov_b32 m0, s36
	ds_read_b128 v[194:197], v145 offset:32768
	ds_read_b128 v[198:201], v145 offset:33792
	ds_read_b128 v[202:205], v145 offset:34816
	ds_read_b128 v[206:209], v145 offset:35840
	ds_read_b128 v[210:213], v145 offset:36864
	ds_read_b128 v[214:217], v145 offset:37888
	ds_read_b128 v[218:221], v145 offset:38912
	ds_read_b128 v[222:225], v145 offset:39936
	buffer_load_dwordx4 v130, s[40:43], s39 offen lds
	s_mov_b32 m0, s37
	s_nop 0
	buffer_load_dwordx4 v132, s[40:43], s39 offen lds
	s_waitcnt vmcnt(8)
	s_waitcnt lgkmcnt(0)
	s_barrier
	s_setprio 1
	v_mfma_f32_16x16x32_bf16 v[124:127], v[148:151], v[194:197], v[124:127]
	v_mfma_f32_16x16x32_bf16 v[120:123], v[170:173], v[194:197], v[120:123]
	v_mfma_f32_16x16x32_bf16 v[108:111], v[148:151], v[202:205], v[108:111]
	v_mfma_f32_16x16x32_bf16 v[104:107], v[170:173], v[202:205], v[104:107]
	v_mfma_f32_16x16x32_bf16 v[92:95], v[148:151], v[210:213], v[92:95]
	v_mfma_f32_16x16x32_bf16 v[88:91], v[170:173], v[210:213], v[88:91]
	v_mfma_f32_16x16x32_bf16 v[76:79], v[148:151], v[218:221], v[76:79]
	v_mfma_f32_16x16x32_bf16 v[72:75], v[170:173], v[218:221], v[72:75]
	v_mfma_f32_16x16x32_bf16 v[124:127], v[156:159], v[198:201], v[124:127]
	v_mfma_f32_16x16x32_bf16 v[120:123], v[174:177], v[198:201], v[120:123]
	v_mfma_f32_16x16x32_bf16 v[108:111], v[156:159], v[206:209], v[108:111]
	v_mfma_f32_16x16x32_bf16 v[104:107], v[174:177], v[206:209], v[104:107]
	v_mfma_f32_16x16x32_bf16 v[92:95], v[156:159], v[214:217], v[92:95]
	v_mfma_f32_16x16x32_bf16 v[88:91], v[174:177], v[214:217], v[88:91]
	v_mfma_f32_16x16x32_bf16 v[76:79], v[156:159], v[222:225], v[76:79]
	v_mfma_f32_16x16x32_bf16 v[72:75], v[174:177], v[222:225], v[72:75]
	s_setprio 0
	s_setprio 1
	v_mfma_f32_16x16x32_bf16 v[116:119], v[178:181], v[194:197], v[116:119]
	v_mfma_f32_16x16x32_bf16 v[112:115], v[186:189], v[194:197], v[112:115]
	v_mfma_f32_16x16x32_bf16 v[100:103], v[178:181], v[202:205], v[100:103]
	v_mfma_f32_16x16x32_bf16 v[96:99], v[186:189], v[202:205], v[96:99]
	v_mfma_f32_16x16x32_bf16 v[84:87], v[178:181], v[210:213], v[84:87]
	v_mfma_f32_16x16x32_bf16 v[80:83], v[186:189], v[210:213], v[80:83]
	v_mfma_f32_16x16x32_bf16 v[68:71], v[178:181], v[218:221], v[68:71]
	v_mfma_f32_16x16x32_bf16 v[64:67], v[186:189], v[218:221], v[64:67]
	v_mfma_f32_16x16x32_bf16 v[116:119], v[182:185], v[198:201], v[116:119]
	v_mfma_f32_16x16x32_bf16 v[112:115], v[190:193], v[198:201], v[112:115]
	v_mfma_f32_16x16x32_bf16 v[100:103], v[182:185], v[206:209], v[100:103]
	v_mfma_f32_16x16x32_bf16 v[96:99], v[190:193], v[206:209], v[96:99]
	v_mfma_f32_16x16x32_bf16 v[84:87], v[182:185], v[214:217], v[84:87]
	v_mfma_f32_16x16x32_bf16 v[80:83], v[190:193], v[214:217], v[80:83]
	v_mfma_f32_16x16x32_bf16 v[68:71], v[182:185], v[222:225], v[68:71]
	v_mfma_f32_16x16x32_bf16 v[64:67], v[190:193], v[222:225], v[64:67]
	s_setprio 0
	s_barrier
	s_mov_b32 m0, s45
	s_add_i32 s39, s46, 0x80
	ds_read_b128 v[194:197], v145 offset:49152
	ds_read_b128 v[198:201], v145 offset:50176
	ds_read_b128 v[202:205], v145 offset:51200
	ds_read_b128 v[206:209], v145 offset:52224
	ds_read_b128 v[210:213], v145 offset:53248
	ds_read_b128 v[214:217], v145 offset:54272
	ds_read_b128 v[218:221], v145 offset:55296
	ds_read_b128 v[222:225], v145 offset:56320
	buffer_load_dwordx4 v131, s[52:55], s39 offen lds
	s_mov_b32 m0, s56
	s_add_i32 s46, s46, 0x30080
	buffer_load_dwordx4 v133, s[52:55], s39 offen lds
	s_mov_b32 m0, s61
	s_nop 0
	buffer_load_dwordx4 v131, s[52:55], s46 offen lds
	s_mov_b32 m0, s62
	s_nop 0
	buffer_load_dwordx4 v133, s[52:55], s46 offen lds
	s_mov_b32 m0, s57
	s_nop 0
	buffer_load_dwordx4 v130, s[40:43], s38 offen lds
	s_mov_b32 m0, s60
	s_nop 0
	buffer_load_dwordx4 v132, s[40:43], s38 offen lds
	s_waitcnt vmcnt(8)
	s_waitcnt lgkmcnt(0)
	s_barrier
	s_setprio 1
	v_mfma_f32_16x16x32_bf16 v[60:63], v[148:151], v[194:197], v[60:63]
	v_mfma_f32_16x16x32_bf16 v[56:59], v[170:173], v[194:197], v[56:59]
	v_mfma_f32_16x16x32_bf16 v[44:47], v[148:151], v[202:205], v[44:47]
	v_mfma_f32_16x16x32_bf16 v[40:43], v[170:173], v[202:205], v[40:43]
	v_mfma_f32_16x16x32_bf16 v[28:31], v[148:151], v[210:213], v[28:31]
	v_mfma_f32_16x16x32_bf16 v[24:27], v[170:173], v[210:213], v[24:27]
	v_mfma_f32_16x16x32_bf16 v[12:15], v[148:151], v[218:221], v[12:15]
	v_mfma_f32_16x16x32_bf16 v[8:11], v[170:173], v[218:221], v[8:11]
	v_mfma_f32_16x16x32_bf16 v[60:63], v[156:159], v[198:201], v[60:63]
	v_mfma_f32_16x16x32_bf16 v[56:59], v[174:177], v[198:201], v[56:59]
	v_mfma_f32_16x16x32_bf16 v[44:47], v[156:159], v[206:209], v[44:47]
	v_mfma_f32_16x16x32_bf16 v[40:43], v[174:177], v[206:209], v[40:43]
	v_mfma_f32_16x16x32_bf16 v[28:31], v[156:159], v[214:217], v[28:31]
	v_mfma_f32_16x16x32_bf16 v[24:27], v[174:177], v[214:217], v[24:27]
	v_mfma_f32_16x16x32_bf16 v[12:15], v[156:159], v[222:225], v[12:15]
	v_mfma_f32_16x16x32_bf16 v[8:11], v[174:177], v[222:225], v[8:11]
	s_setprio 0
	s_setprio 1
	v_mfma_f32_16x16x32_bf16 v[52:55], v[178:181], v[194:197], v[52:55]
	v_mfma_f32_16x16x32_bf16 v[48:51], v[186:189], v[194:197], v[48:51]
	v_mfma_f32_16x16x32_bf16 v[36:39], v[178:181], v[202:205], v[36:39]
	v_mfma_f32_16x16x32_bf16 v[32:35], v[186:189], v[202:205], v[32:35]
	v_mfma_f32_16x16x32_bf16 v[20:23], v[178:181], v[210:213], v[20:23]
	v_mfma_f32_16x16x32_bf16 v[16:19], v[186:189], v[210:213], v[16:19]
	v_mfma_f32_16x16x32_bf16 v[4:7], v[178:181], v[218:221], v[4:7]
	v_mfma_f32_16x16x32_bf16 v[0:3], v[186:189], v[218:221], v[0:3]
	v_mfma_f32_16x16x32_bf16 v[52:55], v[182:185], v[198:201], v[52:55]
	v_mfma_f32_16x16x32_bf16 v[48:51], v[190:193], v[198:201], v[48:51]
	v_mfma_f32_16x16x32_bf16 v[36:39], v[182:185], v[206:209], v[36:39]
	v_mfma_f32_16x16x32_bf16 v[32:35], v[190:193], v[206:209], v[32:35]
	v_mfma_f32_16x16x32_bf16 v[20:23], v[182:185], v[214:217], v[20:23]
	v_mfma_f32_16x16x32_bf16 v[16:19], v[190:193], v[214:217], v[16:19]
	v_mfma_f32_16x16x32_bf16 v[4:7], v[182:185], v[222:225], v[4:7]
	v_mfma_f32_16x16x32_bf16 v[0:3], v[190:193], v[222:225], v[0:3]
	s_setprio 0
	s_barrier
	s_add_i32 s71, s71, 2
	s_addk_i32 s10, 0x100
	s_addk_i32 s11, 0x100
	s_cmp_gt_u32 s71, 9
	s_cbranch_scc0 .LBB0_513
	s_and_b64 vcc, exec, s[8:9]
	s_cbranch_vccz .LBB0_516
	s_barrier

; #define PG8_STAGE(srd, bufoff, goff, voff) do { _Pragma("unroll") for (int _i = 0; _i < 2; ++_i) \
;         __builtin_amdgcn_raw_ptr_buffer_load_lds(srd, (PG8_LAS unsigned*)(lds + (bufoff) + ldsw + _i * 8192), 16, (voff)[_i], (goff), 0, 0); } while (0)
; #define PG8_LDA(dst, b, h) do { _Pragma("unroll") for (int m = 0; m < 4; ++m) _Pragma("unroll") for (int k = 0; k < 2; ++k) dst[m][k] = *(const PG8_LAS bf16x8*)(lds + PG8_SA(b, h) + aoff + m * 2048 + k * 1024); } while (0)
; #define PG8_LDB(dst, b, h) do { _Pragma("unroll") for (int n = 0; n < 2; ++n) _Pragma("unroll") for (int k = 0; k < 2; ++k) dst[n][k] = *(const PG8_LAS bf16x8*)(lds + PG8_SB(b, h) + boff + n * 2048 + k * 1024); } while (0)
; #define PG8_MMA(ai, bj, At, Bt) do { __builtin_amdgcn_s_setprio(1); _Pragma("unroll") for (int m = 0; m < 4; ++m) _Pragma("unroll") for (int n = 0; n < 2; ++n) _Pragma("unroll") for (int k = 0; k < 2; ++k) \
;         acc[ai][bj][m][n] = __builtin_amdgcn_mfma_f32_16x16x32_bf16(Bt[n][k], At[m][k], acc[ai][bj][m][n], 0, 0, 0); __builtin_amdgcn_s_setprio(0); } while (0)
; #define PG8_WAIT_V(n) asm volatile("s_waitcnt vmcnt(" #n ")" ::: "memory")
; #define PG8_WAIT_L(n) asm volatile("s_waitcnt lgkmcnt(" #n ")" ::: "memory")
; #define PG8_BAR __builtin_amdgcn_s_barrier()
; #define PG8_SCHED __builtin_amdgcn_sched_barrier(0)
; template <class Epi, class Sched, bool ALIGN_EPI = true>
; __device__ __forceinline__ void gemm_phase(PG8_LAS unsigned char* lds, const Gemm g, const Sched& S, const Epi& E) {
;     ...
;             PG8_LDB(B0, 0, 0); PG8_LDB(B1, 0, 1); PG8_SCHED; PG8_LDA(At, 0, 0); PG8_STAGE(srdA, PG8_SA(1, 1), a1 + hstepA, voffA);
;             PG8_WAIT_V(8); PG8_WAIT_L(0); PG8_BAR; PG8_MMA(0, 0, At, B0); PG8_MMA(0, 1, At, B1); PG8_BAR; PG8_SCHED;
;             PG8_LDA(At, 0, 1); PG8_STAGE(srdB, PG8_SB(0, 0), b2, voffB); PG8_STAGE(srdB, PG8_SB(0, 1), b2 + hstepB, voffB); PG8_STAGE(srdA, PG8_SA(0, 0), a2, voffA);
;             PG8_WAIT_V(8); PG8_WAIT_L(0); PG8_BAR; PG8_MMA(1, 0, At, B0); PG8_MMA(1, 1, At, B1); PG8_BAR; PG8_SCHED;
.LBB0_596:
	ds_read_b128 v[104:107], v155
	ds_read_b128 v[108:111], v155 offset:1024
	ds_read_b128 v[140:143], v155 offset:2048
	ds_read_b128 v[144:147], v155 offset:3072
	ds_read_b128 v[170:173], v156
	ds_read_b128 v[174:177], v156 offset:1024
	ds_read_b128 v[178:181], v156 offset:2048
	ds_read_b128 v[182:185], v156 offset:3072
	s_add_i32 s38, s75, 0xfffc0080
	s_cmp_eq_u32 s81, 12
	s_cselect_b32 s46, s10, s38
	s_cselect_b32 s39, s11, s80
	s_or_b32 s38, s46, 0x80
	s_mov_b32 m0, s62
	ds_read_b128 v[186:189], v157
	ds_read_b128 v[190:193], v157 offset:1024
	ds_read_b128 v[194:197], v157 offset:2048
	ds_read_b128 v[198:201], v157 offset:3072
	ds_read_b128 v[202:205], v157 offset:4096
	ds_read_b128 v[206:209], v157 offset:5120
	ds_read_b128 v[210:213], v157 offset:6144
	ds_read_b128 v[214:217], v157 offset:7168
	buffer_load_dwordx4 v148, s[28:31], s75 offen lds
	s_mov_b32 m0, s63
	s_nop 0
	buffer_load_dwordx4 v150, s[28:31], s75 offen lds
	s_waitcnt vmcnt(8)
	s_waitcnt lgkmcnt(0)
	s_barrier
	s_setprio 1
	v_mfma_f32_16x16x32_bf16 v[132:135], v[104:107], v[186:189], v[132:135]
	v_mfma_f32_16x16x32_bf16 v[128:131], v[140:143], v[186:189], v[128:131]
	v_mfma_f32_16x16x32_bf16 v[124:127], v[104:107], v[194:197], v[124:127]
	v_mfma_f32_16x16x32_bf16 v[120:123], v[140:143], v[194:197], v[120:123]
	v_mfma_f32_16x16x32_bf16 v[116:119], v[104:107], v[202:205], v[116:119]
	v_mfma_f32_16x16x32_bf16 v[112:115], v[140:143], v[202:205], v[112:115]
	v_mfma_f32_16x16x32_bf16 v[100:103], v[104:107], v[210:213], v[100:103]
	v_mfma_f32_16x16x32_bf16 v[96:99], v[140:143], v[210:213], v[96:99]
	v_mfma_f32_16x16x32_bf16 v[132:135], v[108:111], v[190:193], v[132:135]
	v_mfma_f32_16x16x32_bf16 v[128:131], v[144:147], v[190:193], v[128:131]
	v_mfma_f32_16x16x32_bf16 v[124:127], v[108:111], v[198:201], v[124:127]
	v_mfma_f32_16x16x32_bf16 v[120:123], v[144:147], v[198:201], v[120:123]
	v_mfma_f32_16x16x32_bf16 v[116:119], v[108:111], v[206:209], v[116:119]
	v_mfma_f32_16x16x32_bf16 v[112:115], v[144:147], v[206:209], v[112:115]
	v_mfma_f32_16x16x32_bf16 v[100:103], v[108:111], v[214:217], v[100:103]
	v_mfma_f32_16x16x32_bf16 v[96:99], v[144:147], v[214:217], v[96:99]
	s_setprio 0
	s_setprio 1
	v_mfma_f32_16x16x32_bf16 v[60:63], v[170:173], v[186:189], v[60:63]
	v_mfma_f32_16x16x32_bf16 v[56:59], v[178:181], v[186:189], v[56:59]
	v_mfma_f32_16x16x32_bf16 v[52:55], v[170:173], v[194:197], v[52:55]
	v_mfma_f32_16x16x32_bf16 v[48:51], v[178:181], v[194:197], v[48:51]
	v_mfma_f32_16x16x32_bf16 v[44:47], v[170:173], v[202:205], v[44:47]
	v_mfma_f32_16x16x32_bf16 v[40:43], v[178:181], v[202:205], v[40:43]
	v_mfma_f32_16x16x32_bf16 v[36:39], v[170:173], v[210:213], v[36:39]
	v_mfma_f32_16x16x32_bf16 v[32:35], v[178:181], v[210:213], v[32:35]
	v_mfma_f32_16x16x32_bf16 v[60:63], v[174:177], v[190:193], v[60:63]
	v_mfma_f32_16x16x32_bf16 v[56:59], v[182:185], v[190:193], v[56:59]
	v_mfma_f32_16x16x32_bf16 v[52:55], v[174:177], v[198:201], v[52:55]
	v_mfma_f32_16x16x32_bf16 v[48:51], v[182:185], v[198:201], v[48:51]
	v_mfma_f32_16x16x32_bf16 v[44:47], v[174:177], v[206:209], v[44:47]
	v_mfma_f32_16x16x32_bf16 v[40:43], v[182:185], v[206:209], v[40:43]
	v_mfma_f32_16x16x32_bf16 v[36:39], v[174:177], v[214:217], v[36:39]
	v_mfma_f32_16x16x32_bf16 v[32:35], v[182:185], v[214:217], v[32:35]
	s_setprio 0
	s_barrier
	s_mov_b32 m0, s21
	s_mov_b32 s42, s30
	s_mov_b32 s43, s31
	ds_read_b128 v[186:189], v157 offset:16384
	ds_read_b128 v[190:193], v157 offset:17408
	ds_read_b128 v[194:197], v157 offset:18432
	ds_read_b128 v[198:201], v157 offset:19456
	ds_read_b128 v[202:205], v157 offset:20480
	ds_read_b128 v[206:209], v157 offset:21504
	ds_read_b128 v[210:213], v157 offset:22528
	ds_read_b128 v[214:217], v157 offset:23552
	buffer_load_dwordx4 v149, s[40:43], s39 offen lds
	s_mov_b32 m0, s33
	s_add_i32 s47, s39, 0x40000
	buffer_load_dwordx4 v151, s[40:43], s39 offen lds
	s_mov_b32 m0, s34
	s_nop 0
	buffer_load_dwordx4 v149, s[40:43], s47 offen lds
	s_mov_b32 m0, s35
	s_nop 0
	buffer_load_dwordx4 v151, s[40:43], s47 offen lds
	s_mov_b32 m0, s3
	s_nop 0
	buffer_load_dwordx4 v148, s[28:31], s46 offen lds
	s_mov_b32 m0, s44
	s_nop 0
	buffer_load_dwordx4 v150, s[28:31], s46 offen lds
	s_waitcnt vmcnt(8)
	s_waitcnt lgkmcnt(0)
	s_barrier
	s_setprio 1
	v_mfma_f32_16x16x32_bf16 v[92:95], v[104:107], v[186:189], v[92:95]
	v_mfma_f32_16x16x32_bf16 v[88:91], v[140:143], v[186:189], v[88:91]
	v_mfma_f32_16x16x32_bf16 v[84:87], v[104:107], v[194:197], v[84:87]
	v_mfma_f32_16x16x32_bf16 v[80:83], v[140:143], v[194:197], v[80:83]
	v_mfma_f32_16x16x32_bf16 v[76:79], v[104:107], v[202:205], v[76:79]
	v_mfma_f32_16x16x32_bf16 v[72:75], v[140:143], v[202:205], v[72:75]
	v_mfma_f32_16x16x32_bf16 v[68:71], v[104:107], v[210:213], v[68:71]
	v_mfma_f32_16x16x32_bf16 v[64:67], v[140:143], v[210:213], v[64:67]
	v_mfma_f32_16x16x32_bf16 v[92:95], v[108:111], v[190:193], v[92:95]
	v_mfma_f32_16x16x32_bf16 v[88:91], v[144:147], v[190:193], v[88:91]
	v_mfma_f32_16x16x32_bf16 v[84:87], v[108:111], v[198:201], v[84:87]
	v_mfma_f32_16x16x32_bf16 v[80:83], v[144:147], v[198:201], v[80:83]
	v_mfma_f32_16x16x32_bf16 v[76:79], v[108:111], v[206:209], v[76:79]
	v_mfma_f32_16x16x32_bf16 v[72:75], v[144:147], v[206:209], v[72:75]
	v_mfma_f32_16x16x32_bf16 v[68:71], v[108:111], v[214:217], v[68:71]
	v_mfma_f32_16x16x32_bf16 v[64:67], v[144:147], v[214:217], v[64:67]
	s_setprio 0
	s_setprio 1
	v_mfma_f32_16x16x32_bf16 v[28:31], v[170:173], v[186:189], v[28:31]
	v_mfma_f32_16x16x32_bf16 v[24:27], v[178:181], v[186:189], v[24:27]
	v_mfma_f32_16x16x32_bf16 v[20:23], v[170:173], v[194:197], v[20:23]
	v_mfma_f32_16x16x32_bf16 v[16:19], v[178:181], v[194:197], v[16:19]
	v_mfma_f32_16x16x32_bf16 v[12:15], v[170:173], v[202:205], v[12:15]
	v_mfma_f32_16x16x32_bf16 v[8:11], v[178:181], v[202:205], v[8:11]
	v_mfma_f32_16x16x32_bf16 v[4:7], v[170:173], v[210:213], v[4:7]
	v_mfma_f32_16x16x32_bf16 v[0:3], v[178:181], v[210:213], v[0:3]
	v_mfma_f32_16x16x32_bf16 v[28:31], v[174:177], v[190:193], v[28:31]
	v_mfma_f32_16x16x32_bf16 v[24:27], v[182:185], v[190:193], v[24:27]
	v_mfma_f32_16x16x32_bf16 v[20:23], v[174:177], v[198:201], v[20:23]
	v_mfma_f32_16x16x32_bf16 v[16:19], v[182:185], v[198:201], v[16:19]
	v_mfma_f32_16x16x32_bf16 v[12:15], v[174:177], v[206:209], v[12:15]
	v_mfma_f32_16x16x32_bf16 v[8:11], v[182:185], v[206:209], v[8:11]
	v_mfma_f32_16x16x32_bf16 v[4:7], v[174:177], v[214:217], v[4:7]
	v_mfma_f32_16x16x32_bf16 v[0:3], v[182:185], v[214:217], v[0:3]
	s_setprio 0
	s_barrier
; #define PG8_STAGE(srd, bufoff, goff, voff) do { _Pragma("unroll") for (int _i = 0; _i < 2; ++_i) \
;         __builtin_amdgcn_raw_ptr_buffer_load_lds(srd, (PG8_LAS unsigned*)(lds + (bufoff) + ldsw + _i * 8192), 16, (voff)[_i], (goff), 0, 0); } while (0)
; #define PG8_LDA(dst, b, h) do { _Pragma("unroll") for (int m = 0; m < 4; ++m) _Pragma("unroll") for (int k = 0; k < 2; ++k) dst[m][k] = *(const PG8_LAS bf16x8*)(lds + PG8_SA(b, h) + aoff + m * 2048 + k * 1024); } while (0)
; #define PG8_LDB(dst, b, h) do { _Pragma("unroll") for (int n = 0; n < 2; ++n) _Pragma("unroll") for (int k = 0; k < 2; ++k) dst[n][k] = *(const PG8_LAS bf16x8*)(lds + PG8_SB(b, h) + boff + n * 2048 + k * 1024); } while (0)
; #define PG8_MMA(ai, bj, At, Bt) do { __builtin_amdgcn_s_setprio(1); _Pragma("unroll") for (int m = 0; m < 4; ++m) _Pragma("unroll") for (int n = 0; n < 2; ++n) _Pragma("unroll") for (int k = 0; k < 2; ++k) \
;         acc[ai][bj][m][n] = __builtin_amdgcn_mfma_f32_16x16x32_bf16(Bt[n][k], At[m][k], acc[ai][bj][m][n], 0, 0, 0); __builtin_amdgcn_s_setprio(0); } while (0)
; #define PG8_WAIT_V(n) asm volatile("s_waitcnt vmcnt(" #n ")" ::: "memory")
; #define PG8_WAIT_L(n) asm volatile("s_waitcnt lgkmcnt(" #n ")" ::: "memory")
; #define PG8_BAR __builtin_amdgcn_s_barrier()
; #define PG8_SCHED __builtin_amdgcn_sched_barrier(0)
; template <class Epi, class Sched, bool ALIGN_EPI = true>
; __device__ __forceinline__ void gemm_phase(PG8_LAS unsigned char* lds, const Gemm g, const Sched& S, const Epi& E) {
;     ...
;             PG8_LDB(B0, 1, 0); PG8_LDB(B1, 1, 1); PG8_SCHED; PG8_LDA(At, 1, 0); PG8_STAGE(srdA, PG8_SA(0, 1), a2 + hstepA, voffA);
;             PG8_WAIT_V(8); PG8_WAIT_L(0); PG8_BAR; PG8_MMA(0, 0, At, B0); PG8_MMA(0, 1, At, B1); PG8_BAR; PG8_SCHED;
;             PG8_LDA(At, 1, 1); PG8_STAGE(srdB, PG8_SB(1, 0), b3, voffB); PG8_STAGE(srdB, PG8_SB(1, 1), b3 + hstepB, voffB); PG8_STAGE(srdA, PG8_SA(1, 0), a3, voffA);
;             PG8_WAIT_V(8); PG8_WAIT_L(0); PG8_BAR; PG8_MMA(1, 0, At, B0); PG8_MMA(1, 1, At, B1); PG8_BAR; PG8_SCHED;
;         }
	ds_read_b128 v[104:107], v158
	ds_read_b128 v[108:111], v158 offset:1024
	ds_read_b128 v[140:143], v158 offset:2048
	ds_read_b128 v[144:147], v158 offset:3072
	ds_read_b128 v[170:173], v159
	ds_read_b128 v[174:177], v159 offset:1024
	ds_read_b128 v[178:181], v159 offset:2048
	ds_read_b128 v[182:185], v159 offset:3072
	s_add_i32 s46, s46, 0x40000
	s_mov_b32 m0, s45
	ds_read_b128 v[186:189], v157 offset:32768
	ds_read_b128 v[190:193], v157 offset:33792
	ds_read_b128 v[194:197], v157 offset:34816
	ds_read_b128 v[198:201], v157 offset:35840
	ds_read_b128 v[202:205], v157 offset:36864
	ds_read_b128 v[206:209], v157 offset:37888
	ds_read_b128 v[210:213], v157 offset:38912
	ds_read_b128 v[214:217], v157 offset:39936
	buffer_load_dwordx4 v148, s[28:31], s46 offen lds
	s_mov_b32 m0, s52
	s_nop 0
	buffer_load_dwordx4 v150, s[28:31], s46 offen lds
	s_waitcnt vmcnt(8)
	s_waitcnt lgkmcnt(0)
	s_barrier
	s_setprio 1
	v_mfma_f32_16x16x32_bf16 v[132:135], v[104:107], v[186:189], v[132:135]
	v_mfma_f32_16x16x32_bf16 v[128:131], v[140:143], v[186:189], v[128:131]
	v_mfma_f32_16x16x32_bf16 v[124:127], v[104:107], v[194:197], v[124:127]
	v_mfma_f32_16x16x32_bf16 v[120:123], v[140:143], v[194:197], v[120:123]
	v_mfma_f32_16x16x32_bf16 v[116:119], v[104:107], v[202:205], v[116:119]
	v_mfma_f32_16x16x32_bf16 v[112:115], v[140:143], v[202:205], v[112:115]
	v_mfma_f32_16x16x32_bf16 v[100:103], v[104:107], v[210:213], v[100:103]
	v_mfma_f32_16x16x32_bf16 v[96:99], v[140:143], v[210:213], v[96:99]
	v_mfma_f32_16x16x32_bf16 v[132:135], v[108:111], v[190:193], v[132:135]
	v_mfma_f32_16x16x32_bf16 v[128:131], v[144:147], v[190:193], v[128:131]
	v_mfma_f32_16x16x32_bf16 v[124:127], v[108:111], v[198:201], v[124:127]
	v_mfma_f32_16x16x32_bf16 v[120:123], v[144:147], v[198:201], v[120:123]
	v_mfma_f32_16x16x32_bf16 v[116:119], v[108:111], v[206:209], v[116:119]
	v_mfma_f32_16x16x32_bf16 v[112:115], v[144:147], v[206:209], v[112:115]
	v_mfma_f32_16x16x32_bf16 v[100:103], v[108:111], v[214:217], v[100:103]
	v_mfma_f32_16x16x32_bf16 v[96:99], v[144:147], v[214:217], v[96:99]
	s_setprio 0
	s_setprio 1
	v_mfma_f32_16x16x32_bf16 v[60:63], v[170:173], v[186:189], v[60:63]
	v_mfma_f32_16x16x32_bf16 v[56:59], v[178:181], v[186:189], v[56:59]
	v_mfma_f32_16x16x32_bf16 v[52:55], v[170:173], v[194:197], v[52:55]
	v_mfma_f32_16x16x32_bf16 v[48:51], v[178:181], v[194:197], v[48:51]
	v_mfma_f32_16x16x32_bf16 v[44:47], v[170:173], v[202:205], v[44:47]
	v_mfma_f32_16x16x32_bf16 v[40:43], v[178:181], v[202:205], v[40:43]
	v_mfma_f32_16x16x32_bf16 v[36:39], v[170:173], v[210:213], v[36:39]
	v_mfma_f32_16x16x32_bf16 v[32:35], v[178:181], v[210:213], v[32:35]
	v_mfma_f32_16x16x32_bf16 v[60:63], v[174:177], v[190:193], v[60:63]
	v_mfma_f32_16x16x32_bf16 v[56:59], v[182:185], v[190:193], v[56:59]
	v_mfma_f32_16x16x32_bf16 v[52:55], v[174:177], v[198:201], v[52:55]
	v_mfma_f32_16x16x32_bf16 v[48:51], v[182:185], v[198:201], v[48:51]
	v_mfma_f32_16x16x32_bf16 v[44:47], v[174:177], v[206:209], v[44:47]
	v_mfma_f32_16x16x32_bf16 v[40:43], v[182:185], v[206:209], v[40:43]
	v_mfma_f32_16x16x32_bf16 v[36:39], v[174:177], v[214:217], v[36:39]
	v_mfma_f32_16x16x32_bf16 v[32:35], v[182:185], v[214:217], v[32:35]
	s_setprio 0
	s_barrier
	s_mov_b32 m0, s54
	s_or_b32 s46, s39, 0x80
	ds_read_b128 v[186:189], v157 offset:49152
	ds_read_b128 v[190:193], v157 offset:50176
	ds_read_b128 v[194:197], v157 offset:51200
	ds_read_b128 v[198:201], v157 offset:52224
	ds_read_b128 v[202:205], v157 offset:53248
	ds_read_b128 v[206:209], v157 offset:54272
	ds_read_b128 v[210:213], v157 offset:55296
	ds_read_b128 v[214:217], v157 offset:56320
	buffer_load_dwordx4 v149, s[40:43], s46 offen lds
	s_mov_b32 m0, s55
	s_add_i32 s39, s39, 0x40080
	buffer_load_dwordx4 v151, s[40:43], s46 offen lds
	s_mov_b32 m0, s60
	s_nop 0
	buffer_load_dwordx4 v149, s[40:43], s39 offen lds
	s_mov_b32 m0, s61
	s_nop 0
	buffer_load_dwordx4 v151, s[40:43], s39 offen lds
	s_mov_b32 m0, s56
	s_nop 0
	buffer_load_dwordx4 v148, s[28:31], s38 offen lds
	s_mov_b32 m0, s57
	s_nop 0
	buffer_load_dwordx4 v150, s[28:31], s38 offen lds
	s_waitcnt vmcnt(8)
	s_waitcnt lgkmcnt(0)
	s_barrier
	s_setprio 1
	v_mfma_f32_16x16x32_bf16 v[92:95], v[104:107], v[186:189], v[92:95]
	v_mfma_f32_16x16x32_bf16 v[88:91], v[140:143], v[186:189], v[88:91]
	v_mfma_f32_16x16x32_bf16 v[84:87], v[104:107], v[194:197], v[84:87]
	v_mfma_f32_16x16x32_bf16 v[80:83], v[140:143], v[194:197], v[80:83]
	v_mfma_f32_16x16x32_bf16 v[76:79], v[104:107], v[202:205], v[76:79]
	v_mfma_f32_16x16x32_bf16 v[72:75], v[140:143], v[202:205], v[72:75]
	v_mfma_f32_16x16x32_bf16 v[68:71], v[104:107], v[210:213], v[68:71]
	v_mfma_f32_16x16x32_bf16 v[64:67], v[140:143], v[210:213], v[64:67]
	v_mfma_f32_16x16x32_bf16 v[92:95], v[108:111], v[190:193], v[92:95]
	v_mfma_f32_16x16x32_bf16 v[88:91], v[144:147], v[190:193], v[88:91]
	v_mfma_f32_16x16x32_bf16 v[84:87], v[108:111], v[198:201], v[84:87]
	v_mfma_f32_16x16x32_bf16 v[80:83], v[144:147], v[198:201], v[80:83]
	v_mfma_f32_16x16x32_bf16 v[76:79], v[108:111], v[206:209], v[76:79]
	v_mfma_f32_16x16x32_bf16 v[72:75], v[144:147], v[206:209], v[72:75]
	v_mfma_f32_16x16x32_bf16 v[68:71], v[108:111], v[214:217], v[68:71]
	v_mfma_f32_16x16x32_bf16 v[64:67], v[144:147], v[214:217], v[64:67]
	s_setprio 0
	s_setprio 1
	v_mfma_f32_16x16x32_bf16 v[28:31], v[170:173], v[186:189], v[28:31]
	v_mfma_f32_16x16x32_bf16 v[24:27], v[178:181], v[186:189], v[24:27]
	v_mfma_f32_16x16x32_bf16 v[20:23], v[170:173], v[194:197], v[20:23]
	v_mfma_f32_16x16x32_bf16 v[16:19], v[178:181], v[194:197], v[16:19]
	v_mfma_f32_16x16x32_bf16 v[12:15], v[170:173], v[202:205], v[12:15]
	v_mfma_f32_16x16x32_bf16 v[8:11], v[178:181], v[202:205], v[8:11]
	v_mfma_f32_16x16x32_bf16 v[4:7], v[170:173], v[210:213], v[4:7]
	v_mfma_f32_16x16x32_bf16 v[0:3], v[178:181], v[210:213], v[0:3]
	v_mfma_f32_16x16x32_bf16 v[28:31], v[174:177], v[190:193], v[28:31]
	v_mfma_f32_16x16x32_bf16 v[24:27], v[182:185], v[190:193], v[24:27]
	v_mfma_f32_16x16x32_bf16 v[20:23], v[174:177], v[198:201], v[20:23]
	v_mfma_f32_16x16x32_bf16 v[16:19], v[182:185], v[198:201], v[16:19]
	v_mfma_f32_16x16x32_bf16 v[12:15], v[174:177], v[206:209], v[12:15]
	v_mfma_f32_16x16x32_bf16 v[8:11], v[182:185], v[206:209], v[8:11]
	v_mfma_f32_16x16x32_bf16 v[4:7], v[174:177], v[214:217], v[4:7]
	v_mfma_f32_16x16x32_bf16 v[0:3], v[182:185], v[214:217], v[0:3]
	s_setprio 0
	s_barrier
	s_add_i32 s81, s81, 2
	s_addk_i32 s75, 0x100
	s_addk_i32 s80, 0x100
	s_cmp_gt_u32 s81, 13
	s_cbranch_scc0 .LBB0_596
	s_mov_b64 s[94:95], s[78:79]
	s_mov_b64 s[92:93], s[76:77]
	s_and_b64 vcc, exec, s[36:37]
	s_cbranch_vccz .LBB0_599
	s_barrier

; #define PG8_STAGE(srd, bufoff, goff, voff) do { _Pragma("unroll") for (int _i = 0; _i < 2; ++_i) \
;         __builtin_amdgcn_raw_ptr_buffer_load_lds(srd, (PG8_LAS unsigned*)(lds + (bufoff) + ldsw + _i * 8192), 16, (voff)[_i], (goff), 0, 0); } while (0)
; #define PG8_LDA(dst, b, h) do { _Pragma("unroll") for (int m = 0; m < 4; ++m) _Pragma("unroll") for (int k = 0; k < 2; ++k) dst[m][k] = *(const PG8_LAS bf16x8*)(lds + PG8_SA(b, h) + aoff + m * 2048 + k * 1024); } while (0)
; #define PG8_LDB(dst, b, h) do { _Pragma("unroll") for (int n = 0; n < 2; ++n) _Pragma("unroll") for (int k = 0; k < 2; ++k) dst[n][k] = *(const PG8_LAS bf16x8*)(lds + PG8_SB(b, h) + boff + n * 2048 + k * 1024); } while (0)
; #define PG8_MMA(ai, bj, At, Bt) do { __builtin_amdgcn_s_setprio(1); _Pragma("unroll") for (int m = 0; m < 4; ++m) _Pragma("unroll") for (int n = 0; n < 2; ++n) _Pragma("unroll") for (int k = 0; k < 2; ++k) \
;         acc[ai][bj][m][n] = __builtin_amdgcn_mfma_f32_16x16x32_bf16(Bt[n][k], At[m][k], acc[ai][bj][m][n], 0, 0, 0); __builtin_amdgcn_s_setprio(0); } while (0)
; #define PG8_WAIT_V(n) asm volatile("s_waitcnt vmcnt(" #n ")" ::: "memory")
; #define PG8_WAIT_L(n) asm volatile("s_waitcnt lgkmcnt(" #n ")" ::: "memory")
; #define PG8_BAR __builtin_amdgcn_s_barrier()
; #define PG8_SCHED __builtin_amdgcn_sched_barrier(0)
; template <class Epi, class Sched, bool ALIGN_EPI = true>
; __device__ __forceinline__ void gemm_phase(PG8_LAS unsigned char* lds, const Gemm g, const Sched& S, const Epi& E) {
;     ...
;             PG8_LDB(B0, 0, 0); PG8_LDB(B1, 0, 1); PG8_SCHED; PG8_LDA(At, 0, 0); PG8_STAGE(srdA, PG8_SA(1, 1), a1 + hstepA, voffA);
;             PG8_WAIT_V(8); PG8_WAIT_L(0); PG8_BAR; PG8_MMA(0, 0, At, B0); PG8_MMA(0, 1, At, B1); PG8_BAR; PG8_SCHED;
;             PG8_LDA(At, 0, 1); PG8_STAGE(srdB, PG8_SB(0, 0), b2, voffB); PG8_STAGE(srdB, PG8_SB(0, 1), b2 + hstepB, voffB); PG8_STAGE(srdA, PG8_SA(0, 0), a2, voffA);
;             PG8_WAIT_V(8); PG8_WAIT_L(0); PG8_BAR; PG8_MMA(1, 0, At, B0); PG8_MMA(1, 1, At, B1); PG8_BAR; PG8_SCHED;
.LBB0_769:
	v_add_u32_e32 v1, 0x10000, v153
	ds_read_b128 v[156:159], v1
	ds_read_b128 v[172:175], v1 offset:1024
	ds_read_b128 v[176:179], v1 offset:2048
	ds_read_b128 v[180:183], v1 offset:3072
	v_add_u32_e32 v1, 0x14000, v153
	ds_read_b128 v[184:187], v1
	ds_read_b128 v[188:191], v1 offset:1024
	ds_read_b128 v[192:195], v1 offset:2048
	ds_read_b128 v[196:199], v1 offset:3072
	s_add_i32 s60, s54, s59
	s_add_i32 s46, s60, 0x100
	s_add_i32 s47, s57, s59
	s_cmpk_eq_i32 s59, 0xf00
	s_cselect_b32 s61, s55, s46
	s_cselect_b32 s47, s56, s47
	s_or_b32 s46, s61, 0x80
	s_add_i32 s60, s60, 0x80080
	s_mov_b32 m0, s45
	ds_read_b128 v[200:203], v154
	ds_read_b128 v[204:207], v154 offset:1024
	ds_read_b128 v[208:211], v154 offset:2048
	ds_read_b128 v[212:215], v154 offset:3072
	ds_read_b128 v[216:219], v154 offset:4096
	ds_read_b128 v[220:223], v154 offset:5120
	ds_read_b128 v[224:227], v154 offset:6144
	ds_read_b128 v[228:231], v154 offset:7168
	buffer_load_dwordx4 v146, s[24:27], s60 offen lds
	s_mov_b32 m0, s48
	s_nop 0
	buffer_load_dwordx4 v148, s[24:27], s60 offen lds
	s_waitcnt vmcnt(8)
	s_waitcnt lgkmcnt(0)
	s_barrier
	s_setprio 1
	v_mfma_f32_16x16x32_bf16 v[128:131], v[156:159], v[200:203], v[128:131]
	v_mfma_f32_16x16x32_bf16 v[124:127], v[176:179], v[200:203], v[124:127]
	v_mfma_f32_16x16x32_bf16 v[112:115], v[156:159], v[208:211], v[112:115]
	v_mfma_f32_16x16x32_bf16 v[108:111], v[176:179], v[208:211], v[108:111]
	v_mfma_f32_16x16x32_bf16 v[96:99], v[156:159], v[216:219], v[96:99]
	v_mfma_f32_16x16x32_bf16 v[92:95], v[176:179], v[216:219], v[92:95]
	v_mfma_f32_16x16x32_bf16 v[80:83], v[156:159], v[224:227], v[80:83]
	v_mfma_f32_16x16x32_bf16 v[76:79], v[176:179], v[224:227], v[76:79]
	v_mfma_f32_16x16x32_bf16 v[128:131], v[172:175], v[204:207], v[128:131]
	v_mfma_f32_16x16x32_bf16 v[124:127], v[180:183], v[204:207], v[124:127]
	v_mfma_f32_16x16x32_bf16 v[112:115], v[172:175], v[212:215], v[112:115]
	v_mfma_f32_16x16x32_bf16 v[108:111], v[180:183], v[212:215], v[108:111]
	v_mfma_f32_16x16x32_bf16 v[96:99], v[172:175], v[220:223], v[96:99]
	v_mfma_f32_16x16x32_bf16 v[92:95], v[180:183], v[220:223], v[92:95]
	v_mfma_f32_16x16x32_bf16 v[80:83], v[172:175], v[228:231], v[80:83]
	v_mfma_f32_16x16x32_bf16 v[76:79], v[180:183], v[228:231], v[76:79]
	s_setprio 0
	s_setprio 1
	v_mfma_f32_16x16x32_bf16 v[120:123], v[184:187], v[200:203], v[120:123]
	v_mfma_f32_16x16x32_bf16 v[116:119], v[192:195], v[200:203], v[116:119]
	v_mfma_f32_16x16x32_bf16 v[104:107], v[184:187], v[208:211], v[104:107]
	v_mfma_f32_16x16x32_bf16 v[100:103], v[192:195], v[208:211], v[100:103]
	v_mfma_f32_16x16x32_bf16 v[88:91], v[184:187], v[216:219], v[88:91]
	v_mfma_f32_16x16x32_bf16 v[84:87], v[192:195], v[216:219], v[84:87]
	v_mfma_f32_16x16x32_bf16 v[72:75], v[184:187], v[224:227], v[72:75]
	v_mfma_f32_16x16x32_bf16 v[68:71], v[192:195], v[224:227], v[68:71]
	v_mfma_f32_16x16x32_bf16 v[120:123], v[188:191], v[204:207], v[120:123]
	v_mfma_f32_16x16x32_bf16 v[116:119], v[196:199], v[204:207], v[116:119]
	v_mfma_f32_16x16x32_bf16 v[104:107], v[188:191], v[212:215], v[104:107]
	v_mfma_f32_16x16x32_bf16 v[100:103], v[196:199], v[212:215], v[100:103]
	v_mfma_f32_16x16x32_bf16 v[88:91], v[188:191], v[220:223], v[88:91]
	v_mfma_f32_16x16x32_bf16 v[84:87], v[196:199], v[220:223], v[84:87]
	v_mfma_f32_16x16x32_bf16 v[72:75], v[188:191], v[228:231], v[72:75]
	v_mfma_f32_16x16x32_bf16 v[68:71], v[196:199], v[228:231], v[68:71]
	s_setprio 0
	s_barrier
	s_mov_b32 m0, s30
	ds_read_b128 v[200:203], v154 offset:16384
	ds_read_b128 v[204:207], v154 offset:17408
	ds_read_b128 v[208:211], v154 offset:18432
	ds_read_b128 v[212:215], v154 offset:19456
	ds_read_b128 v[216:219], v154 offset:20480
	ds_read_b128 v[220:223], v154 offset:21504
	ds_read_b128 v[224:227], v154 offset:22528
	ds_read_b128 v[228:231], v154 offset:23552
	buffer_load_dwordx4 v147, s[4:7], s47 offen lds
	s_mov_b32 m0, s31
	s_add_i32 s60, s47, 0x80000
	buffer_load_dwordx4 v149, s[4:7], s47 offen lds
	s_mov_b32 m0, s33
	s_nop 0
	buffer_load_dwordx4 v147, s[4:7], s60 offen lds
	s_mov_b32 m0, s34
	s_nop 0
	buffer_load_dwordx4 v149, s[4:7], s60 offen lds
	s_mov_b32 m0, s29
	s_nop 0
	buffer_load_dwordx4 v146, s[24:27], s61 offen lds
	s_mov_b32 m0, s35
	s_nop 0
	buffer_load_dwordx4 v148, s[24:27], s61 offen lds
	s_waitcnt vmcnt(8)
	s_waitcnt lgkmcnt(0)
	s_barrier
	s_setprio 1
	v_mfma_f32_16x16x32_bf16 v[64:67], v[156:159], v[200:203], v[64:67]
	v_mfma_f32_16x16x32_bf16 v[60:63], v[176:179], v[200:203], v[60:63]
	v_mfma_f32_16x16x32_bf16 v[48:51], v[156:159], v[208:211], v[48:51]
	v_mfma_f32_16x16x32_bf16 v[44:47], v[176:179], v[208:211], v[44:47]
	v_mfma_f32_16x16x32_bf16 v[32:35], v[156:159], v[216:219], v[32:35]
	v_mfma_f32_16x16x32_bf16 v[28:31], v[176:179], v[216:219], v[28:31]
	v_mfma_f32_16x16x32_bf16 v[16:19], v[156:159], v[224:227], v[16:19]
	v_mfma_f32_16x16x32_bf16 v[12:15], v[176:179], v[224:227], v[12:15]
	v_mfma_f32_16x16x32_bf16 v[64:67], v[172:175], v[204:207], v[64:67]
	v_mfma_f32_16x16x32_bf16 v[60:63], v[180:183], v[204:207], v[60:63]
	v_mfma_f32_16x16x32_bf16 v[48:51], v[172:175], v[212:215], v[48:51]
	v_mfma_f32_16x16x32_bf16 v[44:47], v[180:183], v[212:215], v[44:47]
	v_mfma_f32_16x16x32_bf16 v[32:35], v[172:175], v[220:223], v[32:35]
	v_mfma_f32_16x16x32_bf16 v[28:31], v[180:183], v[220:223], v[28:31]
	v_mfma_f32_16x16x32_bf16 v[16:19], v[172:175], v[228:231], v[16:19]
	v_mfma_f32_16x16x32_bf16 v[12:15], v[180:183], v[228:231], v[12:15]
	s_setprio 0
	s_setprio 1
	v_mfma_f32_16x16x32_bf16 v[56:59], v[184:187], v[200:203], v[56:59]
	v_mfma_f32_16x16x32_bf16 v[52:55], v[192:195], v[200:203], v[52:55]
	v_mfma_f32_16x16x32_bf16 v[40:43], v[184:187], v[208:211], v[40:43]
	v_mfma_f32_16x16x32_bf16 v[36:39], v[192:195], v[208:211], v[36:39]
	v_mfma_f32_16x16x32_bf16 v[24:27], v[184:187], v[216:219], v[24:27]
	v_mfma_f32_16x16x32_bf16 v[20:23], v[192:195], v[216:219], v[20:23]
	v_mfma_f32_16x16x32_bf16 v[8:11], v[184:187], v[224:227], v[8:11]
	v_mfma_f32_16x16x32_bf16 v[2:5], v[192:195], v[224:227], v[4:7]
	v_mfma_f32_16x16x32_bf16 v[56:59], v[188:191], v[204:207], v[56:59]
	v_mfma_f32_16x16x32_bf16 v[52:55], v[196:199], v[204:207], v[52:55]
	v_mfma_f32_16x16x32_bf16 v[40:43], v[188:191], v[212:215], v[40:43]
	v_mfma_f32_16x16x32_bf16 v[36:39], v[196:199], v[212:215], v[36:39]
	v_mfma_f32_16x16x32_bf16 v[24:27], v[188:191], v[220:223], v[24:27]
	v_mfma_f32_16x16x32_bf16 v[20:23], v[196:199], v[220:223], v[20:23]
	v_mfma_f32_16x16x32_bf16 v[8:11], v[188:191], v[228:231], v[8:11]
	v_mfma_f32_16x16x32_bf16 v[2:5], v[196:199], v[228:231], v[2:5]
	s_setprio 0
	s_barrier
; #define PG8_STAGE(srd, bufoff, goff, voff) do { _Pragma("unroll") for (int _i = 0; _i < 2; ++_i) \
;         __builtin_amdgcn_raw_ptr_buffer_load_lds(srd, (PG8_LAS unsigned*)(lds + (bufoff) + ldsw + _i * 8192), 16, (voff)[_i], (goff), 0, 0); } while (0)
; #define PG8_LDA(dst, b, h) do { _Pragma("unroll") for (int m = 0; m < 4; ++m) _Pragma("unroll") for (int k = 0; k < 2; ++k) dst[m][k] = *(const PG8_LAS bf16x8*)(lds + PG8_SA(b, h) + aoff + m * 2048 + k * 1024); } while (0)
; #define PG8_LDB(dst, b, h) do { _Pragma("unroll") for (int n = 0; n < 2; ++n) _Pragma("unroll") for (int k = 0; k < 2; ++k) dst[n][k] = *(const PG8_LAS bf16x8*)(lds + PG8_SB(b, h) + boff + n * 2048 + k * 1024); } while (0)
; #define PG8_MMA(ai, bj, At, Bt) do { __builtin_amdgcn_s_setprio(1); _Pragma("unroll") for (int m = 0; m < 4; ++m) _Pragma("unroll") for (int n = 0; n < 2; ++n) _Pragma("unroll") for (int k = 0; k < 2; ++k) \
;         acc[ai][bj][m][n] = __builtin_amdgcn_mfma_f32_16x16x32_bf16(Bt[n][k], At[m][k], acc[ai][bj][m][n], 0, 0, 0); __builtin_amdgcn_s_setprio(0); } while (0)
; #define PG8_WAIT_V(n) asm volatile("s_waitcnt vmcnt(" #n ")" ::: "memory")
; #define PG8_WAIT_L(n) asm volatile("s_waitcnt lgkmcnt(" #n ")" ::: "memory")
; #define PG8_BAR __builtin_amdgcn_s_barrier()
; #define PG8_SCHED __builtin_amdgcn_sched_barrier(0)
; template <class Epi, class Sched, bool ALIGN_EPI = true>
; __device__ __forceinline__ void gemm_phase(PG8_LAS unsigned char* lds, const Gemm g, const Sched& S, const Epi& E) {
;     ...
;             PG8_LDB(B0, 1, 0); PG8_LDB(B1, 1, 1); PG8_SCHED; PG8_LDA(At, 1, 0); PG8_STAGE(srdA, PG8_SA(0, 1), a2 + hstepA, voffA);
;             PG8_WAIT_V(8); PG8_WAIT_L(0); PG8_BAR; PG8_MMA(0, 0, At, B0); PG8_MMA(0, 1, At, B1); PG8_BAR; PG8_SCHED;
;             PG8_LDA(At, 1, 1); PG8_STAGE(srdB, PG8_SB(1, 0), b3, voffB); PG8_STAGE(srdB, PG8_SB(1, 1), b3 + hstepB, voffB); PG8_STAGE(srdA, PG8_SA(1, 0), a3, voffA);
;             PG8_WAIT_V(8); PG8_WAIT_L(0); PG8_BAR; PG8_MMA(1, 0, At, B0); PG8_MMA(1, 1, At, B1); PG8_BAR; PG8_SCHED;
;         }
	v_add_u32_e32 v1, 0x18000, v153
	ds_read_b128 v[156:159], v1
	ds_read_b128 v[172:175], v1 offset:1024
	ds_read_b128 v[176:179], v1 offset:2048
	ds_read_b128 v[180:183], v1 offset:3072
	v_add_u32_e32 v1, 0x1c000, v153
	ds_read_b128 v[184:187], v1
	ds_read_b128 v[188:191], v1 offset:1024
	ds_read_b128 v[192:195], v1 offset:2048
	ds_read_b128 v[196:199], v1 offset:3072
	s_add_i32 s61, s61, 0x80000
	s_mov_b32 m0, s36
	ds_read_b128 v[200:203], v154 offset:32768
	ds_read_b128 v[204:207], v154 offset:33792
	ds_read_b128 v[208:211], v154 offset:34816
	ds_read_b128 v[212:215], v154 offset:35840
	ds_read_b128 v[216:219], v154 offset:36864
	ds_read_b128 v[220:223], v154 offset:37888
	ds_read_b128 v[224:227], v154 offset:38912
	ds_read_b128 v[228:231], v154 offset:39936
	buffer_load_dwordx4 v146, s[24:27], s61 offen lds
	s_mov_b32 m0, s37
	s_nop 0
	buffer_load_dwordx4 v148, s[24:27], s61 offen lds
	s_waitcnt vmcnt(8)
	s_waitcnt lgkmcnt(0)
	s_barrier
	s_setprio 1
	v_mfma_f32_16x16x32_bf16 v[128:131], v[156:159], v[200:203], v[128:131]
	v_mfma_f32_16x16x32_bf16 v[124:127], v[176:179], v[200:203], v[124:127]
	v_mfma_f32_16x16x32_bf16 v[112:115], v[156:159], v[208:211], v[112:115]
	v_mfma_f32_16x16x32_bf16 v[108:111], v[176:179], v[208:211], v[108:111]
	v_mfma_f32_16x16x32_bf16 v[96:99], v[156:159], v[216:219], v[96:99]
	v_mfma_f32_16x16x32_bf16 v[92:95], v[176:179], v[216:219], v[92:95]
	v_mfma_f32_16x16x32_bf16 v[80:83], v[156:159], v[224:227], v[80:83]
	v_mfma_f32_16x16x32_bf16 v[76:79], v[176:179], v[224:227], v[76:79]
	v_mfma_f32_16x16x32_bf16 v[128:131], v[172:175], v[204:207], v[128:131]
	v_mfma_f32_16x16x32_bf16 v[124:127], v[180:183], v[204:207], v[124:127]
	v_mfma_f32_16x16x32_bf16 v[112:115], v[172:175], v[212:215], v[112:115]
	v_mfma_f32_16x16x32_bf16 v[108:111], v[180:183], v[212:215], v[108:111]
	v_mfma_f32_16x16x32_bf16 v[96:99], v[172:175], v[220:223], v[96:99]
	v_mfma_f32_16x16x32_bf16 v[92:95], v[180:183], v[220:223], v[92:95]
	v_mfma_f32_16x16x32_bf16 v[80:83], v[172:175], v[228:231], v[80:83]
	v_mfma_f32_16x16x32_bf16 v[76:79], v[180:183], v[228:231], v[76:79]
	s_setprio 0
	s_setprio 1
	v_mfma_f32_16x16x32_bf16 v[120:123], v[184:187], v[200:203], v[120:123]
	v_mfma_f32_16x16x32_bf16 v[116:119], v[192:195], v[200:203], v[116:119]
	v_mfma_f32_16x16x32_bf16 v[104:107], v[184:187], v[208:211], v[104:107]
	v_mfma_f32_16x16x32_bf16 v[100:103], v[192:195], v[208:211], v[100:103]
	v_mfma_f32_16x16x32_bf16 v[88:91], v[184:187], v[216:219], v[88:91]
	v_mfma_f32_16x16x32_bf16 v[84:87], v[192:195], v[216:219], v[84:87]
	v_mfma_f32_16x16x32_bf16 v[72:75], v[184:187], v[224:227], v[72:75]
	v_mfma_f32_16x16x32_bf16 v[68:71], v[192:195], v[224:227], v[68:71]
	v_mfma_f32_16x16x32_bf16 v[120:123], v[188:191], v[204:207], v[120:123]
	v_mfma_f32_16x16x32_bf16 v[116:119], v[196:199], v[204:207], v[116:119]
	v_mfma_f32_16x16x32_bf16 v[104:107], v[188:191], v[212:215], v[104:107]
	v_mfma_f32_16x16x32_bf16 v[100:103], v[196:199], v[212:215], v[100:103]
	v_mfma_f32_16x16x32_bf16 v[88:91], v[188:191], v[220:223], v[88:91]
	v_mfma_f32_16x16x32_bf16 v[84:87], v[196:199], v[220:223], v[84:87]
	v_mfma_f32_16x16x32_bf16 v[72:75], v[188:191], v[228:231], v[72:75]
	v_mfma_f32_16x16x32_bf16 v[68:71], v[196:199], v[228:231], v[68:71]
	s_setprio 0
	s_barrier
	s_mov_b32 m0, s39
	s_or_b32 s60, s47, 0x80
	ds_read_b128 v[200:203], v154 offset:49152
	ds_read_b128 v[204:207], v154 offset:50176
	ds_read_b128 v[208:211], v154 offset:51200
	ds_read_b128 v[212:215], v154 offset:52224
	ds_read_b128 v[216:219], v154 offset:53248
	ds_read_b128 v[220:223], v154 offset:54272
	ds_read_b128 v[224:227], v154 offset:55296
	ds_read_b128 v[228:231], v154 offset:56320
	buffer_load_dwordx4 v147, s[4:7], s60 offen lds
	s_mov_b32 m0, s40
	s_add_i32 s47, s47, 0x80080
	buffer_load_dwordx4 v149, s[4:7], s60 offen lds
	s_mov_b32 m0, s43
	s_nop 0
	buffer_load_dwordx4 v147, s[4:7], s47 offen lds
	s_mov_b32 m0, s44
	s_nop 0
	buffer_load_dwordx4 v149, s[4:7], s47 offen lds
	s_mov_b32 m0, s41
	s_nop 0
	buffer_load_dwordx4 v146, s[24:27], s46 offen lds
	s_mov_b32 m0, s42
	s_nop 0
	buffer_load_dwordx4 v148, s[24:27], s46 offen lds
	s_waitcnt vmcnt(8)
	s_waitcnt lgkmcnt(0)
	s_barrier
	s_setprio 1
	v_mfma_f32_16x16x32_bf16 v[64:67], v[156:159], v[200:203], v[64:67]
	v_mfma_f32_16x16x32_bf16 v[60:63], v[176:179], v[200:203], v[60:63]
	v_mfma_f32_16x16x32_bf16 v[48:51], v[156:159], v[208:211], v[48:51]
	v_mfma_f32_16x16x32_bf16 v[44:47], v[176:179], v[208:211], v[44:47]
	v_mfma_f32_16x16x32_bf16 v[32:35], v[156:159], v[216:219], v[32:35]
	v_mfma_f32_16x16x32_bf16 v[28:31], v[176:179], v[216:219], v[28:31]
	v_mfma_f32_16x16x32_bf16 v[16:19], v[156:159], v[224:227], v[16:19]
	v_mfma_f32_16x16x32_bf16 v[12:15], v[176:179], v[224:227], v[12:15]
	v_mfma_f32_16x16x32_bf16 v[64:67], v[172:175], v[204:207], v[64:67]
	v_mfma_f32_16x16x32_bf16 v[60:63], v[180:183], v[204:207], v[60:63]
	v_mfma_f32_16x16x32_bf16 v[48:51], v[172:175], v[212:215], v[48:51]
	v_mfma_f32_16x16x32_bf16 v[44:47], v[180:183], v[212:215], v[44:47]
	v_mfma_f32_16x16x32_bf16 v[32:35], v[172:175], v[220:223], v[32:35]
	v_mfma_f32_16x16x32_bf16 v[28:31], v[180:183], v[220:223], v[28:31]
	v_mfma_f32_16x16x32_bf16 v[16:19], v[172:175], v[228:231], v[16:19]
	v_mfma_f32_16x16x32_bf16 v[12:15], v[180:183], v[228:231], v[12:15]
	s_setprio 0
	s_setprio 1
	v_mfma_f32_16x16x32_bf16 v[56:59], v[184:187], v[200:203], v[56:59]
	v_mfma_f32_16x16x32_bf16 v[52:55], v[192:195], v[200:203], v[52:55]
	v_mfma_f32_16x16x32_bf16 v[40:43], v[184:187], v[208:211], v[40:43]
	v_mfma_f32_16x16x32_bf16 v[36:39], v[192:195], v[208:211], v[36:39]
	v_mfma_f32_16x16x32_bf16 v[24:27], v[184:187], v[216:219], v[24:27]
	v_mfma_f32_16x16x32_bf16 v[20:23], v[192:195], v[216:219], v[20:23]
	v_mfma_f32_16x16x32_bf16 v[6:9], v[184:187], v[224:227], v[8:11]
	v_mfma_f32_16x16x32_bf16 v[2:5], v[192:195], v[224:227], v[2:5]
	v_mfma_f32_16x16x32_bf16 v[56:59], v[188:191], v[204:207], v[56:59]
	v_mfma_f32_16x16x32_bf16 v[52:55], v[196:199], v[204:207], v[52:55]
	v_mfma_f32_16x16x32_bf16 v[40:43], v[188:191], v[212:215], v[40:43]
	v_mfma_f32_16x16x32_bf16 v[36:39], v[196:199], v[212:215], v[36:39]
	v_mfma_f32_16x16x32_bf16 v[24:27], v[188:191], v[220:223], v[24:27]
	v_mfma_f32_16x16x32_bf16 v[20:23], v[196:199], v[220:223], v[20:23]
	v_mfma_f32_16x16x32_bf16 v[8:11], v[188:191], v[228:231], v[6:9]
	v_mfma_f32_16x16x32_bf16 v[4:7], v[196:199], v[228:231], v[2:5]
	s_setprio 0
	s_barrier
	s_add_i32 s58, s58, 2
	s_addk_i32 s59, 0x100
	s_cmp_gt_u32 s58, 29
	s_cbranch_scc1 .LBB0_772

; #define PG8_STAGE(srd, bufoff, goff, voff) do { _Pragma("unroll") for (int _i = 0; _i < 2; ++_i) \
;         __builtin_amdgcn_raw_ptr_buffer_load_lds(srd, (PG8_LAS unsigned*)(lds + (bufoff) + ldsw + _i * 8192), 16, (voff)[_i], (goff), 0, 0); } while (0)
; #define PG8_LDA(dst, b, h) do { _Pragma("unroll") for (int m = 0; m < 4; ++m) _Pragma("unroll") for (int k = 0; k < 2; ++k) dst[m][k] = *(const PG8_LAS bf16x8*)(lds + PG8_SA(b, h) + aoff + m * 2048 + k * 1024); } while (0)
; #define PG8_LDB(dst, b, h) do { _Pragma("unroll") for (int n = 0; n < 2; ++n) _Pragma("unroll") for (int k = 0; k < 2; ++k) dst[n][k] = *(const PG8_LAS bf16x8*)(lds + PG8_SB(b, h) + boff + n * 2048 + k * 1024); } while (0)
; #define PG8_MMA(ai, bj, At, Bt) do { __builtin_amdgcn_s_setprio(1); _Pragma("unroll") for (int m = 0; m < 4; ++m) _Pragma("unroll") for (int n = 0; n < 2; ++n) _Pragma("unroll") for (int k = 0; k < 2; ++k) \
;         acc[ai][bj][m][n] = __builtin_amdgcn_mfma_f32_16x16x32_bf16(Bt[n][k], At[m][k], acc[ai][bj][m][n], 0, 0, 0); __builtin_amdgcn_s_setprio(0); } while (0)
; #define PG8_WAIT_V(n) asm volatile("s_waitcnt vmcnt(" #n ")" ::: "memory")
; #define PG8_WAIT_L(n) asm volatile("s_waitcnt lgkmcnt(" #n ")" ::: "memory")
; #define PG8_BAR __builtin_amdgcn_s_barrier()
; #define PG8_SCHED __builtin_amdgcn_sched_barrier(0)
; template <class Epi, class Sched, bool ALIGN_EPI = true>
; __device__ __forceinline__ void gemm_phase(PG8_LAS unsigned char* lds, const Gemm g, const Sched& S, const Epi& E) {
;     ...
;             PG8_LDB(B0, 0, 0); PG8_LDB(B1, 0, 1); PG8_SCHED; PG8_LDA(At, 0, 0); PG8_STAGE(srdA, PG8_SA(1, 1), a1 + hstepA, voffA);
;             PG8_WAIT_V(8); PG8_WAIT_L(0); PG8_BAR; PG8_MMA(0, 0, At, B0); PG8_MMA(0, 1, At, B1); PG8_BAR; PG8_SCHED;
;             PG8_LDA(At, 0, 1); PG8_STAGE(srdB, PG8_SB(0, 0), b2, voffB); PG8_STAGE(srdB, PG8_SB(0, 1), b2 + hstepB, voffB); PG8_STAGE(srdA, PG8_SA(0, 0), a2, voffA);
;             PG8_WAIT_V(8); PG8_WAIT_L(0); PG8_BAR; PG8_MMA(1, 0, At, B0); PG8_MMA(1, 1, At, B1); PG8_BAR; PG8_SCHED;
.LBB0_896:
	ds_read_b128 v[154:157], v147
	ds_read_b128 v[172:175], v147 offset:1024
	ds_read_b128 v[176:179], v147 offset:2048
	ds_read_b128 v[180:183], v147 offset:3072
	ds_read_b128 v[184:187], v148
	ds_read_b128 v[188:191], v148 offset:1024
	ds_read_b128 v[192:195], v148 offset:2048
	ds_read_b128 v[196:199], v148 offset:3072
	s_add_i32 s26, s53, 0xfff80080
	s_cmp_eq_u32 s55, 28
	s_cselect_b32 s58, s51, s26
	s_cselect_b32 s57, s52, s54
	s_or_b32 s56, s58, 0x80
	s_mov_b32 m0, s44
	ds_read_b128 v[200:203], v149
	ds_read_b128 v[204:207], v149 offset:1024
	ds_read_b128 v[208:211], v149 offset:2048
	ds_read_b128 v[212:215], v149 offset:3072
	ds_read_b128 v[216:219], v149 offset:4096
	ds_read_b128 v[220:223], v149 offset:5120
	ds_read_b128 v[224:227], v149 offset:6144
	ds_read_b128 v[228:231], v149 offset:7168
	buffer_load_dwordx4 v135, s[16:19], s53 offen lds
	s_mov_b32 m0, s45
	s_nop 0
	buffer_load_dwordx4 v137, s[16:19], s53 offen lds
	s_waitcnt vmcnt(8)
	s_waitcnt lgkmcnt(0)
	s_barrier
	s_setprio 1
	v_mfma_f32_16x16x32_bf16 v[116:119], v[154:157], v[200:203], v[116:119]
	v_mfma_f32_16x16x32_bf16 v[112:115], v[176:179], v[200:203], v[112:115]
	v_mfma_f32_16x16x32_bf16 v[100:103], v[154:157], v[208:211], v[100:103]
	v_mfma_f32_16x16x32_bf16 v[96:99], v[176:179], v[208:211], v[96:99]
	v_mfma_f32_16x16x32_bf16 v[84:87], v[154:157], v[216:219], v[84:87]
	v_mfma_f32_16x16x32_bf16 v[80:83], v[176:179], v[216:219], v[80:83]
	v_mfma_f32_16x16x32_bf16 v[68:71], v[154:157], v[224:227], v[68:71]
	v_mfma_f32_16x16x32_bf16 v[64:67], v[176:179], v[224:227], v[64:67]
	v_mfma_f32_16x16x32_bf16 v[116:119], v[172:175], v[204:207], v[116:119]
	v_mfma_f32_16x16x32_bf16 v[112:115], v[180:183], v[204:207], v[112:115]
	v_mfma_f32_16x16x32_bf16 v[100:103], v[172:175], v[212:215], v[100:103]
	v_mfma_f32_16x16x32_bf16 v[96:99], v[180:183], v[212:215], v[96:99]
	v_mfma_f32_16x16x32_bf16 v[84:87], v[172:175], v[220:223], v[84:87]
	v_mfma_f32_16x16x32_bf16 v[80:83], v[180:183], v[220:223], v[80:83]
	v_mfma_f32_16x16x32_bf16 v[68:71], v[172:175], v[228:231], v[68:71]
	v_mfma_f32_16x16x32_bf16 v[64:67], v[180:183], v[228:231], v[64:67]
	s_setprio 0
	s_setprio 1
	v_mfma_f32_16x16x32_bf16 v[124:127], v[184:187], v[200:203], v[124:127]
	v_mfma_f32_16x16x32_bf16 v[120:123], v[192:195], v[200:203], v[120:123]
	v_mfma_f32_16x16x32_bf16 v[108:111], v[184:187], v[208:211], v[108:111]
	v_mfma_f32_16x16x32_bf16 v[104:107], v[192:195], v[208:211], v[104:107]
	v_mfma_f32_16x16x32_bf16 v[92:95], v[184:187], v[216:219], v[92:95]
	v_mfma_f32_16x16x32_bf16 v[88:91], v[192:195], v[216:219], v[88:91]
	v_mfma_f32_16x16x32_bf16 v[76:79], v[184:187], v[224:227], v[76:79]
	v_mfma_f32_16x16x32_bf16 v[72:75], v[192:195], v[224:227], v[72:75]
	v_mfma_f32_16x16x32_bf16 v[124:127], v[188:191], v[204:207], v[124:127]
	v_mfma_f32_16x16x32_bf16 v[120:123], v[196:199], v[204:207], v[120:123]
	v_mfma_f32_16x16x32_bf16 v[108:111], v[188:191], v[212:215], v[108:111]
	v_mfma_f32_16x16x32_bf16 v[104:107], v[196:199], v[212:215], v[104:107]
	v_mfma_f32_16x16x32_bf16 v[92:95], v[188:191], v[220:223], v[92:95]
	v_mfma_f32_16x16x32_bf16 v[88:91], v[196:199], v[220:223], v[88:91]
	v_mfma_f32_16x16x32_bf16 v[76:79], v[188:191], v[228:231], v[76:79]
	v_mfma_f32_16x16x32_bf16 v[72:75], v[196:199], v[228:231], v[72:75]
	s_setprio 0
	s_barrier
	s_mov_b32 m0, s28
	s_mov_b32 s26, s18
	s_mov_b32 s27, s19
	ds_read_b128 v[200:203], v149 offset:16384
	ds_read_b128 v[204:207], v149 offset:17408
	ds_read_b128 v[208:211], v149 offset:18432
	ds_read_b128 v[212:215], v149 offset:19456
	ds_read_b128 v[216:219], v149 offset:20480
	ds_read_b128 v[220:223], v149 offset:21504
	ds_read_b128 v[224:227], v149 offset:22528
	ds_read_b128 v[228:231], v149 offset:23552
	buffer_load_dwordx4 v136, s[24:27], s57 offen lds
	s_mov_b32 m0, s29
	s_add_i32 s59, s57, 0x80000
	buffer_load_dwordx4 v138, s[24:27], s57 offen lds
	s_mov_b32 m0, s30
	s_nop 0
	buffer_load_dwordx4 v136, s[24:27], s59 offen lds
	s_mov_b32 m0, s31
	s_nop 0
	buffer_load_dwordx4 v138, s[24:27], s59 offen lds
	s_mov_b32 m0, s21
	s_nop 0
	buffer_load_dwordx4 v135, s[16:19], s58 offen lds
	s_mov_b32 m0, s34
	s_nop 0
	buffer_load_dwordx4 v137, s[16:19], s58 offen lds
	s_waitcnt vmcnt(8)
	s_waitcnt lgkmcnt(0)
	s_barrier
	s_setprio 1
	v_mfma_f32_16x16x32_bf16 v[52:55], v[154:157], v[200:203], v[52:55]
	v_mfma_f32_16x16x32_bf16 v[48:51], v[176:179], v[200:203], v[48:51]
	v_mfma_f32_16x16x32_bf16 v[36:39], v[154:157], v[208:211], v[36:39]
	v_mfma_f32_16x16x32_bf16 v[32:35], v[176:179], v[208:211], v[32:35]
	v_mfma_f32_16x16x32_bf16 v[20:23], v[154:157], v[216:219], v[20:23]
	v_mfma_f32_16x16x32_bf16 v[16:19], v[176:179], v[216:219], v[16:19]
	v_mfma_f32_16x16x32_bf16 v[8:11], v[154:157], v[224:227], v[8:11]
	v_mfma_f32_16x16x32_bf16 v[4:7], v[176:179], v[224:227], v[4:7]
	v_mfma_f32_16x16x32_bf16 v[52:55], v[172:175], v[204:207], v[52:55]
	v_mfma_f32_16x16x32_bf16 v[48:51], v[180:183], v[204:207], v[48:51]
	v_mfma_f32_16x16x32_bf16 v[36:39], v[172:175], v[212:215], v[36:39]
	v_mfma_f32_16x16x32_bf16 v[32:35], v[180:183], v[212:215], v[32:35]
	v_mfma_f32_16x16x32_bf16 v[20:23], v[172:175], v[220:223], v[20:23]
	v_mfma_f32_16x16x32_bf16 v[16:19], v[180:183], v[220:223], v[16:19]
	v_mfma_f32_16x16x32_bf16 v[8:11], v[172:175], v[228:231], v[8:11]
	v_mfma_f32_16x16x32_bf16 v[4:7], v[180:183], v[228:231], v[4:7]
	s_setprio 0
	s_setprio 1
	v_mfma_f32_16x16x32_bf16 v[60:63], v[184:187], v[200:203], v[60:63]
	v_mfma_f32_16x16x32_bf16 v[56:59], v[192:195], v[200:203], v[56:59]
	v_mfma_f32_16x16x32_bf16 v[44:47], v[184:187], v[208:211], v[44:47]
	v_mfma_f32_16x16x32_bf16 v[40:43], v[192:195], v[208:211], v[40:43]
	v_mfma_f32_16x16x32_bf16 v[28:31], v[184:187], v[216:219], v[28:31]
	v_mfma_f32_16x16x32_bf16 v[24:27], v[192:195], v[216:219], v[24:27]
	v_mfma_f32_16x16x32_bf16 v[12:15], v[184:187], v[224:227], v[12:15]
	v_mfma_f32_16x16x32_bf16 v[0:3], v[192:195], v[224:227], v[0:3]
	v_mfma_f32_16x16x32_bf16 v[60:63], v[188:191], v[204:207], v[60:63]
	v_mfma_f32_16x16x32_bf16 v[56:59], v[196:199], v[204:207], v[56:59]
	v_mfma_f32_16x16x32_bf16 v[44:47], v[188:191], v[212:215], v[44:47]
	v_mfma_f32_16x16x32_bf16 v[40:43], v[196:199], v[212:215], v[40:43]
	v_mfma_f32_16x16x32_bf16 v[28:31], v[188:191], v[220:223], v[28:31]
	v_mfma_f32_16x16x32_bf16 v[24:27], v[196:199], v[220:223], v[24:27]
	v_mfma_f32_16x16x32_bf16 v[12:15], v[188:191], v[228:231], v[12:15]
	v_mfma_f32_16x16x32_bf16 v[0:3], v[196:199], v[228:231], v[0:3]
	s_setprio 0
	s_barrier
; #define PG8_STAGE(srd, bufoff, goff, voff) do { _Pragma("unroll") for (int _i = 0; _i < 2; ++_i) \
;         __builtin_amdgcn_raw_ptr_buffer_load_lds(srd, (PG8_LAS unsigned*)(lds + (bufoff) + ldsw + _i * 8192), 16, (voff)[_i], (goff), 0, 0); } while (0)
; #define PG8_LDA(dst, b, h) do { _Pragma("unroll") for (int m = 0; m < 4; ++m) _Pragma("unroll") for (int k = 0; k < 2; ++k) dst[m][k] = *(const PG8_LAS bf16x8*)(lds + PG8_SA(b, h) + aoff + m * 2048 + k * 1024); } while (0)
; #define PG8_LDB(dst, b, h) do { _Pragma("unroll") for (int n = 0; n < 2; ++n) _Pragma("unroll") for (int k = 0; k < 2; ++k) dst[n][k] = *(const PG8_LAS bf16x8*)(lds + PG8_SB(b, h) + boff + n * 2048 + k * 1024); } while (0)
; #define PG8_MMA(ai, bj, At, Bt) do { __builtin_amdgcn_s_setprio(1); _Pragma("unroll") for (int m = 0; m < 4; ++m) _Pragma("unroll") for (int n = 0; n < 2; ++n) _Pragma("unroll") for (int k = 0; k < 2; ++k) \
;         acc[ai][bj][m][n] = __builtin_amdgcn_mfma_f32_16x16x32_bf16(Bt[n][k], At[m][k], acc[ai][bj][m][n], 0, 0, 0); __builtin_amdgcn_s_setprio(0); } while (0)
; #define PG8_WAIT_V(n) asm volatile("s_waitcnt vmcnt(" #n ")" ::: "memory")
; #define PG8_WAIT_L(n) asm volatile("s_waitcnt lgkmcnt(" #n ")" ::: "memory")
; #define PG8_BAR __builtin_amdgcn_s_barrier()
; #define PG8_SCHED __builtin_amdgcn_sched_barrier(0)
; template <class Epi, class Sched, bool ALIGN_EPI = true>
; __device__ __forceinline__ void gemm_phase(PG8_LAS unsigned char* lds, const Gemm g, const Sched& S, const Epi& E) {
;     ...
;             PG8_LDB(B0, 1, 0); PG8_LDB(B1, 1, 1); PG8_SCHED; PG8_LDA(At, 1, 0); PG8_STAGE(srdA, PG8_SA(0, 1), a2 + hstepA, voffA);
;             PG8_WAIT_V(8); PG8_WAIT_L(0); PG8_BAR; PG8_MMA(0, 0, At, B0); PG8_MMA(0, 1, At, B1); PG8_BAR; PG8_SCHED;
;             PG8_LDA(At, 1, 1); PG8_STAGE(srdB, PG8_SB(1, 0), b3, voffB); PG8_STAGE(srdB, PG8_SB(1, 1), b3 + hstepB, voffB); PG8_STAGE(srdA, PG8_SA(1, 0), a3, voffA);
;             PG8_WAIT_V(8); PG8_WAIT_L(0); PG8_BAR; PG8_MMA(1, 0, At, B0); PG8_MMA(1, 1, At, B1); PG8_BAR; PG8_SCHED;
;         }
	ds_read_b128 v[154:157], v150
	ds_read_b128 v[172:175], v150 offset:1024
	ds_read_b128 v[176:179], v150 offset:2048
	ds_read_b128 v[180:183], v150 offset:3072
	ds_read_b128 v[184:187], v151
	ds_read_b128 v[188:191], v151 offset:1024
	ds_read_b128 v[192:195], v151 offset:2048
	ds_read_b128 v[196:199], v151 offset:3072
	s_add_i32 s58, s58, 0x80000
	s_mov_b32 m0, s35
	ds_read_b128 v[200:203], v149 offset:32768
	ds_read_b128 v[204:207], v149 offset:33792
	ds_read_b128 v[208:211], v149 offset:34816
	ds_read_b128 v[212:215], v149 offset:35840
	ds_read_b128 v[216:219], v149 offset:36864
	ds_read_b128 v[220:223], v149 offset:37888
	ds_read_b128 v[224:227], v149 offset:38912
	ds_read_b128 v[228:231], v149 offset:39936
	buffer_load_dwordx4 v135, s[16:19], s58 offen lds
	s_mov_b32 m0, s36
	s_nop 0
	buffer_load_dwordx4 v137, s[16:19], s58 offen lds
	s_waitcnt vmcnt(8)
	s_waitcnt lgkmcnt(0)
	s_barrier
	s_setprio 1
	v_mfma_f32_16x16x32_bf16 v[116:119], v[154:157], v[200:203], v[116:119]
	v_mfma_f32_16x16x32_bf16 v[112:115], v[176:179], v[200:203], v[112:115]
	v_mfma_f32_16x16x32_bf16 v[100:103], v[154:157], v[208:211], v[100:103]
	v_mfma_f32_16x16x32_bf16 v[96:99], v[176:179], v[208:211], v[96:99]
	v_mfma_f32_16x16x32_bf16 v[84:87], v[154:157], v[216:219], v[84:87]
	v_mfma_f32_16x16x32_bf16 v[80:83], v[176:179], v[216:219], v[80:83]
	v_mfma_f32_16x16x32_bf16 v[68:71], v[154:157], v[224:227], v[68:71]
	v_mfma_f32_16x16x32_bf16 v[64:67], v[176:179], v[224:227], v[64:67]
	v_mfma_f32_16x16x32_bf16 v[116:119], v[172:175], v[204:207], v[116:119]
	v_mfma_f32_16x16x32_bf16 v[112:115], v[180:183], v[204:207], v[112:115]
	v_mfma_f32_16x16x32_bf16 v[100:103], v[172:175], v[212:215], v[100:103]
	v_mfma_f32_16x16x32_bf16 v[96:99], v[180:183], v[212:215], v[96:99]
	v_mfma_f32_16x16x32_bf16 v[84:87], v[172:175], v[220:223], v[84:87]
	v_mfma_f32_16x16x32_bf16 v[80:83], v[180:183], v[220:223], v[80:83]
	v_mfma_f32_16x16x32_bf16 v[68:71], v[172:175], v[228:231], v[68:71]
	v_mfma_f32_16x16x32_bf16 v[64:67], v[180:183], v[228:231], v[64:67]
	s_setprio 0
	s_setprio 1
	v_mfma_f32_16x16x32_bf16 v[124:127], v[184:187], v[200:203], v[124:127]
	v_mfma_f32_16x16x32_bf16 v[120:123], v[192:195], v[200:203], v[120:123]
	v_mfma_f32_16x16x32_bf16 v[108:111], v[184:187], v[208:211], v[108:111]
	v_mfma_f32_16x16x32_bf16 v[104:107], v[192:195], v[208:211], v[104:107]
	v_mfma_f32_16x16x32_bf16 v[92:95], v[184:187], v[216:219], v[92:95]
	v_mfma_f32_16x16x32_bf16 v[88:91], v[192:195], v[216:219], v[88:91]
	v_mfma_f32_16x16x32_bf16 v[76:79], v[184:187], v[224:227], v[76:79]
	v_mfma_f32_16x16x32_bf16 v[72:75], v[192:195], v[224:227], v[72:75]
	v_mfma_f32_16x16x32_bf16 v[124:127], v[188:191], v[204:207], v[124:127]
	v_mfma_f32_16x16x32_bf16 v[120:123], v[196:199], v[204:207], v[120:123]
	v_mfma_f32_16x16x32_bf16 v[108:111], v[188:191], v[212:215], v[108:111]
	v_mfma_f32_16x16x32_bf16 v[104:107], v[196:199], v[212:215], v[104:107]
	v_mfma_f32_16x16x32_bf16 v[92:95], v[188:191], v[220:223], v[92:95]
	v_mfma_f32_16x16x32_bf16 v[88:91], v[196:199], v[220:223], v[88:91]
	v_mfma_f32_16x16x32_bf16 v[76:79], v[188:191], v[228:231], v[76:79]
	v_mfma_f32_16x16x32_bf16 v[72:75], v[196:199], v[228:231], v[72:75]
	s_setprio 0
	s_barrier
	s_mov_b32 m0, s38
	s_or_b32 s58, s57, 0x80
	ds_read_b128 v[200:203], v149 offset:49152
	ds_read_b128 v[204:207], v149 offset:50176
	ds_read_b128 v[208:211], v149 offset:51200
	ds_read_b128 v[212:215], v149 offset:52224
	ds_read_b128 v[216:219], v149 offset:53248
	ds_read_b128 v[220:223], v149 offset:54272
	ds_read_b128 v[224:227], v149 offset:55296
	ds_read_b128 v[228:231], v149 offset:56320
	buffer_load_dwordx4 v136, s[24:27], s58 offen lds
	s_mov_b32 m0, s39
	s_add_i32 s57, s57, 0x80080
	buffer_load_dwordx4 v138, s[24:27], s58 offen lds
	s_mov_b32 m0, s42
	s_nop 0
	buffer_load_dwordx4 v136, s[24:27], s57 offen lds
	s_mov_b32 m0, s43
	s_nop 0
	buffer_load_dwordx4 v138, s[24:27], s57 offen lds
	s_mov_b32 m0, s40
	s_nop 0
	buffer_load_dwordx4 v135, s[16:19], s56 offen lds
	s_mov_b32 m0, s41
	s_nop 0
	buffer_load_dwordx4 v137, s[16:19], s56 offen lds
	s_waitcnt vmcnt(8)
	s_waitcnt lgkmcnt(0)
	s_barrier
	s_setprio 1
	v_mfma_f32_16x16x32_bf16 v[52:55], v[154:157], v[200:203], v[52:55]
	v_mfma_f32_16x16x32_bf16 v[48:51], v[176:179], v[200:203], v[48:51]
	v_mfma_f32_16x16x32_bf16 v[36:39], v[154:157], v[208:211], v[36:39]
	v_mfma_f32_16x16x32_bf16 v[32:35], v[176:179], v[208:211], v[32:35]
	v_mfma_f32_16x16x32_bf16 v[20:23], v[154:157], v[216:219], v[20:23]
	v_mfma_f32_16x16x32_bf16 v[16:19], v[176:179], v[216:219], v[16:19]
	v_mfma_f32_16x16x32_bf16 v[8:11], v[154:157], v[224:227], v[8:11]
	v_mfma_f32_16x16x32_bf16 v[4:7], v[176:179], v[224:227], v[4:7]
	v_mfma_f32_16x16x32_bf16 v[52:55], v[172:175], v[204:207], v[52:55]
	v_mfma_f32_16x16x32_bf16 v[48:51], v[180:183], v[204:207], v[48:51]
	v_mfma_f32_16x16x32_bf16 v[36:39], v[172:175], v[212:215], v[36:39]
	v_mfma_f32_16x16x32_bf16 v[32:35], v[180:183], v[212:215], v[32:35]
	v_mfma_f32_16x16x32_bf16 v[20:23], v[172:175], v[220:223], v[20:23]
	v_mfma_f32_16x16x32_bf16 v[16:19], v[180:183], v[220:223], v[16:19]
	v_mfma_f32_16x16x32_bf16 v[8:11], v[172:175], v[228:231], v[8:11]
	v_mfma_f32_16x16x32_bf16 v[4:7], v[180:183], v[228:231], v[4:7]
	s_setprio 0
	s_setprio 1
	v_mfma_f32_16x16x32_bf16 v[60:63], v[184:187], v[200:203], v[60:63]
	v_mfma_f32_16x16x32_bf16 v[56:59], v[192:195], v[200:203], v[56:59]
	v_mfma_f32_16x16x32_bf16 v[44:47], v[184:187], v[208:211], v[44:47]
	v_mfma_f32_16x16x32_bf16 v[40:43], v[192:195], v[208:211], v[40:43]
	v_mfma_f32_16x16x32_bf16 v[28:31], v[184:187], v[216:219], v[28:31]
	v_mfma_f32_16x16x32_bf16 v[24:27], v[192:195], v[216:219], v[24:27]
	v_mfma_f32_16x16x32_bf16 v[12:15], v[184:187], v[224:227], v[12:15]
	v_mfma_f32_16x16x32_bf16 v[0:3], v[192:195], v[224:227], v[0:3]
	v_mfma_f32_16x16x32_bf16 v[60:63], v[188:191], v[204:207], v[60:63]
	v_mfma_f32_16x16x32_bf16 v[56:59], v[196:199], v[204:207], v[56:59]
	v_mfma_f32_16x16x32_bf16 v[44:47], v[188:191], v[212:215], v[44:47]
	v_mfma_f32_16x16x32_bf16 v[40:43], v[196:199], v[212:215], v[40:43]
	v_mfma_f32_16x16x32_bf16 v[28:31], v[188:191], v[220:223], v[28:31]
	v_mfma_f32_16x16x32_bf16 v[24:27], v[196:199], v[220:223], v[24:27]
	v_mfma_f32_16x16x32_bf16 v[12:15], v[188:191], v[228:231], v[12:15]
	v_mfma_f32_16x16x32_bf16 v[0:3], v[196:199], v[228:231], v[0:3]
	s_setprio 0
	s_barrier
	s_add_i32 s55, s55, 2
	s_addk_i32 s53, 0x100
	s_addk_i32 s54, 0x100
	s_cmp_gt_u32 s55, 29
	s_cbranch_scc0 .LBB0_896
	s_and_b64 vcc, exec, s[10:11]
	s_cbranch_vccz .LBB0_899
	s_barrier

; #define PG8_STAGE(srd, bufoff, goff, voff) do { _Pragma("unroll") for (int _i = 0; _i < 2; ++_i) \
;         __builtin_amdgcn_raw_ptr_buffer_load_lds(srd, (PG8_LAS unsigned*)(lds + (bufoff) + ldsw + _i * 8192), 16, (voff)[_i], (goff), 0, 0); } while (0)
; #define PG8_LDA(dst, b, h) do { _Pragma("unroll") for (int m = 0; m < 4; ++m) _Pragma("unroll") for (int k = 0; k < 2; ++k) dst[m][k] = *(const PG8_LAS bf16x8*)(lds + PG8_SA(b, h) + aoff + m * 2048 + k * 1024); } while (0)
; #define PG8_LDB(dst, b, h) do { _Pragma("unroll") for (int n = 0; n < 2; ++n) _Pragma("unroll") for (int k = 0; k < 2; ++k) dst[n][k] = *(const PG8_LAS bf16x8*)(lds + PG8_SB(b, h) + boff + n * 2048 + k * 1024); } while (0)
; #define PG8_MMA(ai, bj, At, Bt) do { __builtin_amdgcn_s_setprio(1); _Pragma("unroll") for (int m = 0; m < 4; ++m) _Pragma("unroll") for (int n = 0; n < 2; ++n) _Pragma("unroll") for (int k = 0; k < 2; ++k) \
;         acc[ai][bj][m][n] = __builtin_amdgcn_mfma_f32_16x16x32_bf16(Bt[n][k], At[m][k], acc[ai][bj][m][n], 0, 0, 0); __builtin_amdgcn_s_setprio(0); } while (0)
; #define PG8_WAIT_V(n) asm volatile("s_waitcnt vmcnt(" #n ")" ::: "memory")
; #define PG8_WAIT_L(n) asm volatile("s_waitcnt lgkmcnt(" #n ")" ::: "memory")
; #define PG8_BAR __builtin_amdgcn_s_barrier()
; #define PG8_SCHED __builtin_amdgcn_sched_barrier(0)
; template <class Epi, class Sched, bool ALIGN_EPI = true>
; __device__ __forceinline__ void gemm_phase(PG8_LAS unsigned char* lds, const Gemm g, const Sched& S, const Epi& E) {
;     ...
;             PG8_LDB(B0, 0, 0); PG8_LDB(B1, 0, 1); PG8_SCHED; PG8_LDA(At, 0, 0); PG8_STAGE(srdA, PG8_SA(1, 1), a1 + hstepA, voffA);
;             PG8_WAIT_V(8); PG8_WAIT_L(0); PG8_BAR; PG8_MMA(0, 0, At, B0); PG8_MMA(0, 1, At, B1); PG8_BAR; PG8_SCHED;
;             PG8_LDA(At, 0, 1); PG8_STAGE(srdB, PG8_SB(0, 0), b2, voffB); PG8_STAGE(srdB, PG8_SB(0, 1), b2 + hstepB, voffB); PG8_STAGE(srdA, PG8_SA(0, 0), a2, voffA);
;             PG8_WAIT_V(8); PG8_WAIT_L(0); PG8_BAR; PG8_MMA(1, 0, At, B0); PG8_MMA(1, 1, At, B1); PG8_BAR; PG8_SCHED;
.LBB0_965:
	ds_read_b128 v[152:155], v147
	ds_read_b128 v[156:159], v147 offset:1024
	ds_read_b128 v[166:169], v147 offset:2048
	ds_read_b128 v[172:175], v147 offset:3072
	ds_read_b128 v[176:179], v148
	ds_read_b128 v[180:183], v148 offset:1024
	ds_read_b128 v[184:187], v148 offset:2048
	ds_read_b128 v[188:191], v148 offset:3072
	s_add_i32 s49, s46, 0xffea0080
	s_cmpk_eq_i32 s48, 0x54
	s_cselect_b32 s50, s44, s49
	s_cselect_b32 s51, s45, s47
	s_or_b32 s49, s50, 0x80
	s_mov_b32 m0, s38
	ds_read_b128 v[192:195], v149
	ds_read_b128 v[196:199], v149 offset:1024
	ds_read_b128 v[200:203], v149 offset:2048
	ds_read_b128 v[204:207], v149 offset:3072
	ds_read_b128 v[208:211], v149 offset:4096
	ds_read_b128 v[212:215], v149 offset:5120
	ds_read_b128 v[216:219], v149 offset:6144
	ds_read_b128 v[220:223], v149 offset:7168
	buffer_load_dwordx4 v135, s[12:15], s46 offen lds
	s_mov_b32 m0, s39
	s_nop 0
	buffer_load_dwordx4 v137, s[12:15], s46 offen lds
	s_waitcnt vmcnt(8)
	s_waitcnt lgkmcnt(0)
	s_barrier
	s_setprio 1
	v_mfma_f32_16x16x32_bf16 v[124:127], v[152:155], v[192:195], v[124:127]
	v_mfma_f32_16x16x32_bf16 v[120:123], v[166:169], v[192:195], v[120:123]
	v_mfma_f32_16x16x32_bf16 v[116:119], v[152:155], v[200:203], v[116:119]
	v_mfma_f32_16x16x32_bf16 v[108:111], v[166:169], v[200:203], v[108:111]
	v_mfma_f32_16x16x32_bf16 v[100:103], v[152:155], v[208:211], v[100:103]
	v_mfma_f32_16x16x32_bf16 v[92:95], v[166:169], v[208:211], v[92:95]
	v_mfma_f32_16x16x32_bf16 v[84:87], v[152:155], v[216:219], v[84:87]
	v_mfma_f32_16x16x32_bf16 v[76:79], v[166:169], v[216:219], v[76:79]
	v_mfma_f32_16x16x32_bf16 v[124:127], v[156:159], v[196:199], v[124:127]
	v_mfma_f32_16x16x32_bf16 v[120:123], v[172:175], v[196:199], v[120:123]
	v_mfma_f32_16x16x32_bf16 v[116:119], v[156:159], v[204:207], v[116:119]
	v_mfma_f32_16x16x32_bf16 v[108:111], v[172:175], v[204:207], v[108:111]
	v_mfma_f32_16x16x32_bf16 v[100:103], v[156:159], v[212:215], v[100:103]
	v_mfma_f32_16x16x32_bf16 v[92:95], v[172:175], v[212:215], v[92:95]
	v_mfma_f32_16x16x32_bf16 v[84:87], v[156:159], v[220:223], v[84:87]
	v_mfma_f32_16x16x32_bf16 v[76:79], v[172:175], v[220:223], v[76:79]
	s_setprio 0
	s_setprio 1
	v_mfma_f32_16x16x32_bf16 v[112:115], v[176:179], v[192:195], v[112:115]
	v_mfma_f32_16x16x32_bf16 v[104:107], v[184:187], v[192:195], v[104:107]
	v_mfma_f32_16x16x32_bf16 v[96:99], v[176:179], v[200:203], v[96:99]
	v_mfma_f32_16x16x32_bf16 v[88:91], v[184:187], v[200:203], v[88:91]
	v_mfma_f32_16x16x32_bf16 v[80:83], v[176:179], v[208:211], v[80:83]
	v_mfma_f32_16x16x32_bf16 v[72:75], v[184:187], v[208:211], v[72:75]
	v_mfma_f32_16x16x32_bf16 v[68:71], v[176:179], v[216:219], v[68:71]
	v_mfma_f32_16x16x32_bf16 v[64:67], v[184:187], v[216:219], v[64:67]
	v_mfma_f32_16x16x32_bf16 v[112:115], v[180:183], v[196:199], v[112:115]
	v_mfma_f32_16x16x32_bf16 v[104:107], v[188:191], v[196:199], v[104:107]
	v_mfma_f32_16x16x32_bf16 v[96:99], v[180:183], v[204:207], v[96:99]
	v_mfma_f32_16x16x32_bf16 v[88:91], v[188:191], v[204:207], v[88:91]
	v_mfma_f32_16x16x32_bf16 v[80:83], v[180:183], v[212:215], v[80:83]
	v_mfma_f32_16x16x32_bf16 v[72:75], v[188:191], v[212:215], v[72:75]
	v_mfma_f32_16x16x32_bf16 v[68:71], v[180:183], v[220:223], v[68:71]
	v_mfma_f32_16x16x32_bf16 v[64:67], v[188:191], v[220:223], v[64:67]
	s_setprio 0
	s_barrier
	s_mov_b32 m0, s24
	ds_read_b128 v[192:195], v149 offset:16384
	ds_read_b128 v[196:199], v149 offset:17408
	ds_read_b128 v[200:203], v149 offset:18432
	ds_read_b128 v[204:207], v149 offset:19456
	ds_read_b128 v[208:211], v149 offset:20480
	ds_read_b128 v[212:215], v149 offset:21504
	ds_read_b128 v[216:219], v149 offset:22528
	ds_read_b128 v[220:223], v149 offset:23552
	buffer_load_dwordx4 v136, s[16:19], s51 offen lds
	s_mov_b32 m0, s25
	s_add_i32 s52, s51, 0x160000
	buffer_load_dwordx4 v138, s[16:19], s51 offen lds
	s_mov_b32 m0, s26
	s_nop 0
	buffer_load_dwordx4 v136, s[16:19], s52 offen lds
	s_mov_b32 m0, s27
	s_nop 0
	buffer_load_dwordx4 v138, s[16:19], s52 offen lds
	s_mov_b32 m0, s21
	s_nop 0
	buffer_load_dwordx4 v135, s[12:15], s50 offen lds
	s_mov_b32 m0, s22
	s_nop 0
	buffer_load_dwordx4 v137, s[12:15], s50 offen lds
	s_waitcnt vmcnt(8)
	s_waitcnt lgkmcnt(0)
	s_barrier
	s_setprio 1
	v_mfma_f32_16x16x32_bf16 v[60:63], v[152:155], v[192:195], v[60:63]
	v_mfma_f32_16x16x32_bf16 v[56:59], v[166:169], v[192:195], v[56:59]
	v_mfma_f32_16x16x32_bf16 v[52:55], v[152:155], v[200:203], v[52:55]
	v_mfma_f32_16x16x32_bf16 v[44:47], v[166:169], v[200:203], v[44:47]
	v_mfma_f32_16x16x32_bf16 v[36:39], v[152:155], v[208:211], v[36:39]
	v_mfma_f32_16x16x32_bf16 v[28:31], v[166:169], v[208:211], v[28:31]
	v_mfma_f32_16x16x32_bf16 v[20:23], v[152:155], v[216:219], v[20:23]
	v_mfma_f32_16x16x32_bf16 v[12:15], v[166:169], v[216:219], v[12:15]
	v_mfma_f32_16x16x32_bf16 v[60:63], v[156:159], v[196:199], v[60:63]
	v_mfma_f32_16x16x32_bf16 v[56:59], v[172:175], v[196:199], v[56:59]
	v_mfma_f32_16x16x32_bf16 v[52:55], v[156:159], v[204:207], v[52:55]
	v_mfma_f32_16x16x32_bf16 v[44:47], v[172:175], v[204:207], v[44:47]
	v_mfma_f32_16x16x32_bf16 v[36:39], v[156:159], v[212:215], v[36:39]
	v_mfma_f32_16x16x32_bf16 v[28:31], v[172:175], v[212:215], v[28:31]
	v_mfma_f32_16x16x32_bf16 v[20:23], v[156:159], v[220:223], v[20:23]
	v_mfma_f32_16x16x32_bf16 v[12:15], v[172:175], v[220:223], v[12:15]
	s_setprio 0
	s_setprio 1
	v_mfma_f32_16x16x32_bf16 v[48:51], v[176:179], v[192:195], v[48:51]
	v_mfma_f32_16x16x32_bf16 v[40:43], v[184:187], v[192:195], v[40:43]
	v_mfma_f32_16x16x32_bf16 v[32:35], v[176:179], v[200:203], v[32:35]
	v_mfma_f32_16x16x32_bf16 v[24:27], v[184:187], v[200:203], v[24:27]
	v_mfma_f32_16x16x32_bf16 v[16:19], v[176:179], v[208:211], v[16:19]
	v_mfma_f32_16x16x32_bf16 v[8:11], v[184:187], v[208:211], v[8:11]
	v_mfma_f32_16x16x32_bf16 v[4:7], v[176:179], v[216:219], v[4:7]
	v_mfma_f32_16x16x32_bf16 v[0:3], v[184:187], v[216:219], v[0:3]
	v_mfma_f32_16x16x32_bf16 v[48:51], v[180:183], v[196:199], v[48:51]
	v_mfma_f32_16x16x32_bf16 v[40:43], v[188:191], v[196:199], v[40:43]
	v_mfma_f32_16x16x32_bf16 v[32:35], v[180:183], v[204:207], v[32:35]
	v_mfma_f32_16x16x32_bf16 v[24:27], v[188:191], v[204:207], v[24:27]
	v_mfma_f32_16x16x32_bf16 v[16:19], v[180:183], v[212:215], v[16:19]
	v_mfma_f32_16x16x32_bf16 v[8:11], v[188:191], v[212:215], v[8:11]
	v_mfma_f32_16x16x32_bf16 v[4:7], v[180:183], v[220:223], v[4:7]
	v_mfma_f32_16x16x32_bf16 v[0:3], v[188:191], v[220:223], v[0:3]
	s_setprio 0
	s_barrier
; #define PG8_STAGE(srd, bufoff, goff, voff) do { _Pragma("unroll") for (int _i = 0; _i < 2; ++_i) \
;         __builtin_amdgcn_raw_ptr_buffer_load_lds(srd, (PG8_LAS unsigned*)(lds + (bufoff) + ldsw + _i * 8192), 16, (voff)[_i], (goff), 0, 0); } while (0)
; #define PG8_LDA(dst, b, h) do { _Pragma("unroll") for (int m = 0; m < 4; ++m) _Pragma("unroll") for (int k = 0; k < 2; ++k) dst[m][k] = *(const PG8_LAS bf16x8*)(lds + PG8_SA(b, h) + aoff + m * 2048 + k * 1024); } while (0)
; #define PG8_LDB(dst, b, h) do { _Pragma("unroll") for (int n = 0; n < 2; ++n) _Pragma("unroll") for (int k = 0; k < 2; ++k) dst[n][k] = *(const PG8_LAS bf16x8*)(lds + PG8_SB(b, h) + boff + n * 2048 + k * 1024); } while (0)
; #define PG8_MMA(ai, bj, At, Bt) do { __builtin_amdgcn_s_setprio(1); _Pragma("unroll") for (int m = 0; m < 4; ++m) _Pragma("unroll") for (int n = 0; n < 2; ++n) _Pragma("unroll") for (int k = 0; k < 2; ++k) \
;         acc[ai][bj][m][n] = __builtin_amdgcn_mfma_f32_16x16x32_bf16(Bt[n][k], At[m][k], acc[ai][bj][m][n], 0, 0, 0); __builtin_amdgcn_s_setprio(0); } while (0)
; #define PG8_WAIT_V(n) asm volatile("s_waitcnt vmcnt(" #n ")" ::: "memory")
; #define PG8_WAIT_L(n) asm volatile("s_waitcnt lgkmcnt(" #n ")" ::: "memory")
; #define PG8_BAR __builtin_amdgcn_s_barrier()
; #define PG8_SCHED __builtin_amdgcn_sched_barrier(0)
; template <class Epi, class Sched, bool ALIGN_EPI = true>
; __device__ __forceinline__ void gemm_phase(PG8_LAS unsigned char* lds, const Gemm g, const Sched& S, const Epi& E) {
;     ...
;             PG8_LDB(B0, 1, 0); PG8_LDB(B1, 1, 1); PG8_SCHED; PG8_LDA(At, 1, 0); PG8_STAGE(srdA, PG8_SA(0, 1), a2 + hstepA, voffA);
;             PG8_WAIT_V(8); PG8_WAIT_L(0); PG8_BAR; PG8_MMA(0, 0, At, B0); PG8_MMA(0, 1, At, B1); PG8_BAR; PG8_SCHED;
;             PG8_LDA(At, 1, 1); PG8_STAGE(srdB, PG8_SB(1, 0), b3, voffB); PG8_STAGE(srdB, PG8_SB(1, 1), b3 + hstepB, voffB); PG8_STAGE(srdA, PG8_SA(1, 0), a3, voffA);
;             PG8_WAIT_V(8); PG8_WAIT_L(0); PG8_BAR; PG8_MMA(1, 0, At, B0); PG8_MMA(1, 1, At, B1); PG8_BAR; PG8_SCHED;
;         }
	ds_read_b128 v[152:155], v150
	ds_read_b128 v[156:159], v150 offset:1024
	ds_read_b128 v[166:169], v150 offset:2048
	ds_read_b128 v[172:175], v150 offset:3072
	ds_read_b128 v[176:179], v151
	ds_read_b128 v[180:183], v151 offset:1024
	ds_read_b128 v[184:187], v151 offset:2048
	ds_read_b128 v[188:191], v151 offset:3072
	s_add_i32 s50, s50, 0x160000
	s_mov_b32 m0, s23
	ds_read_b128 v[192:195], v149 offset:32768
	ds_read_b128 v[196:199], v149 offset:33792
	ds_read_b128 v[200:203], v149 offset:34816
	ds_read_b128 v[204:207], v149 offset:35840
	ds_read_b128 v[208:211], v149 offset:36864
	ds_read_b128 v[212:215], v149 offset:37888
	ds_read_b128 v[216:219], v149 offset:38912
	ds_read_b128 v[220:223], v149 offset:39936
	buffer_load_dwordx4 v135, s[12:15], s50 offen lds
	s_mov_b32 m0, s28
	s_nop 0
	buffer_load_dwordx4 v137, s[12:15], s50 offen lds
	s_waitcnt vmcnt(8)
	s_waitcnt lgkmcnt(0)
	s_barrier
	s_setprio 1
	v_mfma_f32_16x16x32_bf16 v[124:127], v[152:155], v[192:195], v[124:127]
	v_mfma_f32_16x16x32_bf16 v[120:123], v[166:169], v[192:195], v[120:123]
	v_mfma_f32_16x16x32_bf16 v[116:119], v[152:155], v[200:203], v[116:119]
	v_mfma_f32_16x16x32_bf16 v[108:111], v[166:169], v[200:203], v[108:111]
	v_mfma_f32_16x16x32_bf16 v[100:103], v[152:155], v[208:211], v[100:103]
	v_mfma_f32_16x16x32_bf16 v[92:95], v[166:169], v[208:211], v[92:95]
	v_mfma_f32_16x16x32_bf16 v[84:87], v[152:155], v[216:219], v[84:87]
	v_mfma_f32_16x16x32_bf16 v[76:79], v[166:169], v[216:219], v[76:79]
	v_mfma_f32_16x16x32_bf16 v[124:127], v[156:159], v[196:199], v[124:127]
	v_mfma_f32_16x16x32_bf16 v[120:123], v[172:175], v[196:199], v[120:123]
	v_mfma_f32_16x16x32_bf16 v[116:119], v[156:159], v[204:207], v[116:119]
	v_mfma_f32_16x16x32_bf16 v[108:111], v[172:175], v[204:207], v[108:111]
	v_mfma_f32_16x16x32_bf16 v[100:103], v[156:159], v[212:215], v[100:103]
	v_mfma_f32_16x16x32_bf16 v[92:95], v[172:175], v[212:215], v[92:95]
	v_mfma_f32_16x16x32_bf16 v[84:87], v[156:159], v[220:223], v[84:87]
	v_mfma_f32_16x16x32_bf16 v[76:79], v[172:175], v[220:223], v[76:79]
	s_setprio 0
	s_setprio 1
	v_mfma_f32_16x16x32_bf16 v[112:115], v[176:179], v[192:195], v[112:115]
	v_mfma_f32_16x16x32_bf16 v[104:107], v[184:187], v[192:195], v[104:107]
	v_mfma_f32_16x16x32_bf16 v[96:99], v[176:179], v[200:203], v[96:99]
	v_mfma_f32_16x16x32_bf16 v[88:91], v[184:187], v[200:203], v[88:91]
	v_mfma_f32_16x16x32_bf16 v[80:83], v[176:179], v[208:211], v[80:83]
	v_mfma_f32_16x16x32_bf16 v[72:75], v[184:187], v[208:211], v[72:75]
	v_mfma_f32_16x16x32_bf16 v[68:71], v[176:179], v[216:219], v[68:71]
	v_mfma_f32_16x16x32_bf16 v[64:67], v[184:187], v[216:219], v[64:67]
	v_mfma_f32_16x16x32_bf16 v[112:115], v[180:183], v[196:199], v[112:115]
	v_mfma_f32_16x16x32_bf16 v[104:107], v[188:191], v[196:199], v[104:107]
	v_mfma_f32_16x16x32_bf16 v[96:99], v[180:183], v[204:207], v[96:99]
	v_mfma_f32_16x16x32_bf16 v[88:91], v[188:191], v[204:207], v[88:91]
	v_mfma_f32_16x16x32_bf16 v[80:83], v[180:183], v[212:215], v[80:83]
	v_mfma_f32_16x16x32_bf16 v[72:75], v[188:191], v[212:215], v[72:75]
	v_mfma_f32_16x16x32_bf16 v[68:71], v[180:183], v[220:223], v[68:71]
	v_mfma_f32_16x16x32_bf16 v[64:67], v[188:191], v[220:223], v[64:67]
	s_setprio 0
	s_barrier
	s_mov_b32 m0, s30
	s_or_b32 s50, s51, 0x80
	ds_read_b128 v[192:195], v149 offset:49152
	ds_read_b128 v[196:199], v149 offset:50176
	ds_read_b128 v[200:203], v149 offset:51200
	ds_read_b128 v[204:207], v149 offset:52224
	ds_read_b128 v[208:211], v149 offset:53248
	ds_read_b128 v[212:215], v149 offset:54272
	ds_read_b128 v[216:219], v149 offset:55296
	ds_read_b128 v[220:223], v149 offset:56320
	buffer_load_dwordx4 v136, s[16:19], s50 offen lds
	s_mov_b32 m0, s31
	s_add_i32 s51, s51, 0x160080
	buffer_load_dwordx4 v138, s[16:19], s50 offen lds
	s_mov_b32 m0, s36
	s_nop 0
	buffer_load_dwordx4 v136, s[16:19], s51 offen lds
	s_mov_b32 m0, s37
	s_nop 0
	buffer_load_dwordx4 v138, s[16:19], s51 offen lds
	s_mov_b32 m0, s34
	s_nop 0
	buffer_load_dwordx4 v135, s[12:15], s49 offen lds
	s_mov_b32 m0, s35
	s_nop 0
	buffer_load_dwordx4 v137, s[12:15], s49 offen lds
	s_waitcnt vmcnt(8)
	s_waitcnt lgkmcnt(0)
	s_barrier
	s_setprio 1
	v_mfma_f32_16x16x32_bf16 v[60:63], v[152:155], v[192:195], v[60:63]
	v_mfma_f32_16x16x32_bf16 v[56:59], v[166:169], v[192:195], v[56:59]
	v_mfma_f32_16x16x32_bf16 v[52:55], v[152:155], v[200:203], v[52:55]
	v_mfma_f32_16x16x32_bf16 v[44:47], v[166:169], v[200:203], v[44:47]
	v_mfma_f32_16x16x32_bf16 v[36:39], v[152:155], v[208:211], v[36:39]
	v_mfma_f32_16x16x32_bf16 v[28:31], v[166:169], v[208:211], v[28:31]
	v_mfma_f32_16x16x32_bf16 v[20:23], v[152:155], v[216:219], v[20:23]
	v_mfma_f32_16x16x32_bf16 v[12:15], v[166:169], v[216:219], v[12:15]
	v_mfma_f32_16x16x32_bf16 v[60:63], v[156:159], v[196:199], v[60:63]
	v_mfma_f32_16x16x32_bf16 v[56:59], v[172:175], v[196:199], v[56:59]
	v_mfma_f32_16x16x32_bf16 v[52:55], v[156:159], v[204:207], v[52:55]
	v_mfma_f32_16x16x32_bf16 v[44:47], v[172:175], v[204:207], v[44:47]
	v_mfma_f32_16x16x32_bf16 v[36:39], v[156:159], v[212:215], v[36:39]
	v_mfma_f32_16x16x32_bf16 v[28:31], v[172:175], v[212:215], v[28:31]
	v_mfma_f32_16x16x32_bf16 v[20:23], v[156:159], v[220:223], v[20:23]
	v_mfma_f32_16x16x32_bf16 v[12:15], v[172:175], v[220:223], v[12:15]
	s_setprio 0
	s_setprio 1
	v_mfma_f32_16x16x32_bf16 v[48:51], v[176:179], v[192:195], v[48:51]
	v_mfma_f32_16x16x32_bf16 v[40:43], v[184:187], v[192:195], v[40:43]
	v_mfma_f32_16x16x32_bf16 v[32:35], v[176:179], v[200:203], v[32:35]
	v_mfma_f32_16x16x32_bf16 v[24:27], v[184:187], v[200:203], v[24:27]
	v_mfma_f32_16x16x32_bf16 v[16:19], v[176:179], v[208:211], v[16:19]
	v_mfma_f32_16x16x32_bf16 v[8:11], v[184:187], v[208:211], v[8:11]
	v_mfma_f32_16x16x32_bf16 v[4:7], v[176:179], v[216:219], v[4:7]
	v_mfma_f32_16x16x32_bf16 v[0:3], v[184:187], v[216:219], v[0:3]
	v_mfma_f32_16x16x32_bf16 v[48:51], v[180:183], v[196:199], v[48:51]
	v_mfma_f32_16x16x32_bf16 v[40:43], v[188:191], v[196:199], v[40:43]
	v_mfma_f32_16x16x32_bf16 v[32:35], v[180:183], v[204:207], v[32:35]
	v_mfma_f32_16x16x32_bf16 v[24:27], v[188:191], v[204:207], v[24:27]
	v_mfma_f32_16x16x32_bf16 v[16:19], v[180:183], v[212:215], v[16:19]
	v_mfma_f32_16x16x32_bf16 v[8:11], v[188:191], v[212:215], v[8:11]
	v_mfma_f32_16x16x32_bf16 v[4:7], v[180:183], v[220:223], v[4:7]
	v_mfma_f32_16x16x32_bf16 v[0:3], v[188:191], v[220:223], v[0:3]
	s_setprio 0
	s_barrier
	s_add_i32 s48, s48, 2
	s_addk_i32 s46, 0x100
	s_addk_i32 s47, 0x100
	s_cmpk_gt_u32 s48, 0x55
	s_cbranch_scc0 .LBB0_965
	s_and_b64 vcc, exec, s[8:9]
	s_cbranch_vccz .LBB0_968
	s_barrier
